# baseline (speedup 1.0000x reference)
; #define PG8_STAGE(bufoff, gbase, voff) do { _Pragma("unroll") for (int _i = 0; _i < 2; ++_i) \
;     __builtin_amdgcn_global_load_lds((const unsigned*)((const char*)(gbase) + (voff)[_i]), (LAS unsigned*)(lds + (bufoff) + ldsw + _i * 8192), 16, 0, 0); } while (0)
; #define PG8_WAIT_V(n) asm volatile("s_waitcnt vmcnt(" #n ")" ::: "memory")
; template <class Epi, bool SPLITA = false>
; __device__ __forceinline__ void gemm_phase(const int tid, LAS unsigned char* lds, const Gemm g, const Order& S, const Epi& E) {
;   const int wid = __builtin_amdgcn_readfirstlane(tid >> 6), lane = tid & 63, wr = wid >> 2, wc = wid & 3, fr = lane & 15, fq = lane >> 4;
;   const int K = g.K, nt = K / BK;
;   unsigned voffA[2], voffB[2];
; #pragma unroll
;   for (int i = 0; i < 2; ++i) { int R, C; stage_rc(tid * 16 + i * 8192, R, C); const int Rb = Epi::PERM ? ((R & ~31) + perm32(R & 31)) : R;
;     voffA[i] = (unsigned)(R * g.lda + C) * 2u; voffB[i] = (unsigned)(Rb * g.ldb + C) * 2u; }
;   const size_t kstep = (size_t)(BK * 2);
;   const size_t hstepA = (size_t)HALF * g.lda * 2, hstepB = (size_t)HALF * g.ldb * 2;
;   const size_t tstepA = 2 * hstepA, tstepB = g.bpn < 0 ? 2 * hstepB : (size_t)g.bpn, apn = (size_t)g.apn;
;   const unsigned ldsw = (unsigned)wid * 1024u;
;   const int aoff = lds_byte(wr * 64 + fr, fq * 8), boff = lds_byte(wc * 32 + fr, fq * 8);
;     ...
;   Unit cur, nxt; int ui = 0;
;   if (!S.next(0, cur)) return;
;   Acc acc;
; #pragma unroll
;   for (int a = 0; a < 2; ++a)
; #pragma unroll
;     for (int b = 0; b < 2; ++b)
; #pragma unroll
;       for (int m = 0; m < 4; ++m)
; #pragma unroll
;         for (int n = 0; n < 2; ++n) acc[a][b][m][n] = (f32x4){0.f, 0.f, 0.f, 0.f};
;   bf16x8 At[4][2], B0[2][2], B1[2][2];
;   const char* cA = (const char*)g.A + (size_t)cur.pm * tstepA + (size_t)cur.pn * apn; const char* cB = (const char*)g.Bt + (size_t)cur.pn * tstepB;
;   const char* cA2 = SPLITA ? (const char*)g.A2 + (size_t)cur.pm * tstepA : cA; const int nt1 = SPLITA ? g.nt1 : nt;
;     ...
;   PG8_STAGE(PG8_SB(0, 0), cB, voffB); PG8_STAGE(PG8_SA(0, 0), cA, voffA); PG8_STAGE(PG8_SB(0, 1), cB + hstepB, voffB); PG8_STAGE(PG8_SA(0, 1), cA + hstepA, voffA);
;   if (wr == 1) PG8_BAR;
;   PG8_WAIT_V(4); PG8_BAR;
;   PG8_STAGE(PG8_SB(1, 0), cB + kstep, voffB); PG8_STAGE(PG8_SA(1, 0), cA + kstep, voffA); PG8_STAGE(PG8_SB(1, 1), cB + hstepB + kstep, voffB);
;   PG8_WAIT_V(6); PG8_BAR;
.LBB0_45:
	v_bfe_u32 v170, v208, 4, 2
	s_lshl_b32 s0, s0, 5
	v_and_b32_e32 v171, 15, v208
	v_lshlrev_b32_e32 v18, 4, v170
	v_lshlrev_b32_e32 v19, 2, v208
	s_and_b32 s43, s0, 0x60
	s_add_i32 m0, s4, 0x18000
	v_lshl_add_u64 v[8:9], v[8:9], 0, s[96:97]
	s_and_b32 s52, 0xffff, s6
	s_lshl_b32 s42, s1, 6
	v_lshl_or_b32 v18, v171, 6, v18
	s_lshl_b32 s1, s1, 13
	v_and_b32_e32 v19, 32, v19
	s_lshl_b32 s0, s43, 7
	s_waitcnt vmcnt(4)
	s_barrier
	global_load_lds_dwordx4 v[8:9], off
	v_lshl_add_u64 v[6:7], v[6:7], 0, s[96:97]
	s_add_i32 m0, s4, 0x1a000
	s_add_i32 s44, s4, 0x8000
	s_add_i32 s45, s4, 0xa000
	v_bitop3_b32 v172, s0, v18, v19 bitop3:0xf6
	v_add_u32_e32 v172, 0x10000, v172
	global_load_lds_dwordx4 v[6:7], off
	v_lshl_add_u64 v[4:5], v[4:5], 0, s[96:97]
	s_mov_b32 m0, s44
	s_add_u32 s0, s16, 0x160080
	v_bitop3_b32 v20, v18, s1, v19 bitop3:0xde
	global_load_lds_dwordx4 v[4:5], off
	v_lshl_add_u64 v[2:3], v[2:3], 0, s[96:97]
	s_mov_b32 m0, s45
	s_addc_u32 s1, s17, 0
	global_load_lds_dwordx4 v[2:3], off
	s_add_i32 m0, s4, 0x1c000
	s_nop 0
	global_load_lds_dwordx4 v0, s[0:1]
	v_lshl_add_u64 v[2:3], s[0:1], 0, v[150:151]
	s_add_i32 m0, s4, 0x1e000
	s_movk_i32 s6, 0x1600
	global_load_lds_dwordx4 v150, s[0:1]
	v_lshrrev_b32_e32 v3, 1, v15
	v_mul_lo_u32 v2, v14, s6
	s_mov_b32 s7, 0x16000
	v_mad_u64_u32 v[2:3], s[0:1], v3, s7, v[2:3]
	v_or_b32_e32 v2, v2, v16
	v_add_lshl_u32 v156, v2, v17, 1
	v_lshrrev_b32_e32 v3, 1, v10
	v_mul_lo_u32 v2, v11, s6
	s_waitcnt vmcnt(6)
	v_mad_u64_u32 v[2:3], s[0:1], v3, s7, v[2:3]
	v_or_b32_e32 v2, v2, v12
	s_ashr_i32 s46, s92, 31
	v_mov_b32_e32 v157, v1
	v_add_lshl_u32 v158, v2, v13, 1
	v_mov_b32_e32 v159, v1
	s_mov_b32 s47, 0
	v_add_u32_e32 v173, 0, v20
	s_barrier

; #define PG8_STAGE(bufoff, gbase, voff) do { _Pragma("unroll") for (int _i = 0; _i < 2; ++_i) \
;     __builtin_amdgcn_global_load_lds((const unsigned*)((const char*)(gbase) + (voff)[_i]), (LAS unsigned*)(lds + (bufoff) + ldsw + _i * 8192), 16, 0, 0); } while (0)
; #define PG8_LDA(dst, b, h) do { _Pragma("unroll") for (int m = 0; m < 4; ++m) _Pragma("unroll") for (int k = 0; k < 2; ++k) dst[m][k] = *(const LAS bf16x8*)(lds + PG8_SA(b, h) + aoff + m * 2048 + k * 1024); } while (0)
; #define PG8_LDB(dst, b, h) do { _Pragma("unroll") for (int n = 0; n < 2; ++n) _Pragma("unroll") for (int k = 0; k < 2; ++k) dst[n][k] = *(const LAS bf16x8*)(lds + PG8_SB(b, h) + boff + n * 2048 + k * 1024); } while (0)
; #define PG8_MMA(ai, bj, At, Bt) do { __builtin_amdgcn_s_setprio(1); _Pragma("unroll") for (int m = 0; m < 4; ++m) _Pragma("unroll") for (int n = 0; n < 2; ++n) _Pragma("unroll") for (int k = 0; k < 2; ++k) \
;     acc[ai][bj][m][n] = __builtin_amdgcn_mfma_f32_16x16x32_bf16(Bt[n][k], At[m][k], acc[ai][bj][m][n], 0, 0, 0); __builtin_amdgcn_s_setprio(0); } while (0)
; #define PG8_WAIT_L(n) asm volatile("s_waitcnt lgkmcnt(" #n ")" ::: "memory")
; #define PG8_BAR __builtin_amdgcn_s_barrier()
; #define PG8_SCHED __builtin_amdgcn_sched_barrier(0)
; template <class Epi, bool SPLITA = false>
; __device__ __forceinline__ void gemm_phase(const int tid, LAS unsigned char* lds, const Gemm g, const Order& S, const Epi& E) {
;     ...
;       PG8_LDB(B0, 0, 0); PG8_SCHED; PG8_LDA(At, 0, 0); PG8_STAGE(PG8_SA(1, 1), a1 + hstepA, voffA);
;       PG8_WAIT_L(8); PG8_BAR; PG8_WAIT_L(0); PG8_MMA(0, 0, At, B0); PG8_BAR; PG8_SCHED;
;       PG8_LDB(B1, 0, 1); PG8_STAGE(PG8_SB(0, 0), b2, voffB);
;       PG8_BAR; PG8_WAIT_L(0); PG8_MMA(0, 1, At, B1); PG8_BAR;
;       PG8_LDA(At, 0, 1); PG8_STAGE(PG8_SA(0, 0), a2, voffA);
;       PG8_BAR; PG8_WAIT_L(0); PG8_MMA(1, 0, At, B0); PG8_BAR; PG8_SCHED;
.LBB0_57:
	s_add_u32 s8, s12, s16
	s_addc_u32 s9, s13, s17
	s_add_u32 s20, s8, 0x100
	s_addc_u32 s21, s9, 0
	s_add_u32 s18, s53, s16
	s_addc_u32 s19, s54, s17
	s_add_u32 s8, s8, 0x180
	s_addc_u32 s9, s9, 0
	s_add_i32 s55, 0, 0x10000
	ds_read_b128 v[134:137], v172
	ds_read_b128 v[138:141], v172 offset:1024
	ds_read_b128 v[142:145], v172 offset:2048
	ds_read_b128 v[146:149], v172 offset:3072
	s_cmpk_eq_i32 s16, 0x2b00
	s_cselect_b32 s23, s7, s9
	s_cselect_b32 s22, s6, s8
	s_cselect_b32 s19, s11, s19
	s_cselect_b32 s18, s10, s18
	s_cselect_b32 s41, s1, s21
	s_cselect_b32 s40, s0, s20
	v_lshl_add_u64 v[168:169], v[130:131], 0, s[16:17]
	s_add_i32 m0, s4, 0xc000
	ds_read_b128 v[160:163], v173
	ds_read_b128 v[164:167], v173 offset:1024
	ds_read_b128 v[174:177], v173 offset:2048
	ds_read_b128 v[178:181], v173 offset:3072
	ds_read_b128 v[182:185], v173 offset:4096
	ds_read_b128 v[186:189], v173 offset:5120
	ds_read_b128 v[190:193], v173 offset:6144
	ds_read_b128 v[210:213], v173 offset:7168
	global_load_lds_dwordx4 v[168:169], off
	v_lshl_add_u64 v[168:169], v[132:133], 0, s[16:17]
	s_add_i32 m0, s4, 0xe000
	s_nop 0
	global_load_lds_dwordx4 v[168:169], off
	s_waitcnt lgkmcnt(8)
	s_barrier
	s_waitcnt lgkmcnt(0)
	s_setprio 1
	s_waitcnt lgkmcnt(0)
	v_mfma_f32_16x16x32_bf16 v[126:129], v[134:137], v[160:163], v[126:129]
	v_mfma_f32_16x16x32_bf16 v[122:125], v[142:145], v[160:163], v[122:125]
	v_mfma_f32_16x16x32_bf16 v[118:121], v[134:137], v[174:177], v[118:121]
	v_mfma_f32_16x16x32_bf16 v[114:117], v[142:145], v[174:177], v[114:117]
	v_mfma_f32_16x16x32_bf16 v[98:101], v[134:137], v[182:185], v[98:101]
	v_mfma_f32_16x16x32_bf16 v[90:93], v[142:145], v[182:185], v[90:93]
	v_mfma_f32_16x16x32_bf16 v[82:85], v[134:137], v[190:193], v[82:85]
	v_mfma_f32_16x16x32_bf16 v[74:77], v[142:145], v[190:193], v[74:77]
	v_mfma_f32_16x16x32_bf16 v[126:129], v[138:141], v[164:167], v[126:129]
	v_mfma_f32_16x16x32_bf16 v[122:125], v[146:149], v[164:167], v[122:125]
	v_mfma_f32_16x16x32_bf16 v[118:121], v[138:141], v[178:181], v[118:121]
	v_mfma_f32_16x16x32_bf16 v[114:117], v[146:149], v[178:181], v[114:117]
	v_mfma_f32_16x16x32_bf16 v[98:101], v[138:141], v[186:189], v[98:101]
	v_mfma_f32_16x16x32_bf16 v[90:93], v[146:149], v[186:189], v[90:93]
	v_mfma_f32_16x16x32_bf16 v[82:85], v[138:141], v[210:213], v[82:85]
	v_mfma_f32_16x16x32_bf16 v[74:77], v[146:149], v[210:213], v[74:77]
	s_setprio 0
	s_barrier
	s_add_i32 s8, 0, 0x14000
	s_add_i32 s9, s55, s3
	ds_read_b128 v[214:217], v172 offset:16384
	ds_read_b128 v[218:221], v172 offset:17408
	ds_read_b128 v[222:225], v172 offset:18432
	ds_read_b128 v[226:229], v172 offset:19456
	s_mov_b32 m0, s9
	s_nop 0
	global_load_lds_dwordx4 v0, s[18:19]
	s_add_i32 m0, s9, 0x2000
	s_nop 0
	global_load_lds_dwordx4 v150, s[18:19]
	s_barrier
	s_waitcnt lgkmcnt(0)
	s_setprio 1
	s_waitcnt lgkmcnt(0)
	v_mfma_f32_16x16x32_bf16 v[110:113], v[214:217], v[160:163], v[110:113]
	v_mfma_f32_16x16x32_bf16 v[106:109], v[222:225], v[160:163], v[106:109]
	v_mfma_f32_16x16x32_bf16 v[102:105], v[214:217], v[174:177], v[102:105]
	v_mfma_f32_16x16x32_bf16 v[94:97], v[222:225], v[174:177], v[94:97]
	v_mfma_f32_16x16x32_bf16 v[86:89], v[214:217], v[182:185], v[86:89]
	v_mfma_f32_16x16x32_bf16 v[78:81], v[222:225], v[182:185], v[78:81]
	v_mfma_f32_16x16x32_bf16 v[70:73], v[214:217], v[190:193], v[70:73]
	v_mfma_f32_16x16x32_bf16 v[66:69], v[222:225], v[190:193], v[66:69]
	v_mfma_f32_16x16x32_bf16 v[110:113], v[218:221], v[164:167], v[110:113]
	v_mfma_f32_16x16x32_bf16 v[106:109], v[226:229], v[164:167], v[106:109]
	v_mfma_f32_16x16x32_bf16 v[102:105], v[218:221], v[178:181], v[102:105]
	v_mfma_f32_16x16x32_bf16 v[94:97], v[226:229], v[178:181], v[94:97]
	v_mfma_f32_16x16x32_bf16 v[86:89], v[218:221], v[186:189], v[86:89]
	v_mfma_f32_16x16x32_bf16 v[78:81], v[226:229], v[186:189], v[78:81]
	v_mfma_f32_16x16x32_bf16 v[70:73], v[218:221], v[210:213], v[70:73]
	v_mfma_f32_16x16x32_bf16 v[66:69], v[226:229], v[210:213], v[66:69]
	s_setprio 0
	s_mov_b32 m0, s4
	s_barrier
	ds_read_b128 v[160:163], v173 offset:16384
	ds_read_b128 v[164:167], v173 offset:17408
	ds_read_b128 v[174:177], v173 offset:18432
	ds_read_b128 v[178:181], v173 offset:19456
	ds_read_b128 v[182:185], v173 offset:20480
	ds_read_b128 v[186:189], v173 offset:21504
	ds_read_b128 v[190:193], v173 offset:22528
	ds_read_b128 v[210:213], v173 offset:23552
	global_load_lds_dwordx4 v154, s[40:41]
	s_mov_b32 m0, s28
	s_nop 0
	global_load_lds_dwordx4 v152, s[40:41]
	s_barrier
	s_waitcnt lgkmcnt(0)
	s_setprio 1
	s_waitcnt lgkmcnt(0)
	v_mfma_f32_16x16x32_bf16 v[62:65], v[134:137], v[160:163], v[62:65]
	v_mfma_f32_16x16x32_bf16 v[58:61], v[142:145], v[160:163], v[58:61]
	v_mfma_f32_16x16x32_bf16 v[50:53], v[134:137], v[174:177], v[50:53]
	v_mfma_f32_16x16x32_bf16 v[42:45], v[142:145], v[174:177], v[42:45]
	v_mfma_f32_16x16x32_bf16 v[34:37], v[134:137], v[182:185], v[34:37]
	v_mfma_f32_16x16x32_bf16 v[26:29], v[142:145], v[182:185], v[26:29]
	v_mfma_f32_16x16x32_bf16 v[18:21], v[134:137], v[190:193], v[18:21]
	v_mfma_f32_16x16x32_bf16 v[10:13], v[142:145], v[190:193], v[10:13]
	v_mfma_f32_16x16x32_bf16 v[62:65], v[138:141], v[164:167], v[62:65]
	v_mfma_f32_16x16x32_bf16 v[58:61], v[146:149], v[164:167], v[58:61]
	v_mfma_f32_16x16x32_bf16 v[50:53], v[138:141], v[178:181], v[50:53]
	v_mfma_f32_16x16x32_bf16 v[42:45], v[146:149], v[178:181], v[42:45]
	v_mfma_f32_16x16x32_bf16 v[34:37], v[138:141], v[186:189], v[34:37]
	v_mfma_f32_16x16x32_bf16 v[26:29], v[146:149], v[186:189], v[26:29]
	v_mfma_f32_16x16x32_bf16 v[18:21], v[138:141], v[210:213], v[18:21]
	v_mfma_f32_16x16x32_bf16 v[10:13], v[146:149], v[210:213], v[10:13]
	s_setprio 0
	s_barrier
; #define PG8_STAGE(bufoff, gbase, voff) do { _Pragma("unroll") for (int _i = 0; _i < 2; ++_i) \
;     __builtin_amdgcn_global_load_lds((const unsigned*)((const char*)(gbase) + (voff)[_i]), (LAS unsigned*)(lds + (bufoff) + ldsw + _i * 8192), 16, 0, 0); } while (0)
; #define PG8_LDA(dst, b, h) do { _Pragma("unroll") for (int m = 0; m < 4; ++m) _Pragma("unroll") for (int k = 0; k < 2; ++k) dst[m][k] = *(const LAS bf16x8*)(lds + PG8_SA(b, h) + aoff + m * 2048 + k * 1024); } while (0)
; #define PG8_LDB(dst, b, h) do { _Pragma("unroll") for (int n = 0; n < 2; ++n) _Pragma("unroll") for (int k = 0; k < 2; ++k) dst[n][k] = *(const LAS bf16x8*)(lds + PG8_SB(b, h) + boff + n * 2048 + k * 1024); } while (0)
; #define PG8_MMA(ai, bj, At, Bt) do { __builtin_amdgcn_s_setprio(1); _Pragma("unroll") for (int m = 0; m < 4; ++m) _Pragma("unroll") for (int n = 0; n < 2; ++n) _Pragma("unroll") for (int k = 0; k < 2; ++k) \
;     acc[ai][bj][m][n] = __builtin_amdgcn_mfma_f32_16x16x32_bf16(Bt[n][k], At[m][k], acc[ai][bj][m][n], 0, 0, 0); __builtin_amdgcn_s_setprio(0); } while (0)
; #define PG8_WAIT_V(n) asm volatile("s_waitcnt vmcnt(" #n ")" ::: "memory")
; #define PG8_WAIT_L(n) asm volatile("s_waitcnt lgkmcnt(" #n ")" ::: "memory")
; #define PG8_BAR __builtin_amdgcn_s_barrier()
; #define PG8_SCHED __builtin_amdgcn_sched_barrier(0)
; template <class Epi, bool SPLITA = false>
; __device__ __forceinline__ void gemm_phase(const int tid, LAS unsigned char* lds, const Gemm g, const Order& S, const Epi& E) {
;     ...
;       PG8_STAGE(PG8_SB(0, 1), b2 + hstepB, voffB);
;       PG8_WAIT_V(6); PG8_BAR; PG8_MMA(1, 1, At, B1); PG8_BAR;
;       PG8_LDB(B0, 1, 0); PG8_SCHED; PG8_LDA(At, 1, 0); PG8_STAGE(PG8_SA(0, 1), a2 + hstepA, voffA);
;       PG8_WAIT_L(8); PG8_BAR; PG8_WAIT_L(0); PG8_MMA(0, 0, At, B0); PG8_BAR; PG8_SCHED;
;       PG8_LDB(B1, 1, 1); PG8_STAGE(PG8_SB(1, 0), b3, voffB);
;       PG8_BAR; PG8_WAIT_L(0); PG8_MMA(0, 1, At, B1); PG8_BAR;
;       PG8_LDA(At, 1, 1); PG8_STAGE(PG8_SA(1, 0), a3, voffA);
;       PG8_BAR; PG8_WAIT_L(0); PG8_MMA(1, 0, At, B0); PG8_BAR; PG8_SCHED;
	s_add_u32 s20, s18, 0x160000
	s_addc_u32 s21, s19, 0
	s_add_i32 s8, s8, s3
	s_mov_b32 m0, s8
	s_nop 0
	global_load_lds_dwordx4 v0, s[20:21]
	s_add_i32 m0, s8, 0x2000
	s_nop 0
	global_load_lds_dwordx4 v150, s[20:21]
	s_waitcnt vmcnt(6)
	s_barrier
	s_setprio 1
	v_mfma_f32_16x16x32_bf16 v[54:57], v[214:217], v[160:163], v[54:57]
	v_mfma_f32_16x16x32_bf16 v[46:49], v[222:225], v[160:163], v[46:49]
	v_mfma_f32_16x16x32_bf16 v[38:41], v[214:217], v[174:177], v[38:41]
	v_mfma_f32_16x16x32_bf16 v[30:33], v[222:225], v[174:177], v[30:33]
	v_mfma_f32_16x16x32_bf16 v[22:25], v[214:217], v[182:185], v[22:25]
	v_mfma_f32_16x16x32_bf16 v[14:17], v[222:225], v[182:185], v[14:17]
	v_mfma_f32_16x16x32_bf16 v[6:9], v[214:217], v[190:193], v[6:9]
	v_mfma_f32_16x16x32_bf16 v[2:5], v[222:225], v[190:193], v[2:5]
	v_mfma_f32_16x16x32_bf16 v[54:57], v[218:221], v[164:167], v[54:57]
	v_mfma_f32_16x16x32_bf16 v[46:49], v[226:229], v[164:167], v[46:49]
	v_mfma_f32_16x16x32_bf16 v[38:41], v[218:221], v[178:181], v[38:41]
	v_mfma_f32_16x16x32_bf16 v[30:33], v[226:229], v[178:181], v[30:33]
	v_mfma_f32_16x16x32_bf16 v[22:25], v[218:221], v[186:189], v[22:25]
	v_mfma_f32_16x16x32_bf16 v[14:17], v[226:229], v[186:189], v[14:17]
	v_mfma_f32_16x16x32_bf16 v[6:9], v[218:221], v[210:213], v[6:9]
	v_mfma_f32_16x16x32_bf16 v[2:5], v[226:229], v[210:213], v[2:5]
	s_setprio 0
	s_add_i32 s8, 0, 0x18000
	s_barrier
	ds_read_b128 v[134:137], v172 offset:32768
	ds_read_b128 v[138:141], v172 offset:33792
	ds_read_b128 v[142:145], v172 offset:34816
	ds_read_b128 v[146:149], v172 offset:35840
	s_add_u32 s20, s40, 0x160000
	s_addc_u32 s21, s41, 0
	s_mov_b32 m0, s30
	ds_read_b128 v[160:163], v173 offset:32768
	ds_read_b128 v[164:167], v173 offset:33792
	ds_read_b128 v[174:177], v173 offset:34816
	ds_read_b128 v[178:181], v173 offset:35840
	ds_read_b128 v[182:185], v173 offset:36864
	ds_read_b128 v[186:189], v173 offset:37888
	ds_read_b128 v[190:193], v173 offset:38912
	ds_read_b128 v[210:213], v173 offset:39936
	global_load_lds_dwordx4 v154, s[20:21]
	s_mov_b32 m0, s31
	s_nop 0
	global_load_lds_dwordx4 v152, s[20:21]
	s_waitcnt lgkmcnt(8)
	s_barrier
	s_waitcnt lgkmcnt(0)
	s_setprio 1
	s_waitcnt lgkmcnt(0)
	v_mfma_f32_16x16x32_bf16 v[126:129], v[134:137], v[160:163], v[126:129]
	v_mfma_f32_16x16x32_bf16 v[122:125], v[142:145], v[160:163], v[122:125]
	v_mfma_f32_16x16x32_bf16 v[118:121], v[134:137], v[174:177], v[118:121]
	v_mfma_f32_16x16x32_bf16 v[114:117], v[142:145], v[174:177], v[114:117]
	v_mfma_f32_16x16x32_bf16 v[98:101], v[134:137], v[182:185], v[98:101]
	v_mfma_f32_16x16x32_bf16 v[90:93], v[142:145], v[182:185], v[90:93]
	v_mfma_f32_16x16x32_bf16 v[82:85], v[134:137], v[190:193], v[82:85]
	v_mfma_f32_16x16x32_bf16 v[74:77], v[142:145], v[190:193], v[74:77]
	v_mfma_f32_16x16x32_bf16 v[126:129], v[138:141], v[164:167], v[126:129]
	v_mfma_f32_16x16x32_bf16 v[122:125], v[146:149], v[164:167], v[122:125]
	v_mfma_f32_16x16x32_bf16 v[118:121], v[138:141], v[178:181], v[118:121]
	v_mfma_f32_16x16x32_bf16 v[114:117], v[146:149], v[178:181], v[114:117]
	v_mfma_f32_16x16x32_bf16 v[98:101], v[138:141], v[186:189], v[98:101]
	v_mfma_f32_16x16x32_bf16 v[90:93], v[146:149], v[186:189], v[90:93]
	v_mfma_f32_16x16x32_bf16 v[82:85], v[138:141], v[210:213], v[82:85]
	v_mfma_f32_16x16x32_bf16 v[74:77], v[146:149], v[210:213], v[74:77]
	s_setprio 0
	s_barrier
	s_add_i32 s9, 0, 0x1c000
	s_add_i32 s8, s8, s3
	s_add_i32 m0, s8, 0xffffff80
	ds_read_b128 v[214:217], v172 offset:49152
	ds_read_b128 v[218:221], v172 offset:50176
	ds_read_b128 v[222:225], v172 offset:51200
	ds_read_b128 v[226:229], v172 offset:52224
	global_load_lds_dwordx4 v0, s[18:19] offset:128
	s_add_i32 m0, s8, 0x1f80
	s_nop 0
	global_load_lds_dwordx4 v150, s[18:19] offset:128
	s_barrier
	s_waitcnt lgkmcnt(0)
	s_setprio 1
	s_waitcnt lgkmcnt(0)
	v_mfma_f32_16x16x32_bf16 v[110:113], v[214:217], v[160:163], v[110:113]
	v_mfma_f32_16x16x32_bf16 v[106:109], v[222:225], v[160:163], v[106:109]
	v_mfma_f32_16x16x32_bf16 v[102:105], v[214:217], v[174:177], v[102:105]
	v_mfma_f32_16x16x32_bf16 v[94:97], v[222:225], v[174:177], v[94:97]
	v_mfma_f32_16x16x32_bf16 v[86:89], v[214:217], v[182:185], v[86:89]
	v_mfma_f32_16x16x32_bf16 v[78:81], v[222:225], v[182:185], v[78:81]
	v_mfma_f32_16x16x32_bf16 v[70:73], v[214:217], v[190:193], v[70:73]
	v_mfma_f32_16x16x32_bf16 v[66:69], v[222:225], v[190:193], v[66:69]
	v_mfma_f32_16x16x32_bf16 v[110:113], v[218:221], v[164:167], v[110:113]
	v_mfma_f32_16x16x32_bf16 v[106:109], v[226:229], v[164:167], v[106:109]
	v_mfma_f32_16x16x32_bf16 v[102:105], v[218:221], v[178:181], v[102:105]
	v_mfma_f32_16x16x32_bf16 v[94:97], v[226:229], v[178:181], v[94:97]
	v_mfma_f32_16x16x32_bf16 v[86:89], v[218:221], v[186:189], v[86:89]
	v_mfma_f32_16x16x32_bf16 v[78:81], v[226:229], v[186:189], v[78:81]
	v_mfma_f32_16x16x32_bf16 v[70:73], v[218:221], v[210:213], v[70:73]
	v_mfma_f32_16x16x32_bf16 v[66:69], v[226:229], v[210:213], v[66:69]
	s_setprio 0
	s_mov_b32 m0, s44
	s_barrier
	ds_read_b128 v[160:163], v173 offset:49152
	ds_read_b128 v[164:167], v173 offset:50176
	ds_read_b128 v[174:177], v173 offset:51200
	ds_read_b128 v[178:181], v173 offset:52224
	ds_read_b128 v[182:185], v173 offset:53248
	ds_read_b128 v[186:189], v173 offset:54272
	ds_read_b128 v[190:193], v173 offset:55296
	ds_read_b128 v[210:213], v173 offset:56320
	global_load_lds_dwordx4 v154, s[22:23]
	s_mov_b32 m0, s45
	s_nop 0
	global_load_lds_dwordx4 v152, s[22:23]
	s_barrier
; #define PG8_STAGE(bufoff, gbase, voff) do { _Pragma("unroll") for (int _i = 0; _i < 2; ++_i) \
;     __builtin_amdgcn_global_load_lds((const unsigned*)((const char*)(gbase) + (voff)[_i]), (LAS unsigned*)(lds + (bufoff) + ldsw + _i * 8192), 16, 0, 0); } while (0)
; #define PG8_MMA(ai, bj, At, Bt) do { __builtin_amdgcn_s_setprio(1); _Pragma("unroll") for (int m = 0; m < 4; ++m) _Pragma("unroll") for (int n = 0; n < 2; ++n) _Pragma("unroll") for (int k = 0; k < 2; ++k) \
;     acc[ai][bj][m][n] = __builtin_amdgcn_mfma_f32_16x16x32_bf16(Bt[n][k], At[m][k], acc[ai][bj][m][n], 0, 0, 0); __builtin_amdgcn_s_setprio(0); } while (0)
; #define PG8_WAIT_V(n) asm volatile("s_waitcnt vmcnt(" #n ")" ::: "memory")
; #define PG8_WAIT_L(n) asm volatile("s_waitcnt lgkmcnt(" #n ")" ::: "memory")
; #define PG8_BAR __builtin_amdgcn_s_barrier()
; #define PG8_SCHED __builtin_amdgcn_sched_barrier(0)
; template <class Epi, bool SPLITA = false>
; __device__ __forceinline__ void gemm_phase(const int tid, LAS unsigned char* lds, const Gemm g, const Order& S, const Epi& E) {
;     ...
;       PG8_BAR; PG8_WAIT_L(0); PG8_MMA(1, 0, At, B0); PG8_BAR; PG8_SCHED;
;       PG8_STAGE(PG8_SB(1, 1), b3 + hstepB, voffB);
;       PG8_WAIT_V(6); PG8_BAR; PG8_MMA(1, 1, At, B1); PG8_BAR;
;     }
;     E(acc, cur, wr, wc, fr, fq);
;   __device__ __forceinline__ void operator()(const Acc& acc, const Unit& u, int wr, int wc, int fr_, int fq_) const {
;     ...
;       u32x4 hv[4][2];
; #pragma unroll
;       for (int m = 0; m < 4; ++m)
; #pragma unroll
;         for (int bj = 0; bj < 2; ++bj) hv[m][bj] = *(const u32x4*)(rin + (size_t)(row0 + ai * HALF + m * 16) * DM + col0 + bj * HALF);
	s_waitcnt lgkmcnt(0)
	s_setprio 1
	s_waitcnt lgkmcnt(0)
	v_mfma_f32_16x16x32_bf16 v[62:65], v[134:137], v[160:163], v[62:65]
	v_mfma_f32_16x16x32_bf16 v[58:61], v[142:145], v[160:163], v[58:61]
	v_mfma_f32_16x16x32_bf16 v[50:53], v[134:137], v[174:177], v[50:53]
	v_mfma_f32_16x16x32_bf16 v[42:45], v[142:145], v[174:177], v[42:45]
	v_mfma_f32_16x16x32_bf16 v[34:37], v[134:137], v[182:185], v[34:37]
	v_mfma_f32_16x16x32_bf16 v[26:29], v[142:145], v[182:185], v[26:29]
	v_mfma_f32_16x16x32_bf16 v[18:21], v[134:137], v[190:193], v[18:21]
	v_mfma_f32_16x16x32_bf16 v[10:13], v[142:145], v[190:193], v[10:13]
	v_mfma_f32_16x16x32_bf16 v[62:65], v[138:141], v[164:167], v[62:65]
	v_mfma_f32_16x16x32_bf16 v[58:61], v[146:149], v[164:167], v[58:61]
	v_mfma_f32_16x16x32_bf16 v[50:53], v[138:141], v[178:181], v[50:53]
	v_mfma_f32_16x16x32_bf16 v[42:45], v[146:149], v[178:181], v[42:45]
	v_mfma_f32_16x16x32_bf16 v[34:37], v[138:141], v[186:189], v[34:37]
	v_mfma_f32_16x16x32_bf16 v[26:29], v[146:149], v[186:189], v[26:29]
	v_mfma_f32_16x16x32_bf16 v[18:21], v[138:141], v[210:213], v[18:21]
	v_mfma_f32_16x16x32_bf16 v[10:13], v[146:149], v[210:213], v[10:13]
	s_setprio 0
	s_barrier
	s_add_u32 s18, s18, 0x160080
	s_addc_u32 s19, s19, 0
	s_add_i32 s8, s9, s3
	s_mov_b32 m0, s8
	s_nop 0
	global_load_lds_dwordx4 v0, s[18:19]
	s_add_i32 m0, s8, 0x2000
	s_nop 0
	global_load_lds_dwordx4 v150, s[18:19]
	s_waitcnt vmcnt(6)
	s_barrier
	s_setprio 1
	v_mfma_f32_16x16x32_bf16 v[54:57], v[214:217], v[160:163], v[54:57]
	v_mfma_f32_16x16x32_bf16 v[46:49], v[222:225], v[160:163], v[46:49]
	v_mfma_f32_16x16x32_bf16 v[38:41], v[214:217], v[174:177], v[38:41]
	v_mfma_f32_16x16x32_bf16 v[30:33], v[222:225], v[174:177], v[30:33]
	v_mfma_f32_16x16x32_bf16 v[22:25], v[214:217], v[182:185], v[22:25]
	v_mfma_f32_16x16x32_bf16 v[14:17], v[222:225], v[182:185], v[14:17]
	v_mfma_f32_16x16x32_bf16 v[6:9], v[214:217], v[190:193], v[6:9]
	v_mfma_f32_16x16x32_bf16 v[2:5], v[222:225], v[190:193], v[2:5]
	v_mfma_f32_16x16x32_bf16 v[54:57], v[218:221], v[164:167], v[54:57]
	v_mfma_f32_16x16x32_bf16 v[46:49], v[226:229], v[164:167], v[46:49]
	v_mfma_f32_16x16x32_bf16 v[38:41], v[218:221], v[178:181], v[38:41]
	v_mfma_f32_16x16x32_bf16 v[30:33], v[226:229], v[178:181], v[30:33]
	v_mfma_f32_16x16x32_bf16 v[22:25], v[218:221], v[186:189], v[22:25]
	v_mfma_f32_16x16x32_bf16 v[14:17], v[226:229], v[186:189], v[14:17]
	v_mfma_f32_16x16x32_bf16 v[6:9], v[218:221], v[210:213], v[6:9]
	v_mfma_f32_16x16x32_bf16 v[2:5], v[226:229], v[210:213], v[2:5]
	s_setprio 0
	s_add_i32 s29, s29, 2
	s_add_u32 s16, s16, 0x100
	s_addc_u32 s17, s17, 0
	s_cmpk_gt_u32 s29, 0x55
	s_barrier
	s_cbranch_scc0 .LBB0_57
	s_lshl_b32 s6, s51, 8
	v_mov_b32_e32 v130, v171
	v_mov_b32_e32 v131, v170
	s_add_i32 s6, s6, s42
	v_readlane_b32 s40, v255, 9
	v_add_u32_e32 v160, s6, v130
	s_lshl_b32 s6, s52, 8
	s_or_b32 s6, s6, s43
	v_lshl_add_u32 v186, v131, 3, s6
	v_readlane_b32 s6, v255, 5
	v_ashrrev_i32_e32 v187, 31, v186
	v_readlane_b32 s7, v255, 6
	v_ashrrev_i32_e32 v161, 31, v160
	v_lshlrev_b64 v[130:131], 12, v[160:161]
	v_lshl_add_u64 v[162:163], v[186:187], 1, s[6:7]
	v_lshl_add_u64 v[130:131], v[162:163], 0, v[130:131]
	global_load_dwordx4 v[174:177], v[130:131], off
	global_load_dwordx4 v[178:181], v[130:131], off offset:256
	v_add_u32_e32 v168, 16, v160
	v_ashrrev_i32_e32 v169, 31, v168
	v_lshlrev_b64 v[130:131], 12, v[168:169]
	v_lshl_add_u64 v[130:131], v[162:163], 0, v[130:131]
	global_load_dwordx4 v[182:185], v[130:131], off
	global_load_dwordx4 v[146:149], v[130:131], off offset:256
	v_add_u32_e32 v166, 32, v160
	v_ashrrev_i32_e32 v167, 31, v166
	v_lshlrev_b64 v[130:131], 12, v[166:167]
	v_lshl_add_u64 v[130:131], v[162:163], 0, v[130:131]
	global_load_dwordx4 v[142:145], v[130:131], off
	global_load_dwordx4 v[138:141], v[130:131], off offset:256
	v_add_u32_e32 v164, 48, v160
	v_ashrrev_i32_e32 v165, 31, v164
	v_lshlrev_b64 v[130:131], 12, v[164:165]
	v_lshl_add_u64 v[130:131], v[162:163], 0, v[130:131]
	global_load_dwordx4 v[134:137], v[130:131], off
	s_nop 0
	global_load_dwordx4 v[130:133], v[130:131], off offset:256
	s_and_b64 vcc, exec, s[38:39]
	s_mov_b32 s52, s48
	s_mov_b32 s51, s49
	s_mov_b64 s[16:17], s[10:11]
	s_mov_b64 s[12:13], s[0:1]
	s_mov_b64 s[20:21], s[34:35]
	v_readlane_b32 s41, v255, 10
	s_waitcnt vmcnt(0)
; __device__ __forceinline__ float bflo(unsigned w) { return __uint_as_float(w << 16); }
; __device__ __forceinline__ float bfhi(unsigned w) { return __uint_as_float(w & 0xffff0000u); }
;   __device__ __forceinline__ void operator()(const Acc& acc, const Unit& u, int wr, int wc, int fr_, int fq_) const {
;     ...
;       for (int m = 0; m < 4; ++m) { const size_t ro = (size_t)(row0 + ai * HALF + m * 16) * DM + col0; float ss = 0.f;
; #pragma unroll
;         for (int bj = 0; bj < 2; ++bj) { const u32x4 h = hv[m][bj];
;           f32x4 v0 = acc[ai][bj][m][0], v1 = acc[ai][bj][m][1];
;           v0[0] += bflo(h.x); v0[1] += bfhi(h.x); v0[2] += bflo(h.y); v0[3] += bfhi(h.y);
;           v1[0] += bflo(h.z); v1[1] += bfhi(h.z); v1[2] += bflo(h.w); v1[3] += bfhi(h.w);
;           if (FINAL) { *(f32x4*)(outf + ro + bj * HALF) = v0; *(f32x4*)(outf + ro + bj * HALF + 4) = v1; }
	v_lshlrev_b32_e32 v188, 16, v174
	v_and_b32_e32 v189, 0xffff0000, v174
	v_lshlrev_b32_e32 v174, 16, v175
	v_and_b32_e32 v175, 0xffff0000, v175
	v_pk_add_f32 v[128:129], v[128:129], v[174:175]
	v_lshlrev_b32_e32 v174, 16, v176
	v_and_b32_e32 v175, 0xffff0000, v176
	v_pk_add_f32 v[174:175], v[122:123], v[174:175]
	v_lshlrev_b32_e32 v122, 16, v177
	v_and_b32_e32 v123, 0xffff0000, v177
	v_pk_add_f32 v[176:177], v[124:125], v[122:123]
	v_lshlrev_b64 v[122:123], 13, v[160:161]
	v_lshl_add_u64 v[124:125], s[86:87], 0, v[122:123]
	v_lshlrev_b64 v[122:123], 2, v[186:187]
	v_pk_add_f32 v[126:127], v[126:127], v[188:189]
	v_lshl_add_u64 v[124:125], v[124:125], 0, v[122:123]
	global_store_dwordx4 v[124:125], v[126:129], off
	global_store_dwordx4 v[124:125], v[174:177], off offset:16
	s_nop 0
	v_lshlrev_b32_e32 v126, 16, v178
	v_and_b32_e32 v127, 0xffff0000, v178
	v_pk_add_f32 v[110:111], v[110:111], v[126:127]
	v_lshlrev_b32_e32 v126, 16, v179
	v_and_b32_e32 v127, 0xffff0000, v179
	v_pk_add_f32 v[112:113], v[112:113], v[126:127]
	v_lshlrev_b32_e32 v126, 16, v180
	v_and_b32_e32 v127, 0xffff0000, v180
	v_pk_add_f32 v[106:107], v[106:107], v[126:127]
	v_lshlrev_b32_e32 v126, 16, v181
	v_and_b32_e32 v127, 0xffff0000, v181
	v_pk_add_f32 v[108:109], v[108:109], v[126:127]
	global_store_dwordx4 v[124:125], v[110:113], off offset:512
	global_store_dwordx4 v[124:125], v[106:109], off offset:528
	s_nop 0
	v_lshlrev_b32_e32 v110, 16, v184
	v_and_b32_e32 v111, 0xffff0000, v184
	v_pk_add_f32 v[110:111], v[114:115], v[110:111]
	v_lshlrev_b64 v[114:115], 13, v[168:169]
	v_lshlrev_b32_e32 v106, 16, v182
	v_and_b32_e32 v107, 0xffff0000, v182
	v_lshlrev_b32_e32 v108, 16, v183
	v_and_b32_e32 v109, 0xffff0000, v183
	v_lshl_add_u64 v[114:115], s[86:87], 0, v[114:115]
	v_pk_add_f32 v[106:107], v[118:119], v[106:107]
	v_pk_add_f32 v[108:109], v[120:121], v[108:109]
	v_lshlrev_b32_e32 v112, 16, v185
	v_and_b32_e32 v113, 0xffff0000, v185
	v_lshl_add_u64 v[114:115], v[114:115], 0, v[122:123]
	v_pk_add_f32 v[112:113], v[116:117], v[112:113]
	global_store_dwordx4 v[114:115], v[106:109], off
	global_store_dwordx4 v[114:115], v[110:113], off offset:16
	s_nop 0
	v_lshlrev_b32_e32 v106, 16, v146
	v_and_b32_e32 v107, 0xffff0000, v146
	v_pk_add_f32 v[102:103], v[102:103], v[106:107]
	v_lshlrev_b32_e32 v106, 16, v147
	v_and_b32_e32 v107, 0xffff0000, v147
	v_pk_add_f32 v[104:105], v[104:105], v[106:107]
	v_lshlrev_b32_e32 v106, 16, v148
	v_and_b32_e32 v107, 0xffff0000, v148
	v_pk_add_f32 v[94:95], v[94:95], v[106:107]
	v_lshlrev_b32_e32 v106, 16, v149
	v_and_b32_e32 v107, 0xffff0000, v149
	v_pk_add_f32 v[96:97], v[96:97], v[106:107]
	global_store_dwordx4 v[114:115], v[102:105], off offset:512
	global_store_dwordx4 v[114:115], v[94:97], off offset:528
	s_nop 0
	v_add_u32_e32 v102, 0xa0, v160
	v_lshlrev_b32_e32 v94, 16, v142
	v_and_b32_e32 v95, 0xffff0000, v142
	v_pk_add_f32 v[94:95], v[98:99], v[94:95]
	v_lshlrev_b32_e32 v98, 16, v144
	v_and_b32_e32 v99, 0xffff0000, v144
	v_pk_add_f32 v[90:91], v[90:91], v[98:99]
	v_lshlrev_b32_e32 v98, 16, v145
	v_and_b32_e32 v99, 0xffff0000, v145
	v_pk_add_f32 v[92:93], v[92:93], v[98:99]
	v_lshlrev_b64 v[98:99], 13, v[166:167]
	v_lshlrev_b32_e32 v96, 16, v143
	v_and_b32_e32 v97, 0xffff0000, v143
	v_lshl_add_u64 v[98:99], s[86:87], 0, v[98:99]
	v_pk_add_f32 v[96:97], v[100:101], v[96:97]
	v_lshl_add_u64 v[98:99], v[98:99], 0, v[122:123]
	global_store_dwordx4 v[98:99], v[94:97], off
	global_store_dwordx4 v[98:99], v[90:93], off offset:16
	v_add_u32_e32 v100, 0x90, v160
	v_ashrrev_i32_e32 v101, 31, v100
	v_lshlrev_b32_e32 v90, 16, v138
	v_and_b32_e32 v91, 0xffff0000, v138
	v_pk_add_f32 v[86:87], v[86:87], v[90:91]
	v_lshlrev_b32_e32 v90, 16, v139
	v_and_b32_e32 v91, 0xffff0000, v139
	v_pk_add_f32 v[88:89], v[88:89], v[90:91]
	v_lshlrev_b32_e32 v90, 16, v140
	v_and_b32_e32 v91, 0xffff0000, v140
	v_pk_add_f32 v[78:79], v[78:79], v[90:91]
	v_lshlrev_b32_e32 v90, 16, v141
	v_and_b32_e32 v91, 0xffff0000, v141
	v_pk_add_f32 v[80:81], v[80:81], v[90:91]
	global_store_dwordx4 v[98:99], v[86:89], off offset:512
	global_store_dwordx4 v[98:99], v[78:81], off offset:528
	v_add_u32_e32 v98, 0x80, v160
	v_ashrrev_i32_e32 v99, 31, v98
	v_lshlrev_b32_e32 v78, 16, v134
	v_and_b32_e32 v79, 0xffff0000, v134
	v_pk_add_f32 v[78:79], v[82:83], v[78:79]
	v_lshlrev_b32_e32 v82, 16, v136
	v_and_b32_e32 v83, 0xffff0000, v136
	v_pk_add_f32 v[74:75], v[74:75], v[82:83]
	v_lshlrev_b32_e32 v82, 16, v137
	v_and_b32_e32 v83, 0xffff0000, v137
	v_pk_add_f32 v[76:77], v[76:77], v[82:83]
	v_lshlrev_b64 v[82:83], 13, v[164:165]
	v_lshlrev_b32_e32 v80, 16, v135
	v_and_b32_e32 v81, 0xffff0000, v135
	v_lshl_add_u64 v[82:83], s[86:87], 0, v[82:83]
	v_pk_add_f32 v[80:81], v[84:85], v[80:81]
	v_lshl_add_u64 v[82:83], v[82:83], 0, v[122:123]
	global_store_dwordx4 v[82:83], v[78:81], off
	global_store_dwordx4 v[82:83], v[74:77], off offset:16
	v_ashrrev_i32_e32 v103, 31, v102
	v_add_u32_e32 v104, 0xb0, v160
	v_lshlrev_b32_e32 v74, 16, v130
	v_and_b32_e32 v75, 0xffff0000, v130
	v_pk_add_f32 v[70:71], v[70:71], v[74:75]
	v_lshlrev_b32_e32 v74, 16, v131
	v_and_b32_e32 v75, 0xffff0000, v131
	v_pk_add_f32 v[72:73], v[72:73], v[74:75]
	v_lshlrev_b32_e32 v74, 16, v132
	v_and_b32_e32 v75, 0xffff0000, v132
	v_pk_add_f32 v[66:67], v[66:67], v[74:75]
	v_lshlrev_b32_e32 v74, 16, v133
	v_and_b32_e32 v75, 0xffff0000, v133
	v_pk_add_f32 v[68:69], v[68:69], v[74:75]
	global_store_dwordx4 v[82:83], v[70:73], off offset:512
	global_store_dwordx4 v[82:83], v[66:69], off offset:528
	v_ashrrev_i32_e32 v105, 31, v104
	s_nop 0
	v_lshlrev_b64 v[66:67], 12, v[98:99]
	v_lshl_add_u64 v[66:67], v[162:163], 0, v[66:67]
	global_load_dwordx4 v[70:73], v[66:67], off
	global_load_dwordx4 v[74:77], v[66:67], off offset:256
	v_lshlrev_b64 v[66:67], 12, v[100:101]
	v_lshl_add_u64 v[66:67], v[162:163], 0, v[66:67]
	global_load_dwordx4 v[78:81], v[66:67], off
	global_load_dwordx4 v[82:85], v[66:67], off offset:256
	v_lshlrev_b64 v[66:67], 12, v[102:103]
	v_lshl_add_u64 v[66:67], v[162:163], 0, v[66:67]
	global_load_dwordx4 v[86:89], v[66:67], off
	global_load_dwordx4 v[90:93], v[66:67], off offset:256
	v_lshlrev_b64 v[66:67], 12, v[104:105]
	v_lshl_add_u64 v[66:67], v[162:163], 0, v[66:67]
	global_load_dwordx4 v[94:97], v[66:67], off
	s_nop 0
	global_load_dwordx4 v[66:69], v[66:67], off offset:256
	s_waitcnt vmcnt(0)
; __device__ __forceinline__ float bflo(unsigned w) { return __uint_as_float(w << 16); }
; __device__ __forceinline__ float bfhi(unsigned w) { return __uint_as_float(w & 0xffff0000u); }
;   __device__ __forceinline__ void operator()(const Acc& acc, const Unit& u, int wr, int wc, int fr_, int fq_) const {
;     ...
;       for (int m = 0; m < 4; ++m) { const size_t ro = (size_t)(row0 + ai * HALF + m * 16) * DM + col0; float ss = 0.f;
; #pragma unroll
;         for (int bj = 0; bj < 2; ++bj) { const u32x4 h = hv[m][bj];
;           f32x4 v0 = acc[ai][bj][m][0], v1 = acc[ai][bj][m][1];
;           v0[0] += bflo(h.x); v0[1] += bfhi(h.x); v0[2] += bflo(h.y); v0[3] += bfhi(h.y);
;           v1[0] += bflo(h.z); v1[1] += bfhi(h.z); v1[2] += bflo(h.w); v1[3] += bfhi(h.w);
;           if (FINAL) { *(f32x4*)(outf + ro + bj * HALF) = v0; *(f32x4*)(outf + ro + bj * HALF + 4) = v1; }
	v_lshlrev_b32_e32 v106, 16, v70
	v_and_b32_e32 v107, 0xffff0000, v70
	v_lshlrev_b32_e32 v70, 16, v71
	v_and_b32_e32 v71, 0xffff0000, v71
	v_pk_add_f32 v[64:65], v[64:65], v[70:71]
	v_lshlrev_b32_e32 v70, 16, v72
	v_and_b32_e32 v71, 0xffff0000, v72
	v_pk_add_f32 v[58:59], v[58:59], v[70:71]
	v_lshlrev_b32_e32 v70, 16, v73
	v_and_b32_e32 v71, 0xffff0000, v73
	v_pk_add_f32 v[60:61], v[60:61], v[70:71]
	v_lshlrev_b64 v[70:71], 13, v[98:99]
	v_lshl_add_u64 v[70:71], s[86:87], 0, v[70:71]
	v_pk_add_f32 v[62:63], v[62:63], v[106:107]
	v_lshl_add_u64 v[70:71], v[70:71], 0, v[122:123]
	global_store_dwordx4 v[70:71], v[62:65], off
	global_store_dwordx4 v[70:71], v[58:61], off offset:16
	s_nop 1
	v_lshlrev_b32_e32 v58, 16, v74
	v_and_b32_e32 v59, 0xffff0000, v74
	v_pk_add_f32 v[54:55], v[54:55], v[58:59]
	v_lshlrev_b32_e32 v58, 16, v75
	v_and_b32_e32 v59, 0xffff0000, v75
	v_pk_add_f32 v[56:57], v[56:57], v[58:59]
	v_lshlrev_b32_e32 v58, 16, v76
	v_and_b32_e32 v59, 0xffff0000, v76
	v_pk_add_f32 v[46:47], v[46:47], v[58:59]
	v_lshlrev_b32_e32 v58, 16, v77
	v_and_b32_e32 v59, 0xffff0000, v77
	v_pk_add_f32 v[48:49], v[48:49], v[58:59]
	global_store_dwordx4 v[70:71], v[54:57], off offset:512
	global_store_dwordx4 v[70:71], v[46:49], off offset:528
	s_nop 1
	v_lshlrev_b32_e32 v46, 16, v78
	v_and_b32_e32 v47, 0xffff0000, v78
	v_pk_add_f32 v[46:47], v[50:51], v[46:47]
	v_lshlrev_b32_e32 v50, 16, v80
	v_and_b32_e32 v51, 0xffff0000, v80
	v_pk_add_f32 v[42:43], v[42:43], v[50:51]
	v_lshlrev_b32_e32 v50, 16, v81
	v_and_b32_e32 v51, 0xffff0000, v81
	v_pk_add_f32 v[44:45], v[44:45], v[50:51]
	v_lshlrev_b64 v[50:51], 13, v[100:101]
	v_lshlrev_b32_e32 v48, 16, v79
	v_and_b32_e32 v49, 0xffff0000, v79
	v_lshl_add_u64 v[50:51], s[86:87], 0, v[50:51]
	v_pk_add_f32 v[48:49], v[52:53], v[48:49]
	v_lshl_add_u64 v[50:51], v[50:51], 0, v[122:123]
	global_store_dwordx4 v[50:51], v[46:49], off
	global_store_dwordx4 v[50:51], v[42:45], off offset:16
	s_nop 1
	v_lshlrev_b32_e32 v42, 16, v82
	v_and_b32_e32 v43, 0xffff0000, v82
	v_pk_add_f32 v[38:39], v[38:39], v[42:43]
	v_lshlrev_b32_e32 v42, 16, v83
	v_and_b32_e32 v43, 0xffff0000, v83
	v_pk_add_f32 v[40:41], v[40:41], v[42:43]
	v_lshlrev_b32_e32 v42, 16, v84
	v_and_b32_e32 v43, 0xffff0000, v84
	v_pk_add_f32 v[30:31], v[30:31], v[42:43]
	v_lshlrev_b32_e32 v42, 16, v85
	v_and_b32_e32 v43, 0xffff0000, v85
	v_pk_add_f32 v[32:33], v[32:33], v[42:43]
	global_store_dwordx4 v[50:51], v[38:41], off offset:512
	global_store_dwordx4 v[50:51], v[30:33], off offset:528
	s_nop 1
	v_lshlrev_b32_e32 v30, 16, v86
	v_and_b32_e32 v31, 0xffff0000, v86
	v_pk_add_f32 v[30:31], v[34:35], v[30:31]
	v_lshlrev_b32_e32 v34, 16, v88
	v_and_b32_e32 v35, 0xffff0000, v88
	v_pk_add_f32 v[26:27], v[26:27], v[34:35]
	v_lshlrev_b32_e32 v34, 16, v89
	v_and_b32_e32 v35, 0xffff0000, v89
	v_pk_add_f32 v[28:29], v[28:29], v[34:35]
	v_lshlrev_b64 v[34:35], 13, v[102:103]
	v_lshlrev_b32_e32 v32, 16, v87
	v_and_b32_e32 v33, 0xffff0000, v87
	v_lshl_add_u64 v[34:35], s[86:87], 0, v[34:35]
	v_pk_add_f32 v[32:33], v[36:37], v[32:33]
	v_lshl_add_u64 v[34:35], v[34:35], 0, v[122:123]
	global_store_dwordx4 v[34:35], v[30:33], off
	global_store_dwordx4 v[34:35], v[26:29], off offset:16
	s_nop 1
	v_lshlrev_b32_e32 v26, 16, v90
	v_and_b32_e32 v27, 0xffff0000, v90
	v_pk_add_f32 v[22:23], v[22:23], v[26:27]
	v_lshlrev_b32_e32 v26, 16, v91
	v_and_b32_e32 v27, 0xffff0000, v91
	v_pk_add_f32 v[24:25], v[24:25], v[26:27]
	v_lshlrev_b32_e32 v26, 16, v92
	v_and_b32_e32 v27, 0xffff0000, v92
	v_pk_add_f32 v[14:15], v[14:15], v[26:27]
	v_lshlrev_b32_e32 v26, 16, v93
	v_and_b32_e32 v27, 0xffff0000, v93
	v_pk_add_f32 v[16:17], v[16:17], v[26:27]
	global_store_dwordx4 v[34:35], v[22:25], off offset:512
	global_store_dwordx4 v[34:35], v[14:17], off offset:528
	s_nop 1
	v_lshlrev_b32_e32 v14, 16, v94
	v_and_b32_e32 v15, 0xffff0000, v94
	v_pk_add_f32 v[14:15], v[18:19], v[14:15]
	v_lshlrev_b32_e32 v18, 16, v96
	v_and_b32_e32 v19, 0xffff0000, v96
	v_pk_add_f32 v[10:11], v[10:11], v[18:19]
	v_lshlrev_b32_e32 v18, 16, v97
	v_and_b32_e32 v19, 0xffff0000, v97
	v_pk_add_f32 v[12:13], v[12:13], v[18:19]
	v_lshlrev_b64 v[18:19], 13, v[104:105]
	v_lshlrev_b32_e32 v16, 16, v95
	v_and_b32_e32 v17, 0xffff0000, v95
	v_lshl_add_u64 v[18:19], s[86:87], 0, v[18:19]
	v_pk_add_f32 v[16:17], v[20:21], v[16:17]
	v_lshl_add_u64 v[18:19], v[18:19], 0, v[122:123]
	global_store_dwordx4 v[18:19], v[14:17], off
	global_store_dwordx4 v[18:19], v[10:13], off offset:16
	s_nop 1
	v_lshlrev_b32_e32 v10, 16, v66
	v_and_b32_e32 v11, 0xffff0000, v66
	v_pk_add_f32 v[6:7], v[6:7], v[10:11]
	v_lshlrev_b32_e32 v10, 16, v67
	v_and_b32_e32 v11, 0xffff0000, v67
	v_pk_add_f32 v[8:9], v[8:9], v[10:11]
	v_lshlrev_b32_e32 v10, 16, v68
	v_and_b32_e32 v11, 0xffff0000, v68
	v_pk_add_f32 v[2:3], v[2:3], v[10:11]
	v_lshlrev_b32_e32 v10, 16, v69
	v_and_b32_e32 v11, 0xffff0000, v69
	v_pk_add_f32 v[4:5], v[4:5], v[10:11]
	global_store_dwordx4 v[18:19], v[6:9], off offset:512
	global_store_dwordx4 v[18:19], v[2:5], off offset:528
	s_cbranch_vccz .LBB0_46
	s_waitcnt vmcnt(0)
	v_mov_b32_e32 v219, v196
	s_cmpk_gt_u32 s2, 0xff
	s_cbranch_scc1 .LBB0_61
	s_barrier

; #define PG8_STAGE(bufoff, gbase, voff) do { _Pragma("unroll") for (int _i = 0; _i < 2; ++_i) \
;     __builtin_amdgcn_global_load_lds((const unsigned*)((const char*)(gbase) + (voff)[_i]), (LAS unsigned*)(lds + (bufoff) + ldsw + _i * 8192), 16, 0, 0); } while (0)
; #define PG8_WAIT_V(n) asm volatile("s_waitcnt vmcnt(" #n ")" ::: "memory")
; template <class Epi, bool SPLITA = false>
; __device__ __forceinline__ void gemm_phase(const int tid, LAS unsigned char* lds, const Gemm g, const Order& S, const Epi& E) {
;   const int wid = __builtin_amdgcn_readfirstlane(tid >> 6), lane = tid & 63, wr = wid >> 2, wc = wid & 3, fr = lane & 15, fq = lane >> 4;
;   const int K = g.K, nt = K / BK;
;   unsigned voffA[2], voffB[2];
; #pragma unroll
;   for (int i = 0; i < 2; ++i) { int R, C; stage_rc(tid * 16 + i * 8192, R, C); const int Rb = Epi::PERM ? ((R & ~31) + perm32(R & 31)) : R;
;     voffA[i] = (unsigned)(R * g.lda + C) * 2u; voffB[i] = (unsigned)(Rb * g.ldb + C) * 2u; }
;   const size_t kstep = (size_t)(BK * 2);
;   const size_t hstepA = (size_t)HALF * g.lda * 2, hstepB = (size_t)HALF * g.ldb * 2;
;   const size_t tstepA = 2 * hstepA, tstepB = g.bpn < 0 ? 2 * hstepB : (size_t)g.bpn, apn = (size_t)g.apn;
;   const unsigned ldsw = (unsigned)wid * 1024u;
;   const int aoff = lds_byte(wr * 64 + fr, fq * 8), boff = lds_byte(wc * 32 + fr, fq * 8);
;     ...
;   Unit cur, nxt; int ui = 0;
;   if (!S.next(0, cur)) return;
;   Acc acc;
; #pragma unroll
;   for (int a = 0; a < 2; ++a)
; #pragma unroll
;     for (int b = 0; b < 2; ++b)
; #pragma unroll
;       for (int m = 0; m < 4; ++m)
; #pragma unroll
;         for (int n = 0; n < 2; ++n) acc[a][b][m][n] = (f32x4){0.f, 0.f, 0.f, 0.f};
;   bf16x8 At[4][2], B0[2][2], B1[2][2];
;   const char* cA = (const char*)g.A + (size_t)cur.pm * tstepA + (size_t)cur.pn * apn; const char* cB = (const char*)g.Bt + (size_t)cur.pn * tstepB;
;   const char* cA2 = SPLITA ? (const char*)g.A2 + (size_t)cur.pm * tstepA : cA; const int nt1 = SPLITA ? g.nt1 : nt;
;     ...
;   PG8_STAGE(PG8_SB(0, 0), cB, voffB); PG8_STAGE(PG8_SA(0, 0), cA, voffA); PG8_STAGE(PG8_SB(0, 1), cB + hstepB, voffB); PG8_STAGE(PG8_SA(0, 1), cA + hstepA, voffA);
;   if (wr == 1) PG8_BAR;
;   PG8_WAIT_V(4); PG8_BAR;
;   PG8_STAGE(PG8_SB(1, 0), cB + kstep, voffB); PG8_STAGE(PG8_SA(1, 0), cA + kstep, voffA); PG8_STAGE(PG8_SB(1, 1), cB + hstepB + kstep, voffB);
;   PG8_WAIT_V(6); PG8_BAR;
.LBB0_74:
	v_bfe_u32 v186, v210, 4, 2
	v_and_b32_e32 v187, 15, v210
	v_lshlrev_b32_e32 v18, 4, v186
	v_lshlrev_b32_e32 v19, 2, v210
	s_and_b32 s44, s0, 3
	v_lshl_or_b32 v18, v187, 6, v18
	s_lshl_b32 s0, s1, 13
	v_and_b32_e32 v19, 32, v19
	s_add_i32 m0, s30, 0x18000
	v_lshl_add_u64 v[8:9], v[8:9], 0, s[96:97]
	s_lshl_b32 s45, s1, 6
	v_bitop3_b32 v20, v18, s0, v19 bitop3:0xde
	s_lshl_b32 s46, s44, 5
	s_lshl_b32 s0, s44, 12
	s_waitcnt vmcnt(4)
	s_barrier
	global_load_lds_dwordx4 v[8:9], off
	v_lshl_add_u64 v[6:7], v[6:7], 0, s[96:97]
	s_add_i32 m0, s30, 0x1a000
	s_add_i32 s47, s30, 0x8000
	s_add_i32 s48, s30, 0xa000
	v_bitop3_b32 v188, v18, s0, v19 bitop3:0xde
	v_add_u32_e32 v188, 0x10000, v188
	global_load_lds_dwordx4 v[6:7], off
	v_lshl_add_u64 v[4:5], v[4:5], 0, s[96:97]
	s_mov_b32 m0, s47
	s_add_u32 s0, s16, 0x160080
	global_load_lds_dwordx4 v[4:5], off
	v_lshl_add_u64 v[2:3], v[2:3], 0, s[96:97]
	s_mov_b32 m0, s48
	s_addc_u32 s1, s17, 0
	global_load_lds_dwordx4 v[2:3], off
	s_add_i32 m0, s30, 0x1c000
	s_nop 0
	global_load_lds_dwordx4 v0, s[0:1]
	v_lshl_add_u64 v[2:3], s[0:1], 0, v[162:163]
	s_add_i32 m0, s30, 0x1e000
	s_movk_i32 s6, 0x1600
	global_load_lds_dwordx4 v162, s[0:1]
	v_lshrrev_b32_e32 v3, 1, v10
	v_mul_lo_u32 v2, v12, s6
	s_mov_b32 s7, 0x16000
	v_mad_u64_u32 v[2:3], s[0:1], v3, s7, v[2:3]
	v_or_b32_e32 v2, v2, v11
	v_add_lshl_u32 v164, v2, v13, 1
	v_lshrrev_b32_e32 v3, 1, v14
	v_mul_lo_u32 v2, v16, s6
	s_waitcnt vmcnt(6)
	v_mad_u64_u32 v[2:3], s[0:1], v3, s7, v[2:3]
	v_or_b32_e32 v2, v2, v15
	s_ashr_i32 s49, s92, 31
	v_mov_b32_e32 v165, v1
	v_add_lshl_u32 v166, v2, v17, 1
	v_mov_b32_e32 v167, v1
	s_mov_b32 s51, 0
	v_add_u32_e32 v189, 0, v20
	s_barrier
	s_branch .LBB0_76

; #define PG8_STAGE(bufoff, gbase, voff) do { _Pragma("unroll") for (int _i = 0; _i < 2; ++_i) \
;     __builtin_amdgcn_global_load_lds((const unsigned*)((const char*)(gbase) + (voff)[_i]), (LAS unsigned*)(lds + (bufoff) + ldsw + _i * 8192), 16, 0, 0); } while (0)
; #define PG8_LDA(dst, b, h) do { _Pragma("unroll") for (int m = 0; m < 4; ++m) _Pragma("unroll") for (int k = 0; k < 2; ++k) dst[m][k] = *(const LAS bf16x8*)(lds + PG8_SA(b, h) + aoff + m * 2048 + k * 1024); } while (0)
; #define PG8_LDB(dst, b, h) do { _Pragma("unroll") for (int n = 0; n < 2; ++n) _Pragma("unroll") for (int k = 0; k < 2; ++k) dst[n][k] = *(const LAS bf16x8*)(lds + PG8_SB(b, h) + boff + n * 2048 + k * 1024); } while (0)
; #define PG8_MMA(ai, bj, At, Bt) do { __builtin_amdgcn_s_setprio(1); _Pragma("unroll") for (int m = 0; m < 4; ++m) _Pragma("unroll") for (int n = 0; n < 2; ++n) _Pragma("unroll") for (int k = 0; k < 2; ++k) \
;     acc[ai][bj][m][n] = __builtin_amdgcn_mfma_f32_16x16x32_bf16(Bt[n][k], At[m][k], acc[ai][bj][m][n], 0, 0, 0); __builtin_amdgcn_s_setprio(0); } while (0)
; #define PG8_WAIT_L(n) asm volatile("s_waitcnt lgkmcnt(" #n ")" ::: "memory")
; #define PG8_BAR __builtin_amdgcn_s_barrier()
; #define PG8_SCHED __builtin_amdgcn_sched_barrier(0)
; template <class Epi, bool SPLITA = false>
; __device__ __forceinline__ void gemm_phase(const int tid, LAS unsigned char* lds, const Gemm g, const Order& S, const Epi& E) {
;     ...
;       PG8_LDB(B0, 0, 0); PG8_SCHED; PG8_LDA(At, 0, 0); PG8_STAGE(PG8_SA(1, 1), a1 + hstepA, voffA);
;       PG8_WAIT_L(8); PG8_BAR; PG8_WAIT_L(0); PG8_MMA(0, 0, At, B0); PG8_BAR; PG8_SCHED;
;       PG8_LDB(B1, 0, 1); PG8_STAGE(PG8_SB(0, 0), b2, voffB);
;       PG8_BAR; PG8_WAIT_L(0); PG8_MMA(0, 1, At, B1); PG8_BAR;
;       PG8_LDA(At, 0, 1); PG8_STAGE(PG8_SA(0, 0), a2, voffA);
;       PG8_BAR; PG8_WAIT_L(0); PG8_MMA(1, 0, At, B0); PG8_BAR; PG8_SCHED;
.LBB0_87:
	s_add_u32 s8, s12, s16
	s_addc_u32 s9, s13, s17
	s_add_u32 s20, s8, 0x100
	s_addc_u32 s21, s9, 0
	s_add_u32 s18, s54, s16
	s_addc_u32 s19, s55, s17
	s_add_u32 s8, s8, 0x180
	s_addc_u32 s9, s9, 0
	s_add_i32 s90, 0, 0x10000
	ds_read_b128 v[134:137], v188
	ds_read_b128 v[138:141], v188 offset:1024
	ds_read_b128 v[142:145], v188 offset:2048
	ds_read_b128 v[146:149], v188 offset:3072
	s_cmpk_eq_i32 s16, 0x2b00
	s_cselect_b32 s23, s7, s9
	s_cselect_b32 s22, s6, s8
	s_cselect_b32 s19, s11, s19
	s_cselect_b32 s18, s10, s18
	s_cselect_b32 s41, s1, s21
	s_cselect_b32 s40, s0, s20
	v_lshl_add_u64 v[184:185], v[130:131], 0, s[16:17]
	s_add_i32 m0, s30, 0xc000
	ds_read_b128 v[150:153], v189
	ds_read_b128 v[154:157], v189 offset:1024
	ds_read_b128 v[168:171], v189 offset:2048
	ds_read_b128 v[172:175], v189 offset:3072
	ds_read_b128 v[176:179], v189 offset:4096
	ds_read_b128 v[180:183], v189 offset:5120
	ds_read_b128 v[190:193], v189 offset:6144
	ds_read_b128 v[212:215], v189 offset:7168
	global_load_lds_dwordx4 v[184:185], off
	v_lshl_add_u64 v[184:185], v[132:133], 0, s[16:17]
	s_add_i32 m0, s30, 0xe000
	s_nop 0
	global_load_lds_dwordx4 v[184:185], off
	s_waitcnt lgkmcnt(8)
	s_barrier
	s_waitcnt lgkmcnt(0)
	s_setprio 1
	s_waitcnt lgkmcnt(0)
	v_mfma_f32_16x16x32_bf16 v[126:129], v[134:137], v[150:153], v[126:129]
	v_mfma_f32_16x16x32_bf16 v[122:125], v[142:145], v[150:153], v[122:125]
	v_mfma_f32_16x16x32_bf16 v[110:113], v[134:137], v[168:171], v[110:113]
	v_mfma_f32_16x16x32_bf16 v[106:109], v[142:145], v[168:171], v[106:109]
	v_mfma_f32_16x16x32_bf16 v[94:97], v[134:137], v[176:179], v[94:97]
	v_mfma_f32_16x16x32_bf16 v[90:93], v[142:145], v[176:179], v[90:93]
	v_mfma_f32_16x16x32_bf16 v[78:81], v[134:137], v[190:193], v[78:81]
	v_mfma_f32_16x16x32_bf16 v[74:77], v[142:145], v[190:193], v[74:77]
	v_mfma_f32_16x16x32_bf16 v[126:129], v[138:141], v[154:157], v[126:129]
	v_mfma_f32_16x16x32_bf16 v[122:125], v[146:149], v[154:157], v[122:125]
	v_mfma_f32_16x16x32_bf16 v[110:113], v[138:141], v[172:175], v[110:113]
	v_mfma_f32_16x16x32_bf16 v[106:109], v[146:149], v[172:175], v[106:109]
	v_mfma_f32_16x16x32_bf16 v[94:97], v[138:141], v[180:183], v[94:97]
	v_mfma_f32_16x16x32_bf16 v[90:93], v[146:149], v[180:183], v[90:93]
	v_mfma_f32_16x16x32_bf16 v[78:81], v[138:141], v[212:215], v[78:81]
	v_mfma_f32_16x16x32_bf16 v[74:77], v[146:149], v[212:215], v[74:77]
	s_setprio 0
	s_barrier
	s_add_i32 s8, 0, 0x14000
	s_add_i32 s9, s90, s3
	ds_read_b128 v[216:219], v188 offset:16384
	ds_read_b128 v[220:223], v188 offset:17408
	ds_read_b128 v[224:227], v188 offset:18432
	ds_read_b128 v[228:231], v188 offset:19456
	s_mov_b32 m0, s9
	s_nop 0
	global_load_lds_dwordx4 v0, s[18:19]
	s_add_i32 m0, s9, 0x2000
	s_nop 0
	global_load_lds_dwordx4 v162, s[18:19]
	s_barrier
	s_waitcnt lgkmcnt(0)
	s_setprio 1
	s_waitcnt lgkmcnt(0)
	v_mfma_f32_16x16x32_bf16 v[118:121], v[216:219], v[150:153], v[118:121]
	v_mfma_f32_16x16x32_bf16 v[114:117], v[224:227], v[150:153], v[114:117]
	v_mfma_f32_16x16x32_bf16 v[102:105], v[216:219], v[168:171], v[102:105]
	v_mfma_f32_16x16x32_bf16 v[98:101], v[224:227], v[168:171], v[98:101]
	v_mfma_f32_16x16x32_bf16 v[86:89], v[216:219], v[176:179], v[86:89]
	v_mfma_f32_16x16x32_bf16 v[82:85], v[224:227], v[176:179], v[82:85]
	v_mfma_f32_16x16x32_bf16 v[70:73], v[216:219], v[190:193], v[70:73]
	v_mfma_f32_16x16x32_bf16 v[66:69], v[224:227], v[190:193], v[66:69]
	v_mfma_f32_16x16x32_bf16 v[118:121], v[220:223], v[154:157], v[118:121]
	v_mfma_f32_16x16x32_bf16 v[114:117], v[228:231], v[154:157], v[114:117]
	v_mfma_f32_16x16x32_bf16 v[102:105], v[220:223], v[172:175], v[102:105]
	v_mfma_f32_16x16x32_bf16 v[98:101], v[228:231], v[172:175], v[98:101]
	v_mfma_f32_16x16x32_bf16 v[86:89], v[220:223], v[180:183], v[86:89]
	v_mfma_f32_16x16x32_bf16 v[82:85], v[228:231], v[180:183], v[82:85]
	v_mfma_f32_16x16x32_bf16 v[70:73], v[220:223], v[212:215], v[70:73]
	v_mfma_f32_16x16x32_bf16 v[66:69], v[228:231], v[212:215], v[66:69]
	s_setprio 0
	s_mov_b32 m0, s30
	s_barrier
	ds_read_b128 v[150:153], v189 offset:16384
	ds_read_b128 v[154:157], v189 offset:17408
	ds_read_b128 v[168:171], v189 offset:18432
	ds_read_b128 v[172:175], v189 offset:19456
	ds_read_b128 v[176:179], v189 offset:20480
	ds_read_b128 v[180:183], v189 offset:21504
	ds_read_b128 v[190:193], v189 offset:22528
	ds_read_b128 v[212:215], v189 offset:23552
	global_load_lds_dwordx4 v158, s[40:41]
	s_mov_b32 m0, s31
	s_nop 0
	global_load_lds_dwordx4 v160, s[40:41]
	s_barrier
	s_waitcnt lgkmcnt(0)
	s_setprio 1
	s_waitcnt lgkmcnt(0)
	v_mfma_f32_16x16x32_bf16 v[62:65], v[134:137], v[150:153], v[62:65]
	v_mfma_f32_16x16x32_bf16 v[58:61], v[142:145], v[150:153], v[58:61]
	v_mfma_f32_16x16x32_bf16 v[46:49], v[134:137], v[168:171], v[46:49]
	v_mfma_f32_16x16x32_bf16 v[42:45], v[142:145], v[168:171], v[42:45]
	v_mfma_f32_16x16x32_bf16 v[30:33], v[134:137], v[176:179], v[30:33]
	v_mfma_f32_16x16x32_bf16 v[26:29], v[142:145], v[176:179], v[26:29]
	v_mfma_f32_16x16x32_bf16 v[14:17], v[134:137], v[190:193], v[14:17]
	v_mfma_f32_16x16x32_bf16 v[10:13], v[142:145], v[190:193], v[10:13]
	v_mfma_f32_16x16x32_bf16 v[62:65], v[138:141], v[154:157], v[62:65]
	v_mfma_f32_16x16x32_bf16 v[58:61], v[146:149], v[154:157], v[58:61]
	v_mfma_f32_16x16x32_bf16 v[46:49], v[138:141], v[172:175], v[46:49]
	v_mfma_f32_16x16x32_bf16 v[42:45], v[146:149], v[172:175], v[42:45]
	v_mfma_f32_16x16x32_bf16 v[30:33], v[138:141], v[180:183], v[30:33]
	v_mfma_f32_16x16x32_bf16 v[26:29], v[146:149], v[180:183], v[26:29]
	v_mfma_f32_16x16x32_bf16 v[14:17], v[138:141], v[212:215], v[14:17]
	v_mfma_f32_16x16x32_bf16 v[10:13], v[146:149], v[212:215], v[10:13]
	s_setprio 0
	s_barrier
; #define PG8_STAGE(bufoff, gbase, voff) do { _Pragma("unroll") for (int _i = 0; _i < 2; ++_i) \
;     __builtin_amdgcn_global_load_lds((const unsigned*)((const char*)(gbase) + (voff)[_i]), (LAS unsigned*)(lds + (bufoff) + ldsw + _i * 8192), 16, 0, 0); } while (0)
; #define PG8_LDA(dst, b, h) do { _Pragma("unroll") for (int m = 0; m < 4; ++m) _Pragma("unroll") for (int k = 0; k < 2; ++k) dst[m][k] = *(const LAS bf16x8*)(lds + PG8_SA(b, h) + aoff + m * 2048 + k * 1024); } while (0)
; #define PG8_LDB(dst, b, h) do { _Pragma("unroll") for (int n = 0; n < 2; ++n) _Pragma("unroll") for (int k = 0; k < 2; ++k) dst[n][k] = *(const LAS bf16x8*)(lds + PG8_SB(b, h) + boff + n * 2048 + k * 1024); } while (0)
; #define PG8_MMA(ai, bj, At, Bt) do { __builtin_amdgcn_s_setprio(1); _Pragma("unroll") for (int m = 0; m < 4; ++m) _Pragma("unroll") for (int n = 0; n < 2; ++n) _Pragma("unroll") for (int k = 0; k < 2; ++k) \
;     acc[ai][bj][m][n] = __builtin_amdgcn_mfma_f32_16x16x32_bf16(Bt[n][k], At[m][k], acc[ai][bj][m][n], 0, 0, 0); __builtin_amdgcn_s_setprio(0); } while (0)
; #define PG8_WAIT_V(n) asm volatile("s_waitcnt vmcnt(" #n ")" ::: "memory")
; #define PG8_WAIT_L(n) asm volatile("s_waitcnt lgkmcnt(" #n ")" ::: "memory")
; #define PG8_BAR __builtin_amdgcn_s_barrier()
; #define PG8_SCHED __builtin_amdgcn_sched_barrier(0)
; template <class Epi, bool SPLITA = false>
; __device__ __forceinline__ void gemm_phase(const int tid, LAS unsigned char* lds, const Gemm g, const Order& S, const Epi& E) {
;     ...
;       PG8_STAGE(PG8_SB(0, 1), b2 + hstepB, voffB);
;       PG8_WAIT_V(6); PG8_BAR; PG8_MMA(1, 1, At, B1); PG8_BAR;
;       PG8_LDB(B0, 1, 0); PG8_SCHED; PG8_LDA(At, 1, 0); PG8_STAGE(PG8_SA(0, 1), a2 + hstepA, voffA);
;       PG8_WAIT_L(8); PG8_BAR; PG8_WAIT_L(0); PG8_MMA(0, 0, At, B0); PG8_BAR; PG8_SCHED;
;       PG8_LDB(B1, 1, 1); PG8_STAGE(PG8_SB(1, 0), b3, voffB);
;       PG8_BAR; PG8_WAIT_L(0); PG8_MMA(0, 1, At, B1); PG8_BAR;
;       PG8_LDA(At, 1, 1); PG8_STAGE(PG8_SA(1, 0), a3, voffA);
;       PG8_BAR; PG8_WAIT_L(0); PG8_MMA(1, 0, At, B0); PG8_BAR; PG8_SCHED;
	s_add_u32 s20, s18, 0x160000
	s_addc_u32 s21, s19, 0
	s_add_i32 s8, s8, s3
	s_mov_b32 m0, s8
	s_nop 0
	global_load_lds_dwordx4 v0, s[20:21]
	s_add_i32 m0, s8, 0x2000
	s_nop 0
	global_load_lds_dwordx4 v162, s[20:21]
	s_waitcnt vmcnt(6)
	s_barrier
	s_setprio 1
	v_mfma_f32_16x16x32_bf16 v[54:57], v[216:219], v[150:153], v[54:57]
	v_mfma_f32_16x16x32_bf16 v[50:53], v[224:227], v[150:153], v[50:53]
	v_mfma_f32_16x16x32_bf16 v[38:41], v[216:219], v[168:171], v[38:41]
	v_mfma_f32_16x16x32_bf16 v[34:37], v[224:227], v[168:171], v[34:37]
	v_mfma_f32_16x16x32_bf16 v[22:25], v[216:219], v[176:179], v[22:25]
	v_mfma_f32_16x16x32_bf16 v[18:21], v[224:227], v[176:179], v[18:21]
	v_mfma_f32_16x16x32_bf16 v[6:9], v[216:219], v[190:193], v[6:9]
	v_mfma_f32_16x16x32_bf16 v[2:5], v[224:227], v[190:193], v[2:5]
	v_mfma_f32_16x16x32_bf16 v[54:57], v[220:223], v[154:157], v[54:57]
	v_mfma_f32_16x16x32_bf16 v[50:53], v[228:231], v[154:157], v[50:53]
	v_mfma_f32_16x16x32_bf16 v[38:41], v[220:223], v[172:175], v[38:41]
	v_mfma_f32_16x16x32_bf16 v[34:37], v[228:231], v[172:175], v[34:37]
	v_mfma_f32_16x16x32_bf16 v[22:25], v[220:223], v[180:183], v[22:25]
	v_mfma_f32_16x16x32_bf16 v[18:21], v[228:231], v[180:183], v[18:21]
	v_mfma_f32_16x16x32_bf16 v[6:9], v[220:223], v[212:215], v[6:9]
	v_mfma_f32_16x16x32_bf16 v[2:5], v[228:231], v[212:215], v[2:5]
	s_setprio 0
	s_add_i32 s8, 0, 0x18000
	s_barrier
	ds_read_b128 v[134:137], v188 offset:32768
	ds_read_b128 v[138:141], v188 offset:33792
	ds_read_b128 v[142:145], v188 offset:34816
	ds_read_b128 v[146:149], v188 offset:35840
	s_add_u32 s20, s40, 0x160000
	s_addc_u32 s21, s41, 0
	s_mov_b32 m0, s42
	ds_read_b128 v[150:153], v189 offset:32768
	ds_read_b128 v[154:157], v189 offset:33792
	ds_read_b128 v[168:171], v189 offset:34816
	ds_read_b128 v[172:175], v189 offset:35840
	ds_read_b128 v[176:179], v189 offset:36864
	ds_read_b128 v[180:183], v189 offset:37888
	ds_read_b128 v[190:193], v189 offset:38912
	ds_read_b128 v[212:215], v189 offset:39936
	global_load_lds_dwordx4 v158, s[20:21]
	s_mov_b32 m0, s43
	s_nop 0
	global_load_lds_dwordx4 v160, s[20:21]
	s_waitcnt lgkmcnt(8)
	s_barrier
	s_waitcnt lgkmcnt(0)
	s_setprio 1
	s_waitcnt lgkmcnt(0)
	v_mfma_f32_16x16x32_bf16 v[126:129], v[134:137], v[150:153], v[126:129]
	v_mfma_f32_16x16x32_bf16 v[122:125], v[142:145], v[150:153], v[122:125]
	v_mfma_f32_16x16x32_bf16 v[110:113], v[134:137], v[168:171], v[110:113]
	v_mfma_f32_16x16x32_bf16 v[106:109], v[142:145], v[168:171], v[106:109]
	v_mfma_f32_16x16x32_bf16 v[94:97], v[134:137], v[176:179], v[94:97]
	v_mfma_f32_16x16x32_bf16 v[90:93], v[142:145], v[176:179], v[90:93]
	v_mfma_f32_16x16x32_bf16 v[78:81], v[134:137], v[190:193], v[78:81]
	v_mfma_f32_16x16x32_bf16 v[74:77], v[142:145], v[190:193], v[74:77]
	v_mfma_f32_16x16x32_bf16 v[126:129], v[138:141], v[154:157], v[126:129]
	v_mfma_f32_16x16x32_bf16 v[122:125], v[146:149], v[154:157], v[122:125]
	v_mfma_f32_16x16x32_bf16 v[110:113], v[138:141], v[172:175], v[110:113]
	v_mfma_f32_16x16x32_bf16 v[106:109], v[146:149], v[172:175], v[106:109]
	v_mfma_f32_16x16x32_bf16 v[94:97], v[138:141], v[180:183], v[94:97]
	v_mfma_f32_16x16x32_bf16 v[90:93], v[146:149], v[180:183], v[90:93]
	v_mfma_f32_16x16x32_bf16 v[78:81], v[138:141], v[212:215], v[78:81]
	v_mfma_f32_16x16x32_bf16 v[74:77], v[146:149], v[212:215], v[74:77]
	s_setprio 0
	s_barrier
	s_add_i32 s9, 0, 0x1c000
	s_add_i32 s8, s8, s3
	s_add_i32 m0, s8, 0xffffff80
	ds_read_b128 v[216:219], v188 offset:49152
	ds_read_b128 v[220:223], v188 offset:50176
	ds_read_b128 v[224:227], v188 offset:51200
	ds_read_b128 v[228:231], v188 offset:52224
	global_load_lds_dwordx4 v0, s[18:19] offset:128
	s_add_i32 m0, s8, 0x1f80
	s_nop 0
	global_load_lds_dwordx4 v162, s[18:19] offset:128
	s_barrier
	s_waitcnt lgkmcnt(0)
	s_setprio 1
	s_waitcnt lgkmcnt(0)
	v_mfma_f32_16x16x32_bf16 v[118:121], v[216:219], v[150:153], v[118:121]
	v_mfma_f32_16x16x32_bf16 v[114:117], v[224:227], v[150:153], v[114:117]
	v_mfma_f32_16x16x32_bf16 v[102:105], v[216:219], v[168:171], v[102:105]
	v_mfma_f32_16x16x32_bf16 v[98:101], v[224:227], v[168:171], v[98:101]
	v_mfma_f32_16x16x32_bf16 v[86:89], v[216:219], v[176:179], v[86:89]
	v_mfma_f32_16x16x32_bf16 v[82:85], v[224:227], v[176:179], v[82:85]
	v_mfma_f32_16x16x32_bf16 v[70:73], v[216:219], v[190:193], v[70:73]
	v_mfma_f32_16x16x32_bf16 v[66:69], v[224:227], v[190:193], v[66:69]
	v_mfma_f32_16x16x32_bf16 v[118:121], v[220:223], v[154:157], v[118:121]
	v_mfma_f32_16x16x32_bf16 v[114:117], v[228:231], v[154:157], v[114:117]
	v_mfma_f32_16x16x32_bf16 v[102:105], v[220:223], v[172:175], v[102:105]
	v_mfma_f32_16x16x32_bf16 v[98:101], v[228:231], v[172:175], v[98:101]
	v_mfma_f32_16x16x32_bf16 v[86:89], v[220:223], v[180:183], v[86:89]
	v_mfma_f32_16x16x32_bf16 v[82:85], v[228:231], v[180:183], v[82:85]
	v_mfma_f32_16x16x32_bf16 v[70:73], v[220:223], v[212:215], v[70:73]
	v_mfma_f32_16x16x32_bf16 v[66:69], v[228:231], v[212:215], v[66:69]
	s_setprio 0
	s_mov_b32 m0, s47
	s_barrier
	ds_read_b128 v[150:153], v189 offset:49152
	ds_read_b128 v[154:157], v189 offset:50176
	ds_read_b128 v[168:171], v189 offset:51200
	ds_read_b128 v[172:175], v189 offset:52224
	ds_read_b128 v[176:179], v189 offset:53248
	ds_read_b128 v[180:183], v189 offset:54272
	ds_read_b128 v[190:193], v189 offset:55296
	ds_read_b128 v[212:215], v189 offset:56320
	global_load_lds_dwordx4 v158, s[22:23]
	s_mov_b32 m0, s48
	s_nop 0
	global_load_lds_dwordx4 v160, s[22:23]
	s_barrier
; #define PG8_STAGE(bufoff, gbase, voff) do { _Pragma("unroll") for (int _i = 0; _i < 2; ++_i) \
;     __builtin_amdgcn_global_load_lds((const unsigned*)((const char*)(gbase) + (voff)[_i]), (LAS unsigned*)(lds + (bufoff) + ldsw + _i * 8192), 16, 0, 0); } while (0)
; #define PG8_MMA(ai, bj, At, Bt) do { __builtin_amdgcn_s_setprio(1); _Pragma("unroll") for (int m = 0; m < 4; ++m) _Pragma("unroll") for (int n = 0; n < 2; ++n) _Pragma("unroll") for (int k = 0; k < 2; ++k) \
;     acc[ai][bj][m][n] = __builtin_amdgcn_mfma_f32_16x16x32_bf16(Bt[n][k], At[m][k], acc[ai][bj][m][n], 0, 0, 0); __builtin_amdgcn_s_setprio(0); } while (0)
; #define PG8_WAIT_V(n) asm volatile("s_waitcnt vmcnt(" #n ")" ::: "memory")
; #define PG8_WAIT_L(n) asm volatile("s_waitcnt lgkmcnt(" #n ")" ::: "memory")
; #define PG8_BAR __builtin_amdgcn_s_barrier()
; #define PG8_SCHED __builtin_amdgcn_sched_barrier(0)
; template <class Epi, bool SPLITA = false>
; __device__ __forceinline__ void gemm_phase(const int tid, LAS unsigned char* lds, const Gemm g, const Order& S, const Epi& E) {
;     ...
;       PG8_BAR; PG8_WAIT_L(0); PG8_MMA(1, 0, At, B0); PG8_BAR; PG8_SCHED;
;       PG8_STAGE(PG8_SB(1, 1), b3 + hstepB, voffB);
;       PG8_WAIT_V(6); PG8_BAR; PG8_MMA(1, 1, At, B1); PG8_BAR;
	s_waitcnt lgkmcnt(0)
	s_setprio 1
	s_waitcnt lgkmcnt(0)
	v_mfma_f32_16x16x32_bf16 v[62:65], v[134:137], v[150:153], v[62:65]
	v_mfma_f32_16x16x32_bf16 v[58:61], v[142:145], v[150:153], v[58:61]
	v_mfma_f32_16x16x32_bf16 v[46:49], v[134:137], v[168:171], v[46:49]
	v_mfma_f32_16x16x32_bf16 v[42:45], v[142:145], v[168:171], v[42:45]
	v_mfma_f32_16x16x32_bf16 v[30:33], v[134:137], v[176:179], v[30:33]
	v_mfma_f32_16x16x32_bf16 v[26:29], v[142:145], v[176:179], v[26:29]
	v_mfma_f32_16x16x32_bf16 v[14:17], v[134:137], v[190:193], v[14:17]
	v_mfma_f32_16x16x32_bf16 v[10:13], v[142:145], v[190:193], v[10:13]
	v_mfma_f32_16x16x32_bf16 v[62:65], v[138:141], v[154:157], v[62:65]
	v_mfma_f32_16x16x32_bf16 v[58:61], v[146:149], v[154:157], v[58:61]
	v_mfma_f32_16x16x32_bf16 v[46:49], v[138:141], v[172:175], v[46:49]
	v_mfma_f32_16x16x32_bf16 v[42:45], v[146:149], v[172:175], v[42:45]
	v_mfma_f32_16x16x32_bf16 v[30:33], v[138:141], v[180:183], v[30:33]
	v_mfma_f32_16x16x32_bf16 v[26:29], v[146:149], v[180:183], v[26:29]
	v_mfma_f32_16x16x32_bf16 v[14:17], v[138:141], v[212:215], v[14:17]
	v_mfma_f32_16x16x32_bf16 v[10:13], v[146:149], v[212:215], v[10:13]
	s_setprio 0
	s_barrier
	s_add_u32 s18, s18, 0x160080
	s_addc_u32 s19, s19, 0
	s_add_i32 s8, s9, s3
	s_mov_b32 m0, s8
	s_nop 0
	global_load_lds_dwordx4 v0, s[18:19]
	s_add_i32 m0, s8, 0x2000
	s_nop 0
	global_load_lds_dwordx4 v162, s[18:19]
	s_waitcnt vmcnt(6)
	s_barrier
	s_setprio 1
	v_mfma_f32_16x16x32_bf16 v[54:57], v[216:219], v[150:153], v[54:57]
	v_mfma_f32_16x16x32_bf16 v[50:53], v[224:227], v[150:153], v[50:53]
	v_mfma_f32_16x16x32_bf16 v[38:41], v[216:219], v[168:171], v[38:41]
	v_mfma_f32_16x16x32_bf16 v[34:37], v[224:227], v[168:171], v[34:37]
	v_mfma_f32_16x16x32_bf16 v[22:25], v[216:219], v[176:179], v[22:25]
	v_mfma_f32_16x16x32_bf16 v[18:21], v[224:227], v[176:179], v[18:21]
	v_mfma_f32_16x16x32_bf16 v[6:9], v[216:219], v[190:193], v[6:9]
	v_mfma_f32_16x16x32_bf16 v[2:5], v[224:227], v[190:193], v[2:5]
	v_mfma_f32_16x16x32_bf16 v[54:57], v[220:223], v[154:157], v[54:57]
	v_mfma_f32_16x16x32_bf16 v[50:53], v[228:231], v[154:157], v[50:53]
	v_mfma_f32_16x16x32_bf16 v[38:41], v[220:223], v[172:175], v[38:41]
	v_mfma_f32_16x16x32_bf16 v[34:37], v[228:231], v[172:175], v[34:37]
	v_mfma_f32_16x16x32_bf16 v[22:25], v[220:223], v[180:183], v[22:25]
	v_mfma_f32_16x16x32_bf16 v[18:21], v[228:231], v[180:183], v[18:21]
	v_mfma_f32_16x16x32_bf16 v[6:9], v[220:223], v[212:215], v[6:9]
	v_mfma_f32_16x16x32_bf16 v[2:5], v[228:231], v[212:215], v[2:5]
	s_setprio 0
	s_add_i32 s29, s29, 2
	s_add_u32 s16, s16, 0x100
	s_addc_u32 s17, s17, 0
	s_cmpk_gt_u32 s29, 0x55
	s_barrier
	s_cbranch_scc0 .LBB0_87
; __device__ __forceinline__ float bflo(unsigned w) { return __uint_as_float(w << 16); }
; __device__ __forceinline__ float bfhi(unsigned w) { return __uint_as_float(w & 0xffff0000u); }
; __device__ __forceinline__ float lane_read(float v, int src) { return __int_as_float(__builtin_amdgcn_ds_bpermute(src << 2, __float_as_int(v))); }
; __device__ __forceinline__ u32x4 pack8(const f32x4 v0, const f32x4 v1) { u32x4 w; w.x = cvtpk(v0[0], v0[1]); w.y = cvtpk(v0[2], v0[3]); w.z = cvtpk(v1[0], v1[1]); w.w = cvtpk(v1[2], v1[3]); return w; }
;   __device__ __forceinline__ void operator()(const Acc& acc, const Unit& u, int wr, int wc, int fr_, int fq_) const {
;     int fr = fr_, fq = fq_; asm volatile("" : "+v"(fr), "+v"(fq));
;     const int lane = fq * 16 + fr;
;     const int row0 = u.pm * BM + wr * 64 + fr, col0 = u.pn * BM + wc * 32 + 8 * fq;
; #pragma unroll
;     for (int ai = 0; ai < 2; ++ai) {
;       u32x4 hv[4][2];
; #pragma unroll
;       for (int m = 0; m < 4; ++m)
; #pragma unroll
;         for (int bj = 0; bj < 2; ++bj) hv[m][bj] = *(const u32x4*)(rin + (size_t)(row0 + ai * HALF + m * 16) * DM + col0 + bj * HALF);
; #pragma unroll
;       for (int m = 0; m < 4; ++m) { const size_t ro = (size_t)(row0 + ai * HALF + m * 16) * DM + col0; float ss = 0.f;
; #pragma unroll
;         for (int bj = 0; bj < 2; ++bj) { const u32x4 h = hv[m][bj];
;           f32x4 v0 = acc[ai][bj][m][0], v1 = acc[ai][bj][m][1];
;           v0[0] += bflo(h.x); v0[1] += bfhi(h.x); v0[2] += bflo(h.y); v0[3] += bfhi(h.y);
;           v1[0] += bflo(h.z); v1[1] += bfhi(h.z); v1[2] += bflo(h.w); v1[3] += bfhi(h.w);
;           if (FINAL) { *(f32x4*)(outf + ro + bj * HALF) = v0; *(f32x4*)(outf + ro + bj * HALF + 4) = v1; }
;           else { ss += v0[0] * v0[0] + v0[1] * v0[1] + v0[2] * v0[2] + v0[3] * v0[3] + v1[0] * v1[0] + v1[1] * v1[1] + v1[2] * v1[2] + v1[3] * v1[3];
;             *(u32x4*)(outb + ro + bj * HALF) = pack8(v0, v1); } }
;         if (!FINAL) { ss += lane_read(ss, lane ^ 16); ss += lane_read(ss, lane ^ 32);
;           if (fq == 0) rss[(size_t)(row0 + ai * HALF + m * 16) * 32 + u.pn * 4 + wc] = ss; } }
	s_lshl_b32 s6, s53, 8
	v_mov_b32_e32 v130, v187
	v_mov_b32_e32 v131, v186
	s_add_i32 s6, s6, s45
	s_lshl_b32 s12, s4, 2
	v_add_u32_e32 v170, s6, v130
	s_lshl_b32 s6, s4, 8
	s_or_b32 s6, s6, s46
	v_lshl_add_u32 v168, v131, 3, s6
	v_ashrrev_i32_e32 v169, 31, v168
	v_lshlrev_b32_e32 v130, 2, v130
	v_lshlrev_b64 v[192:193], 1, v[168:169]
	v_ashrrev_i32_e32 v171, 31, v170
	v_lshl_add_u32 v130, v131, 6, v130
	v_lshl_add_u64 v[172:173], s[86:87], 0, v[192:193]
	v_lshlrev_b64 v[198:199], 12, v[170:171]
	v_xor_b32_e32 v191, 64, v130
	v_xor_b32_e32 v190, 0x80, v130
	v_cmp_eq_u32_e32 vcc, 0, v131
	v_lshl_add_u64 v[130:131], v[172:173], 0, v[198:199]
	global_load_dwordx4 v[212:215], v[130:131], off
	global_load_dwordx4 v[154:157], v[130:131], off offset:256
	v_add_u32_e32 v182, 16, v170
	v_ashrrev_i32_e32 v183, 31, v182
	v_add_u32_e32 v178, 32, v170
	v_lshlrev_b64 v[184:185], 12, v[182:183]
	v_ashrrev_i32_e32 v179, 31, v178
	v_add_u32_e32 v174, 48, v170
	v_lshl_add_u64 v[130:131], v[172:173], 0, v[184:185]
	v_lshlrev_b64 v[180:181], 12, v[178:179]
	v_ashrrev_i32_e32 v175, 31, v174
	global_load_dwordx4 v[150:153], v[130:131], off
	global_load_dwordx4 v[146:149], v[130:131], off offset:256
	v_lshl_add_u64 v[130:131], v[172:173], 0, v[180:181]
	v_lshlrev_b64 v[176:177], 12, v[174:175]
	global_load_dwordx4 v[142:145], v[130:131], off
	global_load_dwordx4 v[138:141], v[130:131], off offset:256
	v_lshl_add_u64 v[130:131], v[172:173], 0, v[176:177]
	global_load_dwordx4 v[134:137], v[130:131], off
	s_nop 0
	global_load_dwordx4 v[130:133], v[130:131], off offset:256
	s_ashr_i32 s13, s12, 31
	s_waitcnt vmcnt(0)
	v_lshlrev_b32_e32 v200, 16, v212
	v_and_b32_e32 v201, 0xffff0000, v212
	v_pk_add_f32 v[126:127], v[126:127], v[200:201]
	v_lshlrev_b32_e32 v200, 16, v213
	v_and_b32_e32 v201, 0xffff0000, v213
	v_pk_add_f32 v[128:129], v[128:129], v[200:201]
	v_lshlrev_b32_e32 v200, 16, v214
	v_and_b32_e32 v201, 0xffff0000, v214
	v_pk_add_f32 v[200:201], v[122:123], v[200:201]
	v_lshlrev_b32_e32 v122, 16, v215
	v_and_b32_e32 v123, 0xffff0000, v215
	v_pk_add_f32 v[202:203], v[124:125], v[122:123]
	v_pk_mul_f32 v[204:205], v[126:127], v[126:127]
	v_cvt_pk_bf16_f32 v122, v126, v127
	v_lshl_add_u64 v[126:127], s[86:87], 0, v[198:199]
	v_cvt_pk_bf16_f32 v123, v128, v129
	v_cvt_pk_bf16_f32 v124, v200, v201
	v_cvt_pk_bf16_f32 v125, v202, v203
	v_lshl_add_u64 v[126:127], v[126:127], 0, v[192:193]
	global_store_dwordx4 v[126:127], v[122:125], off
	v_pk_mul_f32 v[206:207], v[128:129], v[128:129]
	v_pk_mul_f32 v[212:213], v[200:201], v[200:201]
	v_lshlrev_b32_e32 v122, 16, v154
	v_and_b32_e32 v123, 0xffff0000, v154
	v_pk_add_f32 v[118:119], v[118:119], v[122:123]
	v_lshlrev_b32_e32 v122, 16, v155
	v_and_b32_e32 v123, 0xffff0000, v155
	v_pk_add_f32 v[120:121], v[120:121], v[122:123]
	v_lshlrev_b32_e32 v122, 16, v156
	v_and_b32_e32 v123, 0xffff0000, v156
	v_pk_add_f32 v[122:123], v[114:115], v[122:123]
	v_lshlrev_b32_e32 v114, 16, v157
	v_and_b32_e32 v115, 0xffff0000, v157
	v_pk_add_f32 v[124:125], v[116:117], v[114:115]
	v_pk_mul_f32 v[114:115], v[118:119], v[118:119]
	v_pk_mul_f32 v[116:117], v[120:121], v[120:121]
	v_add_f32_e32 v114, v114, v115
	v_add_f32_e32 v115, v204, v205
	v_add_f32_e32 v114, v116, v114
	v_add_f32_e32 v115, v206, v115
	v_pk_mul_f32 v[128:129], v[122:123], v[122:123]
	v_add_f32_e32 v114, v117, v114
	v_add_f32_e32 v115, v207, v115
	v_add_f32_e32 v114, v128, v114
	v_add_f32_e32 v115, v212, v115
	v_pk_mul_f32 v[214:215], v[202:203], v[202:203]
	v_pk_mul_f32 v[154:155], v[124:125], v[124:125]
	v_add_f32_e32 v114, v129, v114
	v_add_f32_e32 v115, v213, v115
	v_add_f32_e32 v114, v154, v114
	v_add_f32_e32 v115, v214, v115
	v_add_f32_e32 v114, v155, v114
	v_add_f32_e32 v115, v215, v115
	v_add_f32_e32 v128, v115, v114
	v_cvt_pk_bf16_f32 v114, v118, v119
	v_cvt_pk_bf16_f32 v115, v120, v121
	v_cvt_pk_bf16_f32 v116, v122, v123
	v_cvt_pk_bf16_f32 v117, v124, v125
	global_store_dwordx4 v[126:127], v[114:117], off offset:256
	ds_bpermute_b32 v114, v191, v128
	s_waitcnt lgkmcnt(0)
	v_add_f32_e32 v114, v128, v114
	ds_bpermute_b32 v115, v190, v114
	s_and_saveexec_b64 s[6:7], vcc
	s_cbranch_execz .LBB0_90
	v_readlane_b32 s8, v255, 1
	v_lshlrev_b64 v[116:117], 7, v[170:171]
	v_readlane_b32 s9, v255, 2
	s_lshl_b32 s4, s44, 2
	s_waitcnt lgkmcnt(0)
	v_add_f32_e32 v114, v114, v115
	v_lshl_add_u64 v[116:117], s[8:9], 0, v[116:117]
	v_lshl_add_u64 v[116:117], s[12:13], 2, v[116:117]
	v_lshl_add_u64 v[116:117], v[116:117], 0, s[4:5]
	global_store_dword v[116:117], v114, off

; #define PG8_STAGE(bufoff, gbase, voff) do { _Pragma("unroll") for (int _i = 0; _i < 2; ++_i) \
;     __builtin_amdgcn_global_load_lds((const unsigned*)((const char*)(gbase) + (voff)[_i]), (LAS unsigned*)(lds + (bufoff) + ldsw + _i * 8192), 16, 0, 0); } while (0)
; #define PG8_WAIT_V(n) asm volatile("s_waitcnt vmcnt(" #n ")" ::: "memory")
; template <class Epi, bool SPLITA = false>
; __device__ __forceinline__ void gemm_phase(const int tid, LAS unsigned char* lds, const Gemm g, const Order& S, const Epi& E) {
;   const int wid = __builtin_amdgcn_readfirstlane(tid >> 6), lane = tid & 63, wr = wid >> 2, wc = wid & 3, fr = lane & 15, fq = lane >> 4;
;   const int K = g.K, nt = K / BK;
;   unsigned voffA[2], voffB[2];
; #pragma unroll
;   for (int i = 0; i < 2; ++i) { int R, C; stage_rc(tid * 16 + i * 8192, R, C); const int Rb = Epi::PERM ? ((R & ~31) + perm32(R & 31)) : R;
;     voffA[i] = (unsigned)(R * g.lda + C) * 2u; voffB[i] = (unsigned)(Rb * g.ldb + C) * 2u; }
;   const size_t kstep = (size_t)(BK * 2);
;   const size_t hstepA = (size_t)HALF * g.lda * 2, hstepB = (size_t)HALF * g.ldb * 2;
;   const size_t tstepA = 2 * hstepA, tstepB = g.bpn < 0 ? 2 * hstepB : (size_t)g.bpn, apn = (size_t)g.apn;
;   const unsigned ldsw = (unsigned)wid * 1024u;
;   const int aoff = lds_byte(wr * 64 + fr, fq * 8), boff = lds_byte(wc * 32 + fr, fq * 8);
;     ...
;   Unit cur, nxt; int ui = 0;
;   if (!S.next(0, cur)) return;
;   Acc acc;
; #pragma unroll
;   for (int a = 0; a < 2; ++a)
; #pragma unroll
;     for (int b = 0; b < 2; ++b)
; #pragma unroll
;       for (int m = 0; m < 4; ++m)
; #pragma unroll
;         for (int n = 0; n < 2; ++n) acc[a][b][m][n] = (f32x4){0.f, 0.f, 0.f, 0.f};
;   bf16x8 At[4][2], B0[2][2], B1[2][2];
;   const char* cA = (const char*)g.A + (size_t)cur.pm * tstepA + (size_t)cur.pn * apn; const char* cB = (const char*)g.Bt + (size_t)cur.pn * tstepB;
;   const char* cA2 = SPLITA ? (const char*)g.A2 + (size_t)cur.pm * tstepA : cA; const int nt1 = SPLITA ? g.nt1 : nt;
;     ...
;   PG8_STAGE(PG8_SB(0, 0), cB, voffB); PG8_STAGE(PG8_SA(0, 0), cA, voffA); PG8_STAGE(PG8_SB(0, 1), cB + hstepB, voffB); PG8_STAGE(PG8_SA(0, 1), cA + hstepA, voffA);
;   if (wr == 1) PG8_BAR;
;   PG8_WAIT_V(4); PG8_BAR;
;   PG8_STAGE(PG8_SB(1, 0), cB + kstep, voffB); PG8_STAGE(PG8_SA(1, 0), cA + kstep, voffA); PG8_STAGE(PG8_SB(1, 1), cB + hstepB + kstep, voffB);
;   PG8_WAIT_V(6); PG8_BAR;
.LBB0_139:
	v_bfe_u32 v177, v210, 4, 2
	v_and_b32_e32 v179, 15, v210
	v_lshlrev_b32_e32 v16, 4, v177
	v_lshlrev_b32_e32 v17, 2, v210
	v_lshl_or_b32 v16, v179, 6, v16
	s_lshl_b32 s8, s7, 13
	v_and_b32_e32 v17, 32, v17
	v_bitop3_b32 v18, v16, s8, v17 bitop3:0xde
	s_lshl_b32 s8, s10, 5
	s_and_b32 s54, s8, 0x60
	s_add_i32 m0, s31, 0x18000
	v_lshl_add_u64 v[8:9], v[8:9], 0, s[96:97]
	s_and_b32 s90, 0xffff, s6
	s_and_b32 s6, 0xffff, s4
	s_lshl_b32 s4, s7, 6
	s_lshl_b32 s8, s54, 7
	s_waitcnt vmcnt(4)
	s_barrier
	global_load_lds_dwordx4 v[8:9], off
	v_lshl_add_u64 v[6:7], v[6:7], 0, s[96:97]
	s_add_i32 m0, s31, 0x1a000
	s_add_i32 s55, s31, 0x8000
	s_add_i32 s93, s31, 0xa000
	global_load_lds_dwordx4 v[6:7], off
	v_lshl_add_u64 v[4:5], v[4:5], 0, s[96:97]
	s_mov_b32 m0, s55
	s_add_u32 s10, s42, 0x80080
	global_load_lds_dwordx4 v[4:5], off
	v_lshl_add_u64 v[2:3], v[2:3], 0, s[96:97]
	s_mov_b32 m0, s93
	s_addc_u32 s11, s43, 0
	global_load_lds_dwordx4 v[2:3], off
	s_add_i32 m0, s31, 0x1c000
	s_nop 0
	global_load_lds_dwordx4 v0, s[10:11]
	v_lshl_add_u64 v[2:3], s[10:11], 0, v[162:163]
	s_add_i32 m0, s31, 0x1e000
	v_bitop3_b32 v183, s8, v16, v17 bitop3:0xf6
	v_add_u32_e32 v183, 0x10000, v183
	global_load_lds_dwordx4 v162, s[10:11]
	s_ashr_i32 s8, s4, 31
	s_lshl_b32 s7, s7, 1
	v_writelane_b32 v255, s8, 33
	s_cmpk_lt_u32 s3, 0x100
	v_lshlrev_b32_e32 v2, 15, v14
	v_writelane_b32 v255, s7, 44
	s_cselect_b64 s[8:9], -1, 0
	v_and_b32_e32 v2, 0xffff0000, v2
	v_writelane_b32 v255, s8, 38
	s_ashr_i32 s3, s92, 31
	v_lshl_add_u32 v2, v13, 12, v2
	v_and_b32_e32 v3, 1, v14
	v_writelane_b32 v255, s9, 39
	s_add_u32 s48, s14, 0x5800
	v_lshl_or_b32 v2, v3, 6, v2
	v_writelane_b32 v255, s3, 35
	s_addc_u32 s49, s15, 0
	v_lshl_add_u32 v168, v15, 1, v2
	v_lshlrev_b32_e32 v2, 15, v10
	s_add_u32 s8, s14, 0xb000
	v_writelane_b32 v255, s14, 40
	v_and_b32_e32 v2, 0xffff0000, v2
	s_waitcnt vmcnt(6)
	s_addc_u32 s9, s15, 0
	v_writelane_b32 v255, s15, 41
	v_lshl_add_u32 v2, v11, 12, v2
	v_and_b32_e32 v3, 1, v10
	v_writelane_b32 v255, s8, 45
	v_lshl_or_b32 v2, v3, 6, v2
	v_mov_b32_e32 v169, v1
	v_writelane_b32 v255, s9, 46
	v_lshl_add_u32 v170, v12, 1, v2
	v_mov_b32_e32 v171, v1
	s_mov_b32 s15, 0
	v_add_u32_e32 v195, 0, v18
	s_barrier
	s_branch .LBB0_141

; #define PG8_STAGE(bufoff, gbase, voff) do { _Pragma("unroll") for (int _i = 0; _i < 2; ++_i) \
;     __builtin_amdgcn_global_load_lds((const unsigned*)((const char*)(gbase) + (voff)[_i]), (LAS unsigned*)(lds + (bufoff) + ldsw + _i * 8192), 16, 0, 0); } while (0)
; #define PG8_LDA(dst, b, h) do { _Pragma("unroll") for (int m = 0; m < 4; ++m) _Pragma("unroll") for (int k = 0; k < 2; ++k) dst[m][k] = *(const LAS bf16x8*)(lds + PG8_SA(b, h) + aoff + m * 2048 + k * 1024); } while (0)
; #define PG8_LDB(dst, b, h) do { _Pragma("unroll") for (int n = 0; n < 2; ++n) _Pragma("unroll") for (int k = 0; k < 2; ++k) dst[n][k] = *(const LAS bf16x8*)(lds + PG8_SB(b, h) + boff + n * 2048 + k * 1024); } while (0)
; #define PG8_MMA(ai, bj, At, Bt) do { __builtin_amdgcn_s_setprio(1); _Pragma("unroll") for (int m = 0; m < 4; ++m) _Pragma("unroll") for (int n = 0; n < 2; ++n) _Pragma("unroll") for (int k = 0; k < 2; ++k) \
;     acc[ai][bj][m][n] = __builtin_amdgcn_mfma_f32_16x16x32_bf16(Bt[n][k], At[m][k], acc[ai][bj][m][n], 0, 0, 0); __builtin_amdgcn_s_setprio(0); } while (0)
; #define PG8_WAIT_L(n) asm volatile("s_waitcnt lgkmcnt(" #n ")" ::: "memory")
; #define PG8_BAR __builtin_amdgcn_s_barrier()
; #define PG8_SCHED __builtin_amdgcn_sched_barrier(0)
; template <class Epi, bool SPLITA = false>
; __device__ __forceinline__ void gemm_phase(const int tid, LAS unsigned char* lds, const Gemm g, const Order& S, const Epi& E) {
;     ...
;       PG8_LDB(B0, 0, 0); PG8_SCHED; PG8_LDA(At, 0, 0); PG8_STAGE(PG8_SA(1, 1), a1 + hstepA, voffA);
;       PG8_WAIT_L(8); PG8_BAR; PG8_WAIT_L(0); PG8_MMA(0, 0, At, B0); PG8_BAR; PG8_SCHED;
;       PG8_LDB(B1, 0, 1); PG8_STAGE(PG8_SB(0, 0), b2, voffB);
;       PG8_BAR; PG8_WAIT_L(0); PG8_MMA(0, 1, At, B1); PG8_BAR;
;       PG8_LDA(At, 0, 1); PG8_STAGE(PG8_SA(0, 0), a2, voffA);
;       PG8_BAR; PG8_WAIT_L(0); PG8_MMA(1, 0, At, B0); PG8_BAR; PG8_SCHED;
.LBB0_144:
	s_add_u32 s8, s40, s42
	s_addc_u32 s9, s41, s43
	s_add_u32 s20, s8, 0x100
	s_addc_u32 s21, s9, 0
	s_add_u32 s44, s30, s42
	s_addc_u32 s45, s14, s43
	s_add_u32 s8, s8, 0x180
	s_addc_u32 s9, s9, 0
	s_add_i32 s94, 0, 0x10000
	ds_read_b128 v[78:81], v183
	ds_read_b128 v[82:85], v183 offset:1024
	ds_read_b128 v[86:89], v183 offset:2048
	ds_read_b128 v[90:93], v183 offset:3072
	s_cmpk_eq_i32 s42, 0xf00
	s_cselect_b32 s47, s3, s9
	s_cselect_b32 s46, s91, s8
	s_cselect_b32 s45, s23, s45
	s_cselect_b32 s44, s28, s44
	s_cselect_b32 vcc_hi, s7, s21
	s_cselect_b32 vcc_lo, s19, s20
	v_lshl_add_u64 v[180:181], v[74:75], 0, s[42:43]
	s_add_i32 m0, s31, 0xc000
	ds_read_b128 v[94:97], v195
	ds_read_b128 v[98:101], v195 offset:1024
	ds_read_b128 v[102:105], v195 offset:2048
	ds_read_b128 v[172:175], v195 offset:3072
	ds_read_b128 v[184:187], v195 offset:4096
	ds_read_b128 v[188:191], v195 offset:5120
	ds_read_b128 v[212:215], v195 offset:6144
	ds_read_b128 v[216:219], v195 offset:7168
	global_load_lds_dwordx4 v[180:181], off
	v_lshl_add_u64 v[180:181], v[76:77], 0, s[42:43]
	s_add_i32 m0, s31, 0xe000
	s_nop 0
	global_load_lds_dwordx4 v[180:181], off
	s_waitcnt lgkmcnt(8)
	s_barrier
	s_waitcnt lgkmcnt(0)
	s_setprio 1
	s_waitcnt lgkmcnt(0)
	v_mfma_f32_16x16x32_bf16 v[30:33], v[78:81], v[94:97], v[30:33]
	v_mfma_f32_16x16x32_bf16 v[26:29], v[86:89], v[94:97], v[26:29]
	v_mfma_f32_16x16x32_bf16 v[14:17], v[78:81], v[102:105], v[14:17]
	v_mfma_f32_16x16x32_bf16 v[10:13], v[86:89], v[102:105], v[10:13]
	v_mfma_f32_16x16x32_bf16 v[158:161], v[78:81], v[184:187], v[158:161]
	v_mfma_f32_16x16x32_bf16 v[154:157], v[86:89], v[184:187], v[154:157]
	v_mfma_f32_16x16x32_bf16 v[150:153], v[78:81], v[212:215], v[150:153]
	v_mfma_f32_16x16x32_bf16 v[146:149], v[86:89], v[212:215], v[146:149]
	v_mfma_f32_16x16x32_bf16 v[30:33], v[82:85], v[98:101], v[30:33]
	v_mfma_f32_16x16x32_bf16 v[26:29], v[90:93], v[98:101], v[26:29]
	v_mfma_f32_16x16x32_bf16 v[14:17], v[82:85], v[172:175], v[14:17]
	v_mfma_f32_16x16x32_bf16 v[10:13], v[90:93], v[172:175], v[10:13]
	v_mfma_f32_16x16x32_bf16 v[158:161], v[82:85], v[188:191], v[158:161]
	v_mfma_f32_16x16x32_bf16 v[154:157], v[90:93], v[188:191], v[154:157]
	v_mfma_f32_16x16x32_bf16 v[150:153], v[82:85], v[216:219], v[150:153]
	v_mfma_f32_16x16x32_bf16 v[146:149], v[90:93], v[216:219], v[146:149]
	s_setprio 0
	s_barrier
	s_add_i32 s8, 0, 0x14000
	s_add_i32 s9, s94, s2
	s_mov_b32 m0, s9
	ds_read_b128 v[220:223], v183 offset:16384
	ds_read_b128 v[224:227], v183 offset:17408
	ds_read_b128 v[228:231], v183 offset:18432
	ds_read_b128 v[232:235], v183 offset:19456
	global_load_lds_dwordx4 v0, s[44:45]
	s_add_i32 m0, s9, 0x2000
	s_nop 0
	global_load_lds_dwordx4 v162, s[44:45]
	s_barrier
	s_waitcnt lgkmcnt(0)
	s_setprio 1
	s_waitcnt lgkmcnt(0)
	v_mfma_f32_16x16x32_bf16 v[22:25], v[220:223], v[94:97], v[22:25]
	v_mfma_f32_16x16x32_bf16 v[18:21], v[228:231], v[94:97], v[18:21]
	v_mfma_f32_16x16x32_bf16 v[6:9], v[220:223], v[102:105], v[6:9]
	v_mfma_f32_16x16x32_bf16 v[2:5], v[228:231], v[102:105], v[2:5]
	v_mfma_f32_16x16x32_bf16 v[130:133], v[228:231], v[212:215], v[130:133]
	v_mfma_f32_16x16x32_bf16 v[22:25], v[224:227], v[98:101], v[22:25]
	v_mfma_f32_16x16x32_bf16 v[18:21], v[232:235], v[98:101], v[18:21]
	v_mfma_f32_16x16x32_bf16 v[6:9], v[224:227], v[172:175], v[6:9]
	v_mfma_f32_16x16x32_bf16 v[2:5], v[232:235], v[172:175], v[2:5]
	v_mfma_f32_16x16x32_bf16 v[94:97], v[220:223], v[184:187], v[142:145]
	v_mfma_f32_16x16x32_bf16 v[98:101], v[228:231], v[184:187], v[138:141]
	v_mfma_f32_16x16x32_bf16 v[102:105], v[220:223], v[212:215], v[134:137]
	v_mfma_f32_16x16x32_bf16 v[130:133], v[232:235], v[216:219], v[130:133]
	v_mfma_f32_16x16x32_bf16 v[94:97], v[224:227], v[188:191], v[94:97]
	v_mfma_f32_16x16x32_bf16 v[98:101], v[232:235], v[188:191], v[98:101]
	v_mfma_f32_16x16x32_bf16 v[102:105], v[224:227], v[216:219], v[102:105]
	s_setprio 0
	s_mov_b32 m0, s31
	v_lshl_add_u64 v[198:199], vcc, 0, v[166:167]
	s_barrier
	ds_read_b128 v[134:137], v195 offset:16384
	ds_read_b128 v[138:141], v195 offset:17408
	ds_read_b128 v[142:145], v195 offset:18432
	ds_read_b128 v[172:175], v195 offset:19456
	ds_read_b128 v[184:187], v195 offset:20480
	ds_read_b128 v[188:191], v195 offset:21504
	ds_read_b128 v[212:215], v195 offset:22528
	ds_read_b128 v[216:219], v195 offset:23552
	global_load_lds_dwordx4 v[198:199], off
	v_lshl_add_u64 v[198:199], vcc, 0, v[164:165]
	s_mov_b32 m0, s51
	s_nop 0
	global_load_lds_dwordx4 v[198:199], off
	s_barrier
	s_waitcnt lgkmcnt(0)
	s_setprio 1
	s_waitcnt lgkmcnt(0)
	v_mfma_f32_16x16x32_bf16 v[126:129], v[78:81], v[134:137], v[126:129]
	v_mfma_f32_16x16x32_bf16 v[122:125], v[86:89], v[134:137], v[122:125]
	v_mfma_f32_16x16x32_bf16 v[118:121], v[78:81], v[142:145], v[118:121]
	v_mfma_f32_16x16x32_bf16 v[114:117], v[86:89], v[142:145], v[114:117]
	v_mfma_f32_16x16x32_bf16 v[70:73], v[78:81], v[184:187], v[70:73]
	v_mfma_f32_16x16x32_bf16 v[66:69], v[86:89], v[184:187], v[66:69]
	v_mfma_f32_16x16x32_bf16 v[54:57], v[78:81], v[212:215], v[54:57]
	v_mfma_f32_16x16x32_bf16 v[50:53], v[86:89], v[212:215], v[50:53]
	v_mfma_f32_16x16x32_bf16 v[126:129], v[82:85], v[138:141], v[126:129]
	v_mfma_f32_16x16x32_bf16 v[122:125], v[90:93], v[138:141], v[122:125]
	v_mfma_f32_16x16x32_bf16 v[118:121], v[82:85], v[172:175], v[118:121]
	v_mfma_f32_16x16x32_bf16 v[114:117], v[90:93], v[172:175], v[114:117]
	v_mfma_f32_16x16x32_bf16 v[70:73], v[82:85], v[188:191], v[70:73]
	v_mfma_f32_16x16x32_bf16 v[66:69], v[90:93], v[188:191], v[66:69]
	v_mfma_f32_16x16x32_bf16 v[54:57], v[82:85], v[216:219], v[54:57]
	v_mfma_f32_16x16x32_bf16 v[50:53], v[90:93], v[216:219], v[50:53]
	s_setprio 0
	s_barrier
; #define PG8_STAGE(bufoff, gbase, voff) do { _Pragma("unroll") for (int _i = 0; _i < 2; ++_i) \
;     __builtin_amdgcn_global_load_lds((const unsigned*)((const char*)(gbase) + (voff)[_i]), (LAS unsigned*)(lds + (bufoff) + ldsw + _i * 8192), 16, 0, 0); } while (0)
; #define PG8_LDA(dst, b, h) do { _Pragma("unroll") for (int m = 0; m < 4; ++m) _Pragma("unroll") for (int k = 0; k < 2; ++k) dst[m][k] = *(const LAS bf16x8*)(lds + PG8_SA(b, h) + aoff + m * 2048 + k * 1024); } while (0)
; #define PG8_LDB(dst, b, h) do { _Pragma("unroll") for (int n = 0; n < 2; ++n) _Pragma("unroll") for (int k = 0; k < 2; ++k) dst[n][k] = *(const LAS bf16x8*)(lds + PG8_SB(b, h) + boff + n * 2048 + k * 1024); } while (0)
; #define PG8_MMA(ai, bj, At, Bt) do { __builtin_amdgcn_s_setprio(1); _Pragma("unroll") for (int m = 0; m < 4; ++m) _Pragma("unroll") for (int n = 0; n < 2; ++n) _Pragma("unroll") for (int k = 0; k < 2; ++k) \
;     acc[ai][bj][m][n] = __builtin_amdgcn_mfma_f32_16x16x32_bf16(Bt[n][k], At[m][k], acc[ai][bj][m][n], 0, 0, 0); __builtin_amdgcn_s_setprio(0); } while (0)
; #define PG8_WAIT_V(n) asm volatile("s_waitcnt vmcnt(" #n ")" ::: "memory")
; #define PG8_WAIT_L(n) asm volatile("s_waitcnt lgkmcnt(" #n ")" ::: "memory")
; #define PG8_BAR __builtin_amdgcn_s_barrier()
; #define PG8_SCHED __builtin_amdgcn_sched_barrier(0)
; template <class Epi, bool SPLITA = false>
; __device__ __forceinline__ void gemm_phase(const int tid, LAS unsigned char* lds, const Gemm g, const Order& S, const Epi& E) {
;     ...
;       PG8_STAGE(PG8_SB(0, 1), b2 + hstepB, voffB);
;       PG8_WAIT_V(6); PG8_BAR; PG8_MMA(1, 1, At, B1); PG8_BAR;
;       PG8_LDB(B0, 1, 0); PG8_SCHED; PG8_LDA(At, 1, 0); PG8_STAGE(PG8_SA(0, 1), a2 + hstepA, voffA);
;       PG8_WAIT_L(8); PG8_BAR; PG8_WAIT_L(0); PG8_MMA(0, 0, At, B0); PG8_BAR; PG8_SCHED;
;       PG8_LDB(B1, 1, 1); PG8_STAGE(PG8_SB(1, 0), b3, voffB);
;       PG8_BAR; PG8_WAIT_L(0); PG8_MMA(0, 1, At, B1); PG8_BAR;
;       PG8_LDA(At, 1, 1); PG8_STAGE(PG8_SA(1, 0), a3, voffA);
;       PG8_BAR; PG8_WAIT_L(0); PG8_MMA(1, 0, At, B0); PG8_BAR; PG8_SCHED;
	s_add_u32 s20, s44, 0x80000
	s_addc_u32 s21, s45, 0
	s_add_i32 s8, s8, s2
	s_mov_b32 m0, s8
	s_nop 0
	global_load_lds_dwordx4 v0, s[20:21]
	s_add_i32 m0, s8, 0x2000
	s_nop 0
	global_load_lds_dwordx4 v162, s[20:21]
	s_waitcnt vmcnt(6)
	s_barrier
	s_setprio 1
	v_mfma_f32_16x16x32_bf16 v[62:65], v[220:223], v[142:145], v[62:65]
	v_mfma_f32_16x16x32_bf16 v[58:61], v[228:231], v[142:145], v[58:61]
	v_mfma_f32_16x16x32_bf16 v[46:49], v[220:223], v[184:187], v[46:49]
	v_mfma_f32_16x16x32_bf16 v[42:45], v[228:231], v[184:187], v[42:45]
	v_mfma_f32_16x16x32_bf16 v[38:41], v[220:223], v[212:215], v[38:41]
	v_mfma_f32_16x16x32_bf16 v[34:37], v[228:231], v[212:215], v[34:37]
	v_mfma_f32_16x16x32_bf16 v[78:81], v[220:223], v[134:137], v[110:113]
	v_mfma_f32_16x16x32_bf16 v[82:85], v[228:231], v[134:137], v[106:109]
	v_mfma_f32_16x16x32_bf16 v[62:65], v[224:227], v[172:175], v[62:65]
	v_mfma_f32_16x16x32_bf16 v[58:61], v[232:235], v[172:175], v[58:61]
	v_mfma_f32_16x16x32_bf16 v[46:49], v[224:227], v[188:191], v[46:49]
	v_mfma_f32_16x16x32_bf16 v[42:45], v[232:235], v[188:191], v[42:45]
	v_mfma_f32_16x16x32_bf16 v[38:41], v[224:227], v[216:219], v[38:41]
	v_mfma_f32_16x16x32_bf16 v[34:37], v[232:235], v[216:219], v[34:37]
	v_mfma_f32_16x16x32_bf16 v[78:81], v[224:227], v[138:141], v[78:81]
	v_mfma_f32_16x16x32_bf16 v[82:85], v[232:235], v[138:141], v[82:85]
	s_setprio 0
	s_add_i32 s8, 0, 0x18000
	s_barrier
	ds_read_b128 v[86:89], v183 offset:32768
	ds_read_b128 v[90:93], v183 offset:33792
	ds_read_b128 v[106:109], v183 offset:34816
	ds_read_b128 v[110:113], v183 offset:35840
	s_add_u32 s20, vcc_lo, 0x80000
	s_addc_u32 s21, vcc_hi, 0
	s_mov_b32 m0, s52
	ds_read_b128 v[134:137], v195 offset:32768
	ds_read_b128 v[138:141], v195 offset:33792
	ds_read_b128 v[142:145], v195 offset:34816
	ds_read_b128 v[172:175], v195 offset:35840
	ds_read_b128 v[184:187], v195 offset:36864
	ds_read_b128 v[188:191], v195 offset:37888
	ds_read_b128 v[212:215], v195 offset:38912
	ds_read_b128 v[216:219], v195 offset:39936
	global_load_lds_dwordx4 v166, s[20:21]
	s_mov_b32 m0, s53
	s_nop 0
	global_load_lds_dwordx4 v164, s[20:21]
	s_waitcnt lgkmcnt(8)
	s_barrier
	s_waitcnt lgkmcnt(0)
	s_setprio 1
	s_waitcnt lgkmcnt(0)
	v_mfma_f32_16x16x32_bf16 v[30:33], v[86:89], v[134:137], v[30:33]
	v_mfma_f32_16x16x32_bf16 v[26:29], v[106:109], v[134:137], v[26:29]
	v_mfma_f32_16x16x32_bf16 v[14:17], v[86:89], v[142:145], v[14:17]
	v_mfma_f32_16x16x32_bf16 v[10:13], v[106:109], v[142:145], v[10:13]
	v_mfma_f32_16x16x32_bf16 v[158:161], v[86:89], v[184:187], v[158:161]
	v_mfma_f32_16x16x32_bf16 v[154:157], v[106:109], v[184:187], v[154:157]
	v_mfma_f32_16x16x32_bf16 v[150:153], v[86:89], v[212:215], v[150:153]
	v_mfma_f32_16x16x32_bf16 v[146:149], v[106:109], v[212:215], v[146:149]
	v_mfma_f32_16x16x32_bf16 v[30:33], v[90:93], v[138:141], v[30:33]
	v_mfma_f32_16x16x32_bf16 v[26:29], v[110:113], v[138:141], v[26:29]
	v_mfma_f32_16x16x32_bf16 v[14:17], v[90:93], v[172:175], v[14:17]
	v_mfma_f32_16x16x32_bf16 v[10:13], v[110:113], v[172:175], v[10:13]
	v_mfma_f32_16x16x32_bf16 v[158:161], v[90:93], v[188:191], v[158:161]
	v_mfma_f32_16x16x32_bf16 v[154:157], v[110:113], v[188:191], v[154:157]
	v_mfma_f32_16x16x32_bf16 v[150:153], v[90:93], v[216:219], v[150:153]
	v_mfma_f32_16x16x32_bf16 v[146:149], v[110:113], v[216:219], v[146:149]
	s_setprio 0
	s_barrier
	s_add_i32 s9, 0, 0x1c000
	s_add_i32 s8, s8, s2
	s_add_i32 m0, s8, 0xffffff80
	ds_read_b128 v[220:223], v183 offset:49152
	ds_read_b128 v[224:227], v183 offset:50176
	ds_read_b128 v[228:231], v183 offset:51200
	ds_read_b128 v[232:235], v183 offset:52224
	global_load_lds_dwordx4 v0, s[44:45] offset:128
	s_add_i32 m0, s8, 0x1f80
	s_nop 0
	global_load_lds_dwordx4 v162, s[44:45] offset:128
	s_barrier
	s_waitcnt lgkmcnt(0)
	s_setprio 1
	s_waitcnt lgkmcnt(0)
	v_mfma_f32_16x16x32_bf16 v[94:97], v[220:223], v[184:187], v[94:97]
	v_mfma_f32_16x16x32_bf16 v[22:25], v[220:223], v[134:137], v[22:25]
	v_mfma_f32_16x16x32_bf16 v[18:21], v[228:231], v[134:137], v[18:21]
	v_mfma_f32_16x16x32_bf16 v[6:9], v[220:223], v[142:145], v[6:9]
	v_mfma_f32_16x16x32_bf16 v[2:5], v[228:231], v[142:145], v[2:5]
	v_mfma_f32_16x16x32_bf16 v[142:145], v[224:227], v[188:191], v[94:97]
	v_mfma_f32_16x16x32_bf16 v[94:97], v[228:231], v[184:187], v[98:101]
	v_mfma_f32_16x16x32_bf16 v[22:25], v[224:227], v[138:141], v[22:25]
	v_mfma_f32_16x16x32_bf16 v[18:21], v[232:235], v[138:141], v[18:21]
	v_mfma_f32_16x16x32_bf16 v[138:141], v[232:235], v[188:191], v[94:97]
	v_mfma_f32_16x16x32_bf16 v[94:97], v[220:223], v[212:215], v[102:105]
	v_mfma_f32_16x16x32_bf16 v[134:137], v[224:227], v[216:219], v[94:97]
	v_mfma_f32_16x16x32_bf16 v[94:97], v[228:231], v[212:215], v[130:133]
	v_mfma_f32_16x16x32_bf16 v[6:9], v[224:227], v[172:175], v[6:9]
	v_mfma_f32_16x16x32_bf16 v[2:5], v[232:235], v[172:175], v[2:5]
	v_mfma_f32_16x16x32_bf16 v[130:133], v[232:235], v[216:219], v[94:97]
	s_setprio 0
	s_mov_b32 m0, s55
	s_barrier
	s_nop 0
	ds_read_b128 v[94:97], v195 offset:49152
	ds_read_b128 v[98:101], v195 offset:50176
	ds_read_b128 v[102:105], v195 offset:51200
	ds_read_b128 v[172:175], v195 offset:52224
	ds_read_b128 v[184:187], v195 offset:53248
	ds_read_b128 v[188:191], v195 offset:54272
	ds_read_b128 v[212:215], v195 offset:55296
	ds_read_b128 v[216:219], v195 offset:56320
	global_load_lds_dwordx4 v166, s[46:47]
	s_mov_b32 m0, s93
	s_nop 0
	global_load_lds_dwordx4 v164, s[46:47]
	s_barrier
; #define PG8_STAGE(bufoff, gbase, voff) do { _Pragma("unroll") for (int _i = 0; _i < 2; ++_i) \
;     __builtin_amdgcn_global_load_lds((const unsigned*)((const char*)(gbase) + (voff)[_i]), (LAS unsigned*)(lds + (bufoff) + ldsw + _i * 8192), 16, 0, 0); } while (0)
; #define PG8_MMA(ai, bj, At, Bt) do { __builtin_amdgcn_s_setprio(1); _Pragma("unroll") for (int m = 0; m < 4; ++m) _Pragma("unroll") for (int n = 0; n < 2; ++n) _Pragma("unroll") for (int k = 0; k < 2; ++k) \
;     acc[ai][bj][m][n] = __builtin_amdgcn_mfma_f32_16x16x32_bf16(Bt[n][k], At[m][k], acc[ai][bj][m][n], 0, 0, 0); __builtin_amdgcn_s_setprio(0); } while (0)
; #define PG8_WAIT_V(n) asm volatile("s_waitcnt vmcnt(" #n ")" ::: "memory")
; #define PG8_WAIT_L(n) asm volatile("s_waitcnt lgkmcnt(" #n ")" ::: "memory")
; #define PG8_BAR __builtin_amdgcn_s_barrier()
; template <class Epi, bool SPLITA = false>
; __device__ __forceinline__ void gemm_phase(const int tid, LAS unsigned char* lds, const Gemm g, const Order& S, const Epi& E) {
;     ...
;       PG8_BAR; PG8_WAIT_L(0); PG8_MMA(1, 0, At, B0); PG8_BAR; PG8_SCHED;
;       PG8_STAGE(PG8_SB(1, 1), b3 + hstepB, voffB);
;       PG8_WAIT_V(6); PG8_BAR; PG8_MMA(1, 1, At, B1); PG8_BAR;
;     }
;     E(acc, cur, wr, wc, fr, fq);
;   __device__ __forceinline__ void operator()(Acc& acc, const Unit& u, int wr, int wc, int fr_, int fq_) const {
;     ...
;     const int ch0 = u.pn * 128 + wc * 32 + 8 * fq;
;     f32x4 w0[2], w1[2], w2[2], bb[2];
; #pragma unroll
;     for (int n = 0; n < 2; ++n) { w0[n] = *(const f32x4*)(wconv + ch0 + 4 * n); w1[n] = *(const f32x4*)(wconv + DFF + ch0 + 4 * n);
;       w2[n] = *(const f32x4*)(wconv + 2 * DFF + ch0 + 4 * n); bb[n] = *(const f32x4*)(bconv + ch0 + 4 * n); }
;     if (u.pm == 128) {
;       if (wr == 0) {
; #pragma unroll
;         for (int m = 0; m < 2; ++m) { const int rec = 1024 + m * 16 + fr; bf16_t* rp = EDGE + (size_t)rec * 3 * DFF + ch0;
;           f32x4 p0 = w1[0] * acc[0][0][m][0] + bb[0], p1 = w1[1] * acc[0][0][m][1] + bb[1];
;           *(u32x4*)(rp) = pack8(p0, p1); *(u32x4*)(rp + DFF) = pack8(acc[0][0][m][0], acc[0][0][m][1]); *(u32x4*)(rp + 2 * DFF) = pack8(acc[0][1][m][0], acc[0][1][m][1]); }
;       }
;       return;
;     }
; #pragma unroll
;     for (int ai = 0; ai < 2; ++ai)
; #pragma unroll
;       for (int m = 0; m < 4; ++m) { const float rstd = rss[u.pm * BM + ai * HALF + wr * 64 + m * 16 + fr];
	s_waitcnt lgkmcnt(0)
	s_setprio 1
	s_waitcnt lgkmcnt(0)
	v_mfma_f32_16x16x32_bf16 v[126:129], v[86:89], v[94:97], v[126:129]
	v_mfma_f32_16x16x32_bf16 v[122:125], v[106:109], v[94:97], v[122:125]
	v_mfma_f32_16x16x32_bf16 v[118:121], v[86:89], v[102:105], v[118:121]
	v_mfma_f32_16x16x32_bf16 v[114:117], v[106:109], v[102:105], v[114:117]
	v_mfma_f32_16x16x32_bf16 v[70:73], v[86:89], v[184:187], v[70:73]
	v_mfma_f32_16x16x32_bf16 v[66:69], v[106:109], v[184:187], v[66:69]
	v_mfma_f32_16x16x32_bf16 v[54:57], v[86:89], v[212:215], v[54:57]
	v_mfma_f32_16x16x32_bf16 v[50:53], v[106:109], v[212:215], v[50:53]
	v_mfma_f32_16x16x32_bf16 v[126:129], v[90:93], v[98:101], v[126:129]
	v_mfma_f32_16x16x32_bf16 v[122:125], v[110:113], v[98:101], v[122:125]
	v_mfma_f32_16x16x32_bf16 v[118:121], v[90:93], v[172:175], v[118:121]
	v_mfma_f32_16x16x32_bf16 v[114:117], v[110:113], v[172:175], v[114:117]
	v_mfma_f32_16x16x32_bf16 v[70:73], v[90:93], v[188:191], v[70:73]
	v_mfma_f32_16x16x32_bf16 v[66:69], v[110:113], v[188:191], v[66:69]
	v_mfma_f32_16x16x32_bf16 v[54:57], v[90:93], v[216:219], v[54:57]
	v_mfma_f32_16x16x32_bf16 v[50:53], v[110:113], v[216:219], v[50:53]
	s_setprio 0
	s_barrier
	s_add_u32 s20, s44, 0x80080
	s_addc_u32 s21, s45, 0
	s_add_i32 s8, s9, s2
	s_mov_b32 m0, s8
	s_nop 0
	global_load_lds_dwordx4 v0, s[20:21]
	s_add_i32 m0, s8, 0x2000
	s_nop 0
	global_load_lds_dwordx4 v162, s[20:21]
	s_waitcnt vmcnt(6)
	s_barrier
	s_setprio 1
	v_mfma_f32_16x16x32_bf16 v[78:81], v[220:223], v[94:97], v[78:81]
	v_mfma_f32_16x16x32_bf16 v[110:113], v[224:227], v[98:101], v[78:81]
	v_mfma_f32_16x16x32_bf16 v[78:81], v[228:231], v[94:97], v[82:85]
	v_mfma_f32_16x16x32_bf16 v[62:65], v[220:223], v[102:105], v[62:65]
	v_mfma_f32_16x16x32_bf16 v[58:61], v[228:231], v[102:105], v[58:61]
	v_mfma_f32_16x16x32_bf16 v[46:49], v[220:223], v[184:187], v[46:49]
	v_mfma_f32_16x16x32_bf16 v[42:45], v[228:231], v[184:187], v[42:45]
	v_mfma_f32_16x16x32_bf16 v[38:41], v[220:223], v[212:215], v[38:41]
	v_mfma_f32_16x16x32_bf16 v[34:37], v[228:231], v[212:215], v[34:37]
	v_mfma_f32_16x16x32_bf16 v[106:109], v[232:235], v[98:101], v[78:81]
	v_mfma_f32_16x16x32_bf16 v[62:65], v[224:227], v[172:175], v[62:65]
	v_mfma_f32_16x16x32_bf16 v[58:61], v[232:235], v[172:175], v[58:61]
	v_mfma_f32_16x16x32_bf16 v[46:49], v[224:227], v[188:191], v[46:49]
	v_mfma_f32_16x16x32_bf16 v[42:45], v[232:235], v[188:191], v[42:45]
	v_mfma_f32_16x16x32_bf16 v[38:41], v[224:227], v[216:219], v[38:41]
	v_mfma_f32_16x16x32_bf16 v[34:37], v[232:235], v[216:219], v[34:37]
	s_setprio 0
	s_add_i32 s29, s29, 2
	s_add_u32 s42, s42, 0x100
	s_addc_u32 s43, s43, 0
	s_cmp_gt_u32 s29, 29
	s_barrier
	s_cbranch_scc0 .LBB0_144
	s_lshl_b32 s3, s6, 7
	v_mov_b32_e32 v172, v179
	v_mov_b32_e32 v74, v177
	s_or_b32 s3, s3, s54
	s_cmpk_eq_i32 s90, 0x80
	v_lshl_add_u32 v174, v74, 3, s3
	v_ashrrev_i32_e32 v175, 31, v174
	v_lshlrev_b64 v[90:91], 2, v[174:175]
	v_lshl_add_u64 v[78:79], s[48:49], 0, v[90:91]
	v_lshl_add_u64 v[86:87], s[16:17], 0, v[90:91]
	global_load_dwordx4 v[74:77], v[78:79], off offset:16
	s_nop 0
	global_load_dwordx4 v[78:81], v[78:79], off
	s_nop 0
	global_load_dwordx4 v[82:85], v[86:87], off offset:16
	s_nop 0
	global_load_dwordx4 v[86:89], v[86:87], off
	s_mov_b64 s[6:7], -1
	s_movk_i32 s94, 0x1000
	v_mov_b32_e32 v219, v178
	s_cbranch_scc1 .LBB0_163
	v_readlane_b32 s6, v255, 40
	v_readlane_b32 s7, v255, 41
	s_lshl_b32 s3, s90, 8
	s_add_i32 s3, s3, s4
	v_lshl_add_u64 v[92:93], s[6:7], 0, v[90:91]
	v_readlane_b32 s6, v255, 45
	v_readlane_b32 s7, v255, 46
	v_add_u32_e32 v180, s3, v172
	v_ashrrev_i32_e32 v181, 31, v180
	v_lshl_add_u64 v[98:99], s[6:7], 0, v[90:91]
	v_readlane_b32 s6, v255, 36
	v_readlane_b32 s7, v255, 37
	global_load_dwordx4 v[94:97], v[92:93], off offset:16
	global_load_dwordx4 v[102:105], v[92:93], off
	s_nop 0
	global_load_dwordx4 v[90:93], v[98:99], off offset:16
	s_nop 0
	global_load_dwordx4 v[98:101], v[98:99], off
	v_lshl_add_u64 v[198:199], v[180:181], 2, s[6:7]
	global_load_dword v176, v[198:199], off
	global_load_dword v220, v[198:199], off offset:64
	s_ashr_i32 s91, s90, 31
	s_lshl_b64 s[6:7], s[90:91], 8
	s_add_u32 s6, s6, s4
	v_readlane_b32 s3, v255, 33
	s_addc_u32 s7, s7, s3
	v_ashrrev_i32_e32 v173, 31, v172
	v_lshl_add_u64 v[228:229], s[6:7], 0, v[172:173]
	v_mov_b32_e32 v173, v1
	v_cmp_eq_u32_e64 s[42:43], 0, v172
	v_mov_b32_e32 v181, v1
	v_cmp_eq_u32_e64 s[44:45], 15, v172
	v_cmp_ne_u32_e64 s[46:47], 0, v172
	v_cmp_ne_u32_e64 s[40:41], 15, v172
	s_waitcnt vmcnt(0)
; __device__ __forceinline__ float sigmoidf_(float v) { return __builtin_amdgcn_rcpf(1.f + __builtin_amdgcn_exp2f(v * -1.4426950408889634f)); }
; __device__ __forceinline__ float dpp_ror1(float v) { return __int_as_float(__builtin_amdgcn_update_dpp(0, __float_as_int(v), 0x121, 0xf, 0xf, false)); }
;   __device__ __forceinline__ void operator()(Acc& acc, const Unit& u, int wr, int wc, int fr_, int fq_) const {
;     ...
;     for (int ai = 0; ai < 2; ++ai)
; #pragma unroll
;       for (int m = 0; m < 4; ++m) { const float rstd = rss[u.pm * BM + ai * HALF + wr * 64 + m * 16 + fr];
; #pragma unroll
;         for (int bj = 0; bj < 2; ++bj)
; #pragma unroll
;           for (int n = 0; n < 2; ++n) acc[ai][bj][m][n] *= rstd; }
; #pragma unroll
;     for (int ai = 0; ai < 2; ++ai) {
;       const int strip = u.pm * 4 + ai * 2 + wr;
; #pragma unroll
;       for (int m = 0; m < 4; ++m) {
;         f32x4 uv[2];
; #pragma unroll
;         for (int n = 0; n < 2; ++n) {
;           const f32x4 cur = acc[ai][0][m][n]; f32x4 prev, next;
; #pragma unroll
;           for (int e = 0; e < 4; ++e) {
;             const float x = dpp_ror1(cur[e]), y = m > 0 ? dpp_ror1(acc[ai][0][m > 0 ? m - 1 : 0][n][e]) : 0.f;
;             prev[e] = fr == 0 ? y : x;
;             const float x2 = dpp_ror15(cur[e]), y2 = m < 3 ? dpp_ror15(acc[ai][0][m < 3 ? m + 1 : 3][n][e]) : 0.f;
;             next[e] = fr == 15 ? y2 : x2;
;           }
;           uv[n] = w0[n] * prev + w1[n] * cur + w2[n] * next + bb[n];
;         }
;         const bool first = (m == 0 && fr == 0), lastr = (m == 3 && fr == 15);
;         if (first || lastr) {
;           const int rec = strip * 2 + (lastr ? 1 : 0); bf16_t* rp = EDGE + (size_t)rec * 3 * DFF + ch0;
;           *(u32x4*)(rp) = pack8(uv[0], uv[1]); *(u32x4*)(rp + DFF) = pack8(acc[ai][0][m][0], acc[ai][0][m][1]); *(u32x4*)(rp + 2 * DFF) = pack8(acc[ai][1][m][0], acc[ai][1][m][1]);
;         } else {
;           f32x4 o0, o1;
; #pragma unroll
;           for (int e = 0; e < 4; ++e) { o0[e] = uv[0][e] * sigmoidf_(uv[0][e]) * acc[ai][1][m][0][e]; o1[e] = uv[1][e] * sigmoidf_(uv[1][e]) * acc[ai][1][m][1][e]; }
;           const size_t row = (size_t)u.pm * BM + ai * HALF + wr * 64 + m * 16 + fr;
;           *(u32x4*)(ACT + row * DFF + ch0) = pack8(o0, o1);
	v_pk_mul_f32 v[192:193], v[32:33], v[176:177] op_sel_hi:[1,0]
	v_pk_mul_f32 v[212:213], v[30:31], v[176:177] op_sel_hi:[1,0]
	v_pk_mul_f32 v[184:185], v[28:29], v[176:177] op_sel_hi:[1,0]
	v_pk_mul_f32 v[186:187], v[26:27], v[176:177] op_sel_hi:[1,0]
	v_pk_mul_f32 v[224:225], v[24:25], v[176:177] op_sel_hi:[1,0]
	v_pk_mul_f32 v[230:231], v[22:23], v[176:177] op_sel_hi:[1,0]
	v_pk_mul_f32 v[222:223], v[20:21], v[176:177] op_sel_hi:[1,0]
	v_pk_mul_f32 v[226:227], v[18:19], v[176:177] op_sel_hi:[1,0]
	global_load_dword v218, v[198:199], off offset:128
	global_load_dword v196, v[198:199], off offset:192
	global_load_dword v182, v[198:199], off offset:512
	global_load_dword v180, v[198:199], off offset:576
	global_load_dword v178, v[198:199], off offset:640
	global_load_dword v176, v[198:199], off offset:704
	v_mov_b32_dpp v173, v212 row_ror:1 row_mask:0xf bank_mask:0xf
	v_pk_mul_f32 v[216:217], v[14:15], v[220:221] op_sel_hi:[1,0]
	v_cndmask_b32_e64 v198, v173, 0, s[42:43]
	v_mov_b32_e32 v173, v1
	v_mov_b32_dpp v181, v216 row_ror:15 row_mask:0xf bank_mask:0xf
	v_pk_mul_f32 v[214:215], v[16:17], v[220:221] op_sel_hi:[1,0]
	v_mov_b32_dpp v173, v212 row_ror:15 row_mask:0xf bank_mask:0xf
	v_cndmask_b32_e64 v200, v173, v181, s[44:45]
	v_mov_b32_e32 v173, v1
	v_mov_b32_e32 v181, v1
	v_pk_mul_f32 v[190:191], v[10:11], v[220:221] op_sel_hi:[1,0]
	v_mov_b32_dpp v173, v213 row_ror:1 row_mask:0xf bank_mask:0xf
	v_cndmask_b32_e64 v199, v173, 0, s[42:43]
	v_mov_b32_e32 v173, v1
	v_mov_b32_dpp v181, v217 row_ror:15 row_mask:0xf bank_mask:0xf
	v_pk_mul_f32 v[198:199], v[102:103], v[198:199]
	v_mov_b32_dpp v173, v213 row_ror:15 row_mask:0xf bank_mask:0xf
	v_cndmask_b32_e64 v201, v173, v181, s[44:45]
	v_mov_b32_e32 v173, v1
	v_mov_b32_e32 v181, v1
	v_pk_fma_f32 v[198:199], v[78:79], v[212:213], v[198:199]
	v_mov_b32_dpp v173, v192 row_ror:1 row_mask:0xf bank_mask:0xf
	v_cndmask_b32_e64 v202, v173, 0, s[42:43]
	v_mov_b32_e32 v173, v1
	v_mov_b32_dpp v181, v214 row_ror:15 row_mask:0xf bank_mask:0xf
	v_pk_fma_f32 v[198:199], v[98:99], v[200:201], v[198:199]
	v_mov_b32_dpp v173, v192 row_ror:15 row_mask:0xf bank_mask:0xf
	v_cndmask_b32_e64 v204, v173, v181, s[44:45]
	v_mov_b32_e32 v173, v1
	v_mov_b32_e32 v181, v1
	v_pk_mul_f32 v[188:189], v[12:13], v[220:221] op_sel_hi:[1,0]
	v_mov_b32_dpp v173, v193 row_ror:1 row_mask:0xf bank_mask:0xf
	v_cndmask_b32_e64 v203, v173, 0, s[42:43]
	v_mov_b32_e32 v173, v1
	v_mov_b32_dpp v181, v215 row_ror:15 row_mask:0xf bank_mask:0xf
	v_pk_mul_f32 v[202:203], v[104:105], v[202:203]
	v_mov_b32_dpp v173, v193 row_ror:15 row_mask:0xf bank_mask:0xf
	v_cndmask_b32_e64 v205, v173, v181, s[44:45]
	v_mov_b32_e32 v173, v1
	v_mov_b32_e32 v181, v1
	v_pk_fma_f32 v[202:203], v[80:81], v[192:193], v[202:203]
	v_mov_b32_dpp v173, v186 row_ror:1 row_mask:0xf bank_mask:0xf
	v_cndmask_b32_e64 v236, v173, 0, s[42:43]
	v_mov_b32_e32 v173, v1
	v_mov_b32_dpp v181, v190 row_ror:15 row_mask:0xf bank_mask:0xf
	v_pk_add_f32 v[234:235], v[86:87], v[198:199]
	v_mov_b32_dpp v173, v186 row_ror:15 row_mask:0xf bank_mask:0xf
	v_cndmask_b32_e64 v238, v173, v181, s[44:45]
	v_mov_b32_e32 v173, v1
	v_mov_b32_e32 v181, v1
	v_pk_fma_f32 v[200:201], v[100:101], v[204:205], v[202:203]
	v_mov_b32_dpp v173, v187 row_ror:1 row_mask:0xf bank_mask:0xf
	v_cndmask_b32_e64 v237, v173, 0, s[42:43]
	v_mov_b32_e32 v173, v1
	v_mov_b32_dpp v181, v191 row_ror:15 row_mask:0xf bank_mask:0xf
	v_pk_add_f32 v[232:233], v[88:89], v[200:201]
	v_mov_b32_dpp v173, v187 row_ror:15 row_mask:0xf bank_mask:0xf
	v_cndmask_b32_e64 v239, v173, v181, s[44:45]
	v_mov_b32_e32 v173, v1
	v_mov_b32_e32 v181, v1
	v_pk_mul_f32 v[202:203], v[94:95], v[236:237]
	v_mov_b32_dpp v173, v184 row_ror:1 row_mask:0xf bank_mask:0xf
	v_cndmask_b32_e64 v198, v173, 0, s[42:43]
	v_mov_b32_e32 v173, v1
	v_mov_b32_dpp v181, v188 row_ror:15 row_mask:0xf bank_mask:0xf
	v_pk_fma_f32 v[202:203], v[74:75], v[186:187], v[202:203]
	v_mov_b32_dpp v173, v184 row_ror:15 row_mask:0xf bank_mask:0xf
	v_cndmask_b32_e64 v200, v173, v181, s[44:45]
	v_mov_b32_e32 v173, v1
	v_mov_b32_e32 v181, v1
	v_pk_fma_f32 v[202:203], v[90:91], v[238:239], v[202:203]
	v_mov_b32_dpp v173, v185 row_ror:1 row_mask:0xf bank_mask:0xf
	v_cndmask_b32_e64 v199, v173, 0, s[42:43]
	v_mov_b32_e32 v173, v1
	v_mov_b32_dpp v181, v189 row_ror:15 row_mask:0xf bank_mask:0xf
	v_pk_mul_f32 v[198:199], v[96:97], v[198:199]
	v_mov_b32_dpp v173, v185 row_ror:15 row_mask:0xf bank_mask:0xf
	v_cndmask_b32_e64 v201, v173, v181, s[44:45]
	v_pk_fma_f32 v[198:199], v[76:77], v[184:185], v[198:199]
	v_pk_add_f32 v[240:241], v[82:83], v[202:203]
	v_pk_fma_f32 v[198:199], v[92:93], v[200:201], v[198:199]
	s_nop 0
	v_pk_add_f32 v[238:239], v[84:85], v[198:199]
	s_and_saveexec_b64 s[6:7], s[46:47]
	s_xor_b64 vcc, exec, s[6:7]
	s_cbranch_execz .LBB0_148
	v_mul_f32_e32 v173, 0xbfb8aa3b, v234
	v_exp_f32_e32 v173, v173
	v_mad_u64_u32 v[236:237], s[6:7], v228, s24, 0
	v_mad_i32_i24 v237, v229, s24, v237
	v_add_f32_e32 v173, 1.0, v173
	v_rcp_f32_e32 v198, v173
	v_mul_f32_e32 v173, 0xbfb8aa3b, v240
	v_exp_f32_e32 v173, v173
	s_nop 0
	v_add_f32_e32 v173, 1.0, v173
	v_rcp_f32_e32 v200, v173
	v_mul_f32_e32 v173, 0xbfb8aa3b, v235
	v_exp_f32_e32 v173, v173
	s_nop 0
	v_add_f32_e32 v173, 1.0, v173
	v_rcp_f32_e32 v199, v173
	v_mul_f32_e32 v173, 0xbfb8aa3b, v241
	v_exp_f32_e32 v173, v173
	v_pk_mul_f32 v[198:199], v[234:235], v[198:199]
	s_nop 0
	v_pk_mul_f32 v[198:199], v[230:231], v[198:199]
	v_add_f32_e32 v173, 1.0, v173
	v_rcp_f32_e32 v201, v173
	v_mul_f32_e32 v173, 0xbfb8aa3b, v232
	v_exp_f32_e32 v173, v173
	v_pk_mul_f32 v[200:201], v[240:241], v[200:201]
	s_nop 0
	v_pk_mul_f32 v[200:201], v[226:227], v[200:201]
	v_add_f32_e32 v173, 1.0, v173
	v_rcp_f32_e32 v202, v173
	v_mul_f32_e32 v173, 0xbfb8aa3b, v238
	v_exp_f32_e32 v173, v173
	s_nop 0
	v_add_f32_e32 v173, 1.0, v173
	v_rcp_f32_e32 v204, v173
	v_mul_f32_e32 v173, 0xbfb8aa3b, v233
	v_exp_f32_e32 v173, v173
	s_nop 0
	v_add_f32_e32 v173, 1.0, v173
	v_rcp_f32_e32 v203, v173
	v_mul_f32_e32 v173, 0xbfb8aa3b, v239
	v_exp_f32_e32 v173, v173
	v_pk_mul_f32 v[202:203], v[232:233], v[202:203]
	s_nop 0
	v_pk_mul_f32 v[202:203], v[224:225], v[202:203]
	v_add_f32_e32 v173, 1.0, v173
	v_rcp_f32_e32 v205, v173
	v_cvt_pk_bf16_f32 v224, v200, v201
	v_pk_mul_f32 v[204:205], v[238:239], v[204:205]
	s_nop 0
	v_pk_mul_f32 v[204:205], v[222:223], v[204:205]
	v_cvt_pk_bf16_f32 v222, v198, v199
	v_mov_b64_e32 v[198:199], s[34:35]
	v_mad_u64_u32 v[198:199], s[6:7], v228, s24, v[198:199]
	v_mad_i32_i24 v199, v229, s24, v199
	v_cvt_pk_bf16_f32 v223, v202, v203
	v_cvt_pk_bf16_f32 v225, v204, v205
	v_lshl_add_u64 v[198:199], v[174:175], 1, v[198:199]
	global_store_dwordx4 v[198:199], v[222:225], off

; #define PG8_STAGE(bufoff, gbase, voff) do { _Pragma("unroll") for (int _i = 0; _i < 2; ++_i) \
;     __builtin_amdgcn_global_load_lds((const unsigned*)((const char*)(gbase) + (voff)[_i]), (LAS unsigned*)(lds + (bufoff) + ldsw + _i * 8192), 16, 0, 0); } while (0)
; #define PG8_WAIT_V(n) asm volatile("s_waitcnt vmcnt(" #n ")" ::: "memory")
; template <class Epi, bool SPLITA = false>
; __device__ __forceinline__ void gemm_phase(const int tid, LAS unsigned char* lds, const Gemm g, const Order& S, const Epi& E) {
;   const int wid = __builtin_amdgcn_readfirstlane(tid >> 6), lane = tid & 63, wr = wid >> 2, wc = wid & 3, fr = lane & 15, fq = lane >> 4;
;   const int K = g.K, nt = K / BK;
;   unsigned voffA[2], voffB[2];
; #pragma unroll
;   for (int i = 0; i < 2; ++i) { int R, C; stage_rc(tid * 16 + i * 8192, R, C); const int Rb = Epi::PERM ? ((R & ~31) + perm32(R & 31)) : R;
;     voffA[i] = (unsigned)(R * g.lda + C) * 2u; voffB[i] = (unsigned)(Rb * g.ldb + C) * 2u; }
;   const size_t kstep = (size_t)(BK * 2);
;   const size_t hstepA = (size_t)HALF * g.lda * 2, hstepB = (size_t)HALF * g.ldb * 2;
;   const size_t tstepA = 2 * hstepA, tstepB = g.bpn < 0 ? 2 * hstepB : (size_t)g.bpn, apn = (size_t)g.apn;
;   const unsigned ldsw = (unsigned)wid * 1024u;
;   const int aoff = lds_byte(wr * 64 + fr, fq * 8), boff = lds_byte(wc * 32 + fr, fq * 8);
;     ...
;   Unit cur, nxt; int ui = 0;
;   if (!S.next(0, cur)) return;
;   Acc acc;
; #pragma unroll
;   for (int a = 0; a < 2; ++a)
; #pragma unroll
;     for (int b = 0; b < 2; ++b)
; #pragma unroll
;       for (int m = 0; m < 4; ++m)
; #pragma unroll
;         for (int n = 0; n < 2; ++n) acc[a][b][m][n] = (f32x4){0.f, 0.f, 0.f, 0.f};
;   bf16x8 At[4][2], B0[2][2], B1[2][2];
;   const char* cA = (const char*)g.A + (size_t)cur.pm * tstepA + (size_t)cur.pn * apn; const char* cB = (const char*)g.Bt + (size_t)cur.pn * tstepB;
;   const char* cA2 = SPLITA ? (const char*)g.A2 + (size_t)cur.pm * tstepA : cA; const int nt1 = SPLITA ? g.nt1 : nt;
;     ...
;   PG8_STAGE(PG8_SB(0, 0), cB, voffB); PG8_STAGE(PG8_SA(0, 0), cA, voffA); PG8_STAGE(PG8_SB(0, 1), cB + hstepB, voffB); PG8_STAGE(PG8_SA(0, 1), cA + hstepA, voffA);
;   if (wr == 1) PG8_BAR;
;   PG8_WAIT_V(4); PG8_BAR;
;   PG8_STAGE(PG8_SB(1, 0), cB + kstep, voffB); PG8_STAGE(PG8_SA(1, 0), cA + kstep, voffA); PG8_STAGE(PG8_SB(1, 1), cB + hstepB + kstep, voffB);
;   PG8_WAIT_V(6); PG8_BAR;
.LBB0_183:
	v_bfe_u32 v186, v210, 4, 2
	v_lshl_add_u64 v[8:9], s[42:43], 0, v[0:1]
	v_mov_b32_e32 v163, v1
	v_and_b32_e32 v187, 15, v210
	v_lshlrev_b32_e32 v16, 4, v186
	v_lshlrev_b32_e32 v17, 2, v210
	v_mov_b32_e32 v159, v1
	s_and_b32 s54, s2, 3
	v_lshl_or_b32 v16, v187, 6, v16
	s_lshl_b32 s2, s4, 13
	v_and_b32_e32 v17, 32, v17
	s_add_i32 m0, s23, 0x18000
	v_lshl_add_u64 v[8:9], v[8:9], 0, s[96:97]
	v_mov_b32_e32 v161, v1
	s_lshl_b32 s55, s4, 6
	v_bitop3_b32 v18, v16, s2, v17 bitop3:0xde
	s_lshl_b32 s90, s54, 5
	s_lshl_b32 s2, s54, 12
	s_waitcnt vmcnt(4)
	s_barrier
	global_load_lds_dwordx4 v[8:9], off
	s_add_i32 m0, s23, 0x19f80
	s_add_i32 s91, s23, 0x8000
	s_add_i32 s93, s23, 0xa000
	global_load_lds_dwordx4 v162, s[42:43] offset:128
	s_add_i32 m0, s91, 0xffffff80
	s_add_u32 s6, s42, 0x80080
	global_load_lds_dwordx4 v158, s[40:41] offset:128
	s_add_i32 m0, s93, 0xffffff80
	s_addc_u32 s7, s43, 0
	global_load_lds_dwordx4 v160, s[40:41] offset:128
	s_add_i32 m0, s23, 0x1c000
	s_nop 0
	global_load_lds_dwordx4 v0, s[6:7]
	v_lshl_add_u64 v[8:9], s[6:7], 0, v[162:163]
	s_add_i32 m0, s23, 0x1e000
	v_bitop3_b32 v188, v16, s2, v17 bitop3:0xde
	v_add_u32_e32 v188, 0x10000, v188
	global_load_lds_dwordx4 v162, s[6:7]
	v_lshlrev_b32_e32 v8, 15, v2
	v_and_b32_e32 v8, 0xffff0000, v8
	v_lshl_add_u32 v3, v3, 12, v8
	v_and_b32_e32 v2, 1, v2
	v_lshl_or_b32 v2, v2, 6, v3
	v_lshl_add_u32 v164, v4, 1, v2
	v_lshlrev_b32_e32 v2, 15, v5
	v_and_b32_e32 v2, 0xffff0000, v2
	s_waitcnt vmcnt(6)
	v_lshl_add_u32 v2, v6, 12, v2
	v_and_b32_e32 v3, 1, v5
	v_lshl_or_b32 v2, v3, 6, v2
	s_ashr_i32 s2, s92, 31
	v_mov_b32_e32 v165, v1
	v_lshl_add_u32 v166, v7, 1, v2
	v_mov_b32_e32 v167, v1
	s_mov_b32 s28, 0
	v_add_u32_e32 v189, 0, v18
	s_barrier
	s_branch .LBB0_185

; #define PG8_STAGE(bufoff, gbase, voff) do { _Pragma("unroll") for (int _i = 0; _i < 2; ++_i) \
;     __builtin_amdgcn_global_load_lds((const unsigned*)((const char*)(gbase) + (voff)[_i]), (LAS unsigned*)(lds + (bufoff) + ldsw + _i * 8192), 16, 0, 0); } while (0)
; #define PG8_LDA(dst, b, h) do { _Pragma("unroll") for (int m = 0; m < 4; ++m) _Pragma("unroll") for (int k = 0; k < 2; ++k) dst[m][k] = *(const LAS bf16x8*)(lds + PG8_SA(b, h) + aoff + m * 2048 + k * 1024); } while (0)
; #define PG8_LDB(dst, b, h) do { _Pragma("unroll") for (int n = 0; n < 2; ++n) _Pragma("unroll") for (int k = 0; k < 2; ++k) dst[n][k] = *(const LAS bf16x8*)(lds + PG8_SB(b, h) + boff + n * 2048 + k * 1024); } while (0)
; #define PG8_MMA(ai, bj, At, Bt) do { __builtin_amdgcn_s_setprio(1); _Pragma("unroll") for (int m = 0; m < 4; ++m) _Pragma("unroll") for (int n = 0; n < 2; ++n) _Pragma("unroll") for (int k = 0; k < 2; ++k) \
;     acc[ai][bj][m][n] = __builtin_amdgcn_mfma_f32_16x16x32_bf16(Bt[n][k], At[m][k], acc[ai][bj][m][n], 0, 0, 0); __builtin_amdgcn_s_setprio(0); } while (0)
; #define PG8_WAIT_L(n) asm volatile("s_waitcnt lgkmcnt(" #n ")" ::: "memory")
; #define PG8_BAR __builtin_amdgcn_s_barrier()
; #define PG8_SCHED __builtin_amdgcn_sched_barrier(0)
; template <class Epi, bool SPLITA = false>
; __device__ __forceinline__ void gemm_phase(const int tid, LAS unsigned char* lds, const Gemm g, const Order& S, const Epi& E) {
;     ...
;       PG8_LDB(B0, 0, 0); PG8_SCHED; PG8_LDA(At, 0, 0); PG8_STAGE(PG8_SA(1, 1), a1 + hstepA, voffA);
;       PG8_WAIT_L(8); PG8_BAR; PG8_WAIT_L(0); PG8_MMA(0, 0, At, B0); PG8_BAR; PG8_SCHED;
;       PG8_LDB(B1, 0, 1); PG8_STAGE(PG8_SB(0, 0), b2, voffB);
;       PG8_BAR; PG8_WAIT_L(0); PG8_MMA(0, 1, At, B1); PG8_BAR;
;       PG8_LDA(At, 0, 1); PG8_STAGE(PG8_SA(0, 0), a2, voffA);
;       PG8_BAR; PG8_WAIT_L(0); PG8_MMA(1, 0, At, B0); PG8_BAR; PG8_SCHED;
.LBB0_192:
	s_add_u32 s20, s40, s42
	s_addc_u32 s21, s41, s43
	s_add_u32 s48, s20, 0x100
	s_addc_u32 s49, s21, 0
	s_add_u32 s44, vcc_lo, s42
	s_addc_u32 s45, vcc_hi, s43
	s_add_u32 s20, s20, 0x180
	s_addc_u32 s21, s21, 0
	s_add_i32 s94, 0, 0x10000
	ds_read_b128 v[134:137], v188
	ds_read_b128 v[138:141], v188 offset:1024
	ds_read_b128 v[142:145], v188 offset:2048
	ds_read_b128 v[146:149], v188 offset:3072
	s_cmpk_eq_i32 s42, 0xf00
	s_cselect_b32 s47, s19, s21
	s_cselect_b32 s46, s13, s20
	s_cselect_b32 s45, s7, s45
	s_cselect_b32 s44, s11, s44
	s_cselect_b32 s49, s4, s49
	s_cselect_b32 s48, s6, s48
	v_lshl_add_u64 v[184:185], v[130:131], 0, s[42:43]
	s_add_i32 m0, s23, 0xc000
	ds_read_b128 v[150:153], v189
	ds_read_b128 v[154:157], v189 offset:1024
	ds_read_b128 v[168:171], v189 offset:2048
	ds_read_b128 v[172:175], v189 offset:3072
	ds_read_b128 v[176:179], v189 offset:4096
	ds_read_b128 v[180:183], v189 offset:5120
	ds_read_b128 v[190:193], v189 offset:6144
	ds_read_b128 v[212:215], v189 offset:7168
	global_load_lds_dwordx4 v[184:185], off
	v_lshl_add_u64 v[184:185], v[132:133], 0, s[42:43]
	s_add_i32 m0, s23, 0xe000
	s_nop 0
	global_load_lds_dwordx4 v[184:185], off
	s_waitcnt lgkmcnt(8)
	s_barrier
	s_waitcnt lgkmcnt(0)
	s_setprio 1
	s_waitcnt lgkmcnt(0)
	v_mfma_f32_16x16x32_bf16 v[126:129], v[134:137], v[150:153], v[126:129]
	v_mfma_f32_16x16x32_bf16 v[122:125], v[142:145], v[150:153], v[122:125]
	v_mfma_f32_16x16x32_bf16 v[110:113], v[134:137], v[168:171], v[110:113]
	v_mfma_f32_16x16x32_bf16 v[106:109], v[142:145], v[168:171], v[106:109]
	v_mfma_f32_16x16x32_bf16 v[94:97], v[134:137], v[176:179], v[94:97]
	v_mfma_f32_16x16x32_bf16 v[90:93], v[142:145], v[176:179], v[90:93]
	v_mfma_f32_16x16x32_bf16 v[78:81], v[134:137], v[190:193], v[78:81]
	v_mfma_f32_16x16x32_bf16 v[74:77], v[142:145], v[190:193], v[74:77]
	v_mfma_f32_16x16x32_bf16 v[126:129], v[138:141], v[154:157], v[126:129]
	v_mfma_f32_16x16x32_bf16 v[122:125], v[146:149], v[154:157], v[122:125]
	v_mfma_f32_16x16x32_bf16 v[110:113], v[138:141], v[172:175], v[110:113]
	v_mfma_f32_16x16x32_bf16 v[106:109], v[146:149], v[172:175], v[106:109]
	v_mfma_f32_16x16x32_bf16 v[94:97], v[138:141], v[180:183], v[94:97]
	v_mfma_f32_16x16x32_bf16 v[90:93], v[146:149], v[180:183], v[90:93]
	v_mfma_f32_16x16x32_bf16 v[78:81], v[138:141], v[212:215], v[78:81]
	v_mfma_f32_16x16x32_bf16 v[74:77], v[146:149], v[212:215], v[74:77]
	s_setprio 0
	s_barrier
	s_add_i32 s8, 0, 0x14000
	s_add_i32 s9, s94, s3
	ds_read_b128 v[216:219], v188 offset:16384
	ds_read_b128 v[220:223], v188 offset:17408
	ds_read_b128 v[224:227], v188 offset:18432
	ds_read_b128 v[228:231], v188 offset:19456
	s_mov_b32 m0, s9
	s_nop 0
	global_load_lds_dwordx4 v0, s[44:45]
	s_add_i32 m0, s9, 0x2000
	s_nop 0
	global_load_lds_dwordx4 v162, s[44:45]
	s_barrier
	s_waitcnt lgkmcnt(0)
	s_setprio 1
	s_waitcnt lgkmcnt(0)
	v_mfma_f32_16x16x32_bf16 v[118:121], v[216:219], v[150:153], v[118:121]
	v_mfma_f32_16x16x32_bf16 v[114:117], v[224:227], v[150:153], v[114:117]
	v_mfma_f32_16x16x32_bf16 v[102:105], v[216:219], v[168:171], v[102:105]
	v_mfma_f32_16x16x32_bf16 v[98:101], v[224:227], v[168:171], v[98:101]
	v_mfma_f32_16x16x32_bf16 v[86:89], v[216:219], v[176:179], v[86:89]
	v_mfma_f32_16x16x32_bf16 v[82:85], v[224:227], v[176:179], v[82:85]
	v_mfma_f32_16x16x32_bf16 v[70:73], v[216:219], v[190:193], v[70:73]
	v_mfma_f32_16x16x32_bf16 v[66:69], v[224:227], v[190:193], v[66:69]
	v_mfma_f32_16x16x32_bf16 v[118:121], v[220:223], v[154:157], v[118:121]
	v_mfma_f32_16x16x32_bf16 v[114:117], v[228:231], v[154:157], v[114:117]
	v_mfma_f32_16x16x32_bf16 v[102:105], v[220:223], v[172:175], v[102:105]
	v_mfma_f32_16x16x32_bf16 v[98:101], v[228:231], v[172:175], v[98:101]
	v_mfma_f32_16x16x32_bf16 v[86:89], v[220:223], v[180:183], v[86:89]
	v_mfma_f32_16x16x32_bf16 v[82:85], v[228:231], v[180:183], v[82:85]
	v_mfma_f32_16x16x32_bf16 v[70:73], v[220:223], v[212:215], v[70:73]
	v_mfma_f32_16x16x32_bf16 v[66:69], v[228:231], v[212:215], v[66:69]
	s_setprio 0
	s_mov_b32 m0, s23
	s_barrier
	ds_read_b128 v[150:153], v189 offset:16384
	ds_read_b128 v[154:157], v189 offset:17408
	ds_read_b128 v[168:171], v189 offset:18432
	ds_read_b128 v[172:175], v189 offset:19456
	ds_read_b128 v[176:179], v189 offset:20480
	ds_read_b128 v[180:183], v189 offset:21504
	ds_read_b128 v[190:193], v189 offset:22528
	ds_read_b128 v[212:215], v189 offset:23552
	global_load_lds_dwordx4 v158, s[48:49]
	s_mov_b32 m0, s51
	s_nop 0
	global_load_lds_dwordx4 v160, s[48:49]
	s_barrier
	s_waitcnt lgkmcnt(0)
	s_setprio 1
	s_waitcnt lgkmcnt(0)
	v_mfma_f32_16x16x32_bf16 v[62:65], v[134:137], v[150:153], v[62:65]
	v_mfma_f32_16x16x32_bf16 v[58:61], v[142:145], v[150:153], v[58:61]
	v_mfma_f32_16x16x32_bf16 v[46:49], v[134:137], v[168:171], v[46:49]
	v_mfma_f32_16x16x32_bf16 v[42:45], v[142:145], v[168:171], v[42:45]
	v_mfma_f32_16x16x32_bf16 v[30:33], v[134:137], v[176:179], v[30:33]
	v_mfma_f32_16x16x32_bf16 v[26:29], v[142:145], v[176:179], v[26:29]
	v_mfma_f32_16x16x32_bf16 v[14:17], v[134:137], v[190:193], v[14:17]
	v_mfma_f32_16x16x32_bf16 v[10:13], v[142:145], v[190:193], v[10:13]
	v_mfma_f32_16x16x32_bf16 v[62:65], v[138:141], v[154:157], v[62:65]
	v_mfma_f32_16x16x32_bf16 v[58:61], v[146:149], v[154:157], v[58:61]
	v_mfma_f32_16x16x32_bf16 v[46:49], v[138:141], v[172:175], v[46:49]
	v_mfma_f32_16x16x32_bf16 v[42:45], v[146:149], v[172:175], v[42:45]
	v_mfma_f32_16x16x32_bf16 v[30:33], v[138:141], v[180:183], v[30:33]
	v_mfma_f32_16x16x32_bf16 v[26:29], v[146:149], v[180:183], v[26:29]
	v_mfma_f32_16x16x32_bf16 v[14:17], v[138:141], v[212:215], v[14:17]
	v_mfma_f32_16x16x32_bf16 v[10:13], v[146:149], v[212:215], v[10:13]
	s_setprio 0
	s_barrier
; #define PG8_STAGE(bufoff, gbase, voff) do { _Pragma("unroll") for (int _i = 0; _i < 2; ++_i) \
;     __builtin_amdgcn_global_load_lds((const unsigned*)((const char*)(gbase) + (voff)[_i]), (LAS unsigned*)(lds + (bufoff) + ldsw + _i * 8192), 16, 0, 0); } while (0)
; #define PG8_LDA(dst, b, h) do { _Pragma("unroll") for (int m = 0; m < 4; ++m) _Pragma("unroll") for (int k = 0; k < 2; ++k) dst[m][k] = *(const LAS bf16x8*)(lds + PG8_SA(b, h) + aoff + m * 2048 + k * 1024); } while (0)
; #define PG8_LDB(dst, b, h) do { _Pragma("unroll") for (int n = 0; n < 2; ++n) _Pragma("unroll") for (int k = 0; k < 2; ++k) dst[n][k] = *(const LAS bf16x8*)(lds + PG8_SB(b, h) + boff + n * 2048 + k * 1024); } while (0)
; #define PG8_MMA(ai, bj, At, Bt) do { __builtin_amdgcn_s_setprio(1); _Pragma("unroll") for (int m = 0; m < 4; ++m) _Pragma("unroll") for (int n = 0; n < 2; ++n) _Pragma("unroll") for (int k = 0; k < 2; ++k) \
;     acc[ai][bj][m][n] = __builtin_amdgcn_mfma_f32_16x16x32_bf16(Bt[n][k], At[m][k], acc[ai][bj][m][n], 0, 0, 0); __builtin_amdgcn_s_setprio(0); } while (0)
; template <class Epi, bool SPLITA = false>
; __device__ __forceinline__ void gemm_phase(const int tid, LAS unsigned char* lds, const Gemm g, const Order& S, const Epi& E) {
;     ...
;       PG8_LDB(B0, 0, 0); PG8_SCHED; PG8_LDA(At, 0, 0); PG8_STAGE(PG8_SA(1, 1), a1 + hstepA, voffA);
;       PG8_WAIT_L(8); PG8_BAR; PG8_WAIT_L(0); PG8_MMA(0, 0, At, B0); PG8_BAR; PG8_SCHED;
;       PG8_LDB(B1, 0, 1); PG8_STAGE(PG8_SB(0, 0), b2, voffB);
;       PG8_BAR; PG8_WAIT_L(0); PG8_MMA(0, 1, At, B1); PG8_BAR;
;       PG8_LDA(At, 0, 1); PG8_STAGE(PG8_SA(0, 0), a2, voffA);
;       PG8_BAR; PG8_WAIT_L(0); PG8_MMA(1, 0, At, B0); PG8_BAR; PG8_SCHED;
;       PG8_STAGE(PG8_SB(0, 1), b2 + hstepB, voffB);
;       PG8_WAIT_V(6); PG8_BAR; PG8_MMA(1, 1, At, B1); PG8_BAR;
;       PG8_LDB(B0, 1, 0); PG8_SCHED; PG8_LDA(At, 1, 0); PG8_STAGE(PG8_SA(0, 1), a2 + hstepA, voffA);
;       PG8_WAIT_L(8); PG8_BAR; PG8_WAIT_L(0); PG8_MMA(0, 0, At, B0); PG8_BAR; PG8_SCHED;
;       PG8_LDB(B1, 1, 1); PG8_STAGE(PG8_SB(1, 0), b3, voffB);
;       PG8_BAR; PG8_WAIT_L(0); PG8_MMA(0, 1, At, B1); PG8_BAR;
;       PG8_LDA(At, 1, 1); PG8_STAGE(PG8_SA(1, 0), a3, voffA);
;       PG8_BAR; PG8_WAIT_L(0); PG8_MMA(1, 0, At, B0); PG8_BAR; PG8_SCHED;
;       PG8_STAGE(PG8_SB(1, 1), b3 + hstepB, voffB);
;       PG8_WAIT_V(6); PG8_BAR; PG8_MMA(1, 1, At, B1); PG8_BAR;
	s_add_u32 s20, s44, 0x80000
	s_addc_u32 s21, s45, 0
	s_add_i32 s8, s8, s3
	s_mov_b32 m0, s8
	s_nop 0
	global_load_lds_dwordx4 v0, s[20:21]
	s_add_i32 m0, s8, 0x2000
	s_nop 0
	global_load_lds_dwordx4 v162, s[20:21]
	s_waitcnt vmcnt(6)
	s_barrier
	s_setprio 1
	v_mfma_f32_16x16x32_bf16 v[54:57], v[216:219], v[150:153], v[54:57]
	v_mfma_f32_16x16x32_bf16 v[50:53], v[224:227], v[150:153], v[50:53]
	v_mfma_f32_16x16x32_bf16 v[38:41], v[216:219], v[168:171], v[38:41]
	v_mfma_f32_16x16x32_bf16 v[34:37], v[224:227], v[168:171], v[34:37]
	v_mfma_f32_16x16x32_bf16 v[22:25], v[216:219], v[176:179], v[22:25]
	v_mfma_f32_16x16x32_bf16 v[18:21], v[224:227], v[176:179], v[18:21]
	v_mfma_f32_16x16x32_bf16 v[6:9], v[216:219], v[190:193], v[6:9]
	v_mfma_f32_16x16x32_bf16 v[2:5], v[224:227], v[190:193], v[2:5]
	v_mfma_f32_16x16x32_bf16 v[54:57], v[220:223], v[154:157], v[54:57]
	v_mfma_f32_16x16x32_bf16 v[50:53], v[228:231], v[154:157], v[50:53]
	v_mfma_f32_16x16x32_bf16 v[38:41], v[220:223], v[172:175], v[38:41]
	v_mfma_f32_16x16x32_bf16 v[34:37], v[228:231], v[172:175], v[34:37]
	v_mfma_f32_16x16x32_bf16 v[22:25], v[220:223], v[180:183], v[22:25]
	v_mfma_f32_16x16x32_bf16 v[18:21], v[228:231], v[180:183], v[18:21]
	v_mfma_f32_16x16x32_bf16 v[6:9], v[220:223], v[212:215], v[6:9]
	v_mfma_f32_16x16x32_bf16 v[2:5], v[228:231], v[212:215], v[2:5]
	s_setprio 0
	s_add_i32 s8, 0, 0x18000
	s_barrier
	ds_read_b128 v[134:137], v188 offset:32768
	ds_read_b128 v[138:141], v188 offset:33792
	ds_read_b128 v[142:145], v188 offset:34816
	ds_read_b128 v[146:149], v188 offset:35840
	s_add_u32 s20, s48, 0x80000
	s_addc_u32 s21, s49, 0
	s_mov_b32 m0, s52
	ds_read_b128 v[150:153], v189 offset:32768
	ds_read_b128 v[154:157], v189 offset:33792
	ds_read_b128 v[168:171], v189 offset:34816
	ds_read_b128 v[172:175], v189 offset:35840
	ds_read_b128 v[176:179], v189 offset:36864
	ds_read_b128 v[180:183], v189 offset:37888
	ds_read_b128 v[190:193], v189 offset:38912
	ds_read_b128 v[212:215], v189 offset:39936
	global_load_lds_dwordx4 v158, s[20:21]
	s_mov_b32 m0, s53
	s_nop 0
	global_load_lds_dwordx4 v160, s[20:21]
	s_waitcnt lgkmcnt(8)
	s_barrier
	s_waitcnt lgkmcnt(0)
	s_setprio 1
	s_waitcnt lgkmcnt(0)
	v_mfma_f32_16x16x32_bf16 v[126:129], v[134:137], v[150:153], v[126:129]
	v_mfma_f32_16x16x32_bf16 v[122:125], v[142:145], v[150:153], v[122:125]
	v_mfma_f32_16x16x32_bf16 v[110:113], v[134:137], v[168:171], v[110:113]
	v_mfma_f32_16x16x32_bf16 v[106:109], v[142:145], v[168:171], v[106:109]
	v_mfma_f32_16x16x32_bf16 v[94:97], v[134:137], v[176:179], v[94:97]
	v_mfma_f32_16x16x32_bf16 v[90:93], v[142:145], v[176:179], v[90:93]
	v_mfma_f32_16x16x32_bf16 v[78:81], v[134:137], v[190:193], v[78:81]
	v_mfma_f32_16x16x32_bf16 v[74:77], v[142:145], v[190:193], v[74:77]
	v_mfma_f32_16x16x32_bf16 v[126:129], v[138:141], v[154:157], v[126:129]
	v_mfma_f32_16x16x32_bf16 v[122:125], v[146:149], v[154:157], v[122:125]
	v_mfma_f32_16x16x32_bf16 v[110:113], v[138:141], v[172:175], v[110:113]
	v_mfma_f32_16x16x32_bf16 v[106:109], v[146:149], v[172:175], v[106:109]
	v_mfma_f32_16x16x32_bf16 v[94:97], v[138:141], v[180:183], v[94:97]
	v_mfma_f32_16x16x32_bf16 v[90:93], v[146:149], v[180:183], v[90:93]
	v_mfma_f32_16x16x32_bf16 v[78:81], v[138:141], v[212:215], v[78:81]
	v_mfma_f32_16x16x32_bf16 v[74:77], v[146:149], v[212:215], v[74:77]
	s_setprio 0
	s_barrier
	s_add_i32 s9, 0, 0x1c000
	s_add_i32 s8, s8, s3
	s_add_i32 m0, s8, 0xffffff80
	ds_read_b128 v[216:219], v188 offset:49152
	ds_read_b128 v[220:223], v188 offset:50176
	ds_read_b128 v[224:227], v188 offset:51200
	ds_read_b128 v[228:231], v188 offset:52224
	global_load_lds_dwordx4 v0, s[44:45] offset:128
	s_add_i32 m0, s8, 0x1f80
	s_nop 0
	global_load_lds_dwordx4 v162, s[44:45] offset:128
	s_barrier
	s_waitcnt lgkmcnt(0)
	s_setprio 1
	s_waitcnt lgkmcnt(0)
	v_mfma_f32_16x16x32_bf16 v[118:121], v[216:219], v[150:153], v[118:121]
	v_mfma_f32_16x16x32_bf16 v[114:117], v[224:227], v[150:153], v[114:117]
	v_mfma_f32_16x16x32_bf16 v[102:105], v[216:219], v[168:171], v[102:105]
	v_mfma_f32_16x16x32_bf16 v[98:101], v[224:227], v[168:171], v[98:101]
	v_mfma_f32_16x16x32_bf16 v[86:89], v[216:219], v[176:179], v[86:89]
	v_mfma_f32_16x16x32_bf16 v[82:85], v[224:227], v[176:179], v[82:85]
	v_mfma_f32_16x16x32_bf16 v[70:73], v[216:219], v[190:193], v[70:73]
	v_mfma_f32_16x16x32_bf16 v[66:69], v[224:227], v[190:193], v[66:69]
	v_mfma_f32_16x16x32_bf16 v[118:121], v[220:223], v[154:157], v[118:121]
	v_mfma_f32_16x16x32_bf16 v[114:117], v[228:231], v[154:157], v[114:117]
	v_mfma_f32_16x16x32_bf16 v[102:105], v[220:223], v[172:175], v[102:105]
	v_mfma_f32_16x16x32_bf16 v[98:101], v[228:231], v[172:175], v[98:101]
	v_mfma_f32_16x16x32_bf16 v[86:89], v[220:223], v[180:183], v[86:89]
	v_mfma_f32_16x16x32_bf16 v[82:85], v[228:231], v[180:183], v[82:85]
	v_mfma_f32_16x16x32_bf16 v[70:73], v[220:223], v[212:215], v[70:73]
	v_mfma_f32_16x16x32_bf16 v[66:69], v[228:231], v[212:215], v[66:69]
	s_setprio 0
	s_mov_b32 m0, s91
	s_barrier
	ds_read_b128 v[150:153], v189 offset:49152
	ds_read_b128 v[154:157], v189 offset:50176
	ds_read_b128 v[168:171], v189 offset:51200
	ds_read_b128 v[172:175], v189 offset:52224
	ds_read_b128 v[176:179], v189 offset:53248
	ds_read_b128 v[180:183], v189 offset:54272
	ds_read_b128 v[190:193], v189 offset:55296
	ds_read_b128 v[212:215], v189 offset:56320
	global_load_lds_dwordx4 v158, s[46:47]
	s_mov_b32 m0, s93
	s_nop 0
	global_load_lds_dwordx4 v160, s[46:47]
	s_barrier
; #define PG8_STAGE(bufoff, gbase, voff) do { _Pragma("unroll") for (int _i = 0; _i < 2; ++_i) \
;     __builtin_amdgcn_global_load_lds((const unsigned*)((const char*)(gbase) + (voff)[_i]), (LAS unsigned*)(lds + (bufoff) + ldsw + _i * 8192), 16, 0, 0); } while (0)
; #define PG8_LDA(dst, b, h) do { _Pragma("unroll") for (int m = 0; m < 4; ++m) _Pragma("unroll") for (int k = 0; k < 2; ++k) dst[m][k] = *(const LAS bf16x8*)(lds + PG8_SA(b, h) + aoff + m * 2048 + k * 1024); } while (0)
; #define PG8_WAIT_V(n) asm volatile("s_waitcnt vmcnt(" #n ")" ::: "memory")
; #define PG8_WAIT_L(n) asm volatile("s_waitcnt lgkmcnt(" #n ")" ::: "memory")
; template <class Epi, bool SPLITA = false>
; __device__ __forceinline__ void gemm_phase(const int tid, LAS unsigned char* lds, const Gemm g, const Order& S, const Epi& E) {
;     ...
;     for (int t = 0; t < nt; t += 2) {
;       const bool last = (t == nt - 2);
;       if constexpr (SPLITA) { if (t == nt1) E.mid(acc, cur, wr, wc, fr, fq); }
;       const char* a1 = PG8_TA(t + 1);
;       const char* a2 = last ? nA : PG8_TA(t + 2); const char* b2 = last ? nB : cB + (size_t)(t + 2) * kstep;
;       const char* a3 = last ? nA + kstep : PG8_TA(t + 3); const char* b3 = b2 + kstep;
;       PG8_LDB(B0, 0, 0); PG8_SCHED; PG8_LDA(At, 0, 0); PG8_STAGE(PG8_SA(1, 1), a1 + hstepA, voffA);
;       PG8_WAIT_L(8); PG8_BAR; PG8_WAIT_L(0); PG8_MMA(0, 0, At, B0); PG8_BAR; PG8_SCHED;
;       PG8_LDB(B1, 0, 1); PG8_STAGE(PG8_SB(0, 0), b2, voffB);
;       PG8_BAR; PG8_WAIT_L(0); PG8_MMA(0, 1, At, B1); PG8_BAR;
;       PG8_LDA(At, 0, 1); PG8_STAGE(PG8_SA(0, 0), a2, voffA);
;       PG8_BAR; PG8_WAIT_L(0); PG8_MMA(1, 0, At, B0); PG8_BAR; PG8_SCHED;
;       PG8_STAGE(PG8_SB(0, 1), b2 + hstepB, voffB);
;       PG8_WAIT_V(6); PG8_BAR; PG8_MMA(1, 1, At, B1); PG8_BAR;
;       PG8_LDB(B0, 1, 0); PG8_SCHED; PG8_LDA(At, 1, 0); PG8_STAGE(PG8_SA(0, 1), a2 + hstepA, voffA);
;       PG8_WAIT_L(8); PG8_BAR; PG8_WAIT_L(0); PG8_MMA(0, 0, At, B0); PG8_BAR; PG8_SCHED;
;       PG8_LDB(B1, 1, 1); PG8_STAGE(PG8_SB(1, 0), b3, voffB);
;       PG8_BAR; PG8_WAIT_L(0); PG8_MMA(0, 1, At, B1); PG8_BAR;
;       PG8_LDA(At, 1, 1); PG8_STAGE(PG8_SA(1, 0), a3, voffA);
;       PG8_BAR; PG8_WAIT_L(0); PG8_MMA(1, 0, At, B0); PG8_BAR; PG8_SCHED;
;       PG8_STAGE(PG8_SB(1, 1), b3 + hstepB, voffB);
;       PG8_WAIT_V(6); PG8_BAR; PG8_MMA(1, 1, At, B1); PG8_BAR;
	s_waitcnt lgkmcnt(0)
	s_setprio 1
	s_waitcnt lgkmcnt(0)
	v_mfma_f32_16x16x32_bf16 v[62:65], v[134:137], v[150:153], v[62:65]
	v_mfma_f32_16x16x32_bf16 v[58:61], v[142:145], v[150:153], v[58:61]
	v_mfma_f32_16x16x32_bf16 v[46:49], v[134:137], v[168:171], v[46:49]
	v_mfma_f32_16x16x32_bf16 v[42:45], v[142:145], v[168:171], v[42:45]
	v_mfma_f32_16x16x32_bf16 v[30:33], v[134:137], v[176:179], v[30:33]
	v_mfma_f32_16x16x32_bf16 v[26:29], v[142:145], v[176:179], v[26:29]
	v_mfma_f32_16x16x32_bf16 v[14:17], v[134:137], v[190:193], v[14:17]
	v_mfma_f32_16x16x32_bf16 v[10:13], v[142:145], v[190:193], v[10:13]
	v_mfma_f32_16x16x32_bf16 v[62:65], v[138:141], v[154:157], v[62:65]
	v_mfma_f32_16x16x32_bf16 v[58:61], v[146:149], v[154:157], v[58:61]
	v_mfma_f32_16x16x32_bf16 v[46:49], v[138:141], v[172:175], v[46:49]
	v_mfma_f32_16x16x32_bf16 v[42:45], v[146:149], v[172:175], v[42:45]
	v_mfma_f32_16x16x32_bf16 v[30:33], v[138:141], v[180:183], v[30:33]
	v_mfma_f32_16x16x32_bf16 v[26:29], v[146:149], v[180:183], v[26:29]
	v_mfma_f32_16x16x32_bf16 v[14:17], v[138:141], v[212:215], v[14:17]
	v_mfma_f32_16x16x32_bf16 v[10:13], v[146:149], v[212:215], v[10:13]
	s_setprio 0
	s_barrier
	s_add_u32 s20, s44, 0x80080
	s_addc_u32 s21, s45, 0
	s_add_i32 s8, s9, s3
	s_mov_b32 m0, s8
	s_nop 0
	global_load_lds_dwordx4 v0, s[20:21]
	s_add_i32 m0, s8, 0x2000
	s_nop 0
	global_load_lds_dwordx4 v162, s[20:21]
	s_waitcnt vmcnt(6)
	s_barrier
	s_setprio 1
	v_mfma_f32_16x16x32_bf16 v[54:57], v[216:219], v[150:153], v[54:57]
	v_mfma_f32_16x16x32_bf16 v[50:53], v[224:227], v[150:153], v[50:53]
	v_mfma_f32_16x16x32_bf16 v[38:41], v[216:219], v[168:171], v[38:41]
	v_mfma_f32_16x16x32_bf16 v[34:37], v[224:227], v[168:171], v[34:37]
	v_mfma_f32_16x16x32_bf16 v[22:25], v[216:219], v[176:179], v[22:25]
	v_mfma_f32_16x16x32_bf16 v[18:21], v[224:227], v[176:179], v[18:21]
	v_mfma_f32_16x16x32_bf16 v[6:9], v[216:219], v[190:193], v[6:9]
	v_mfma_f32_16x16x32_bf16 v[2:5], v[224:227], v[190:193], v[2:5]
	v_mfma_f32_16x16x32_bf16 v[54:57], v[220:223], v[154:157], v[54:57]
	v_mfma_f32_16x16x32_bf16 v[50:53], v[228:231], v[154:157], v[50:53]
	v_mfma_f32_16x16x32_bf16 v[38:41], v[220:223], v[172:175], v[38:41]
	v_mfma_f32_16x16x32_bf16 v[34:37], v[228:231], v[172:175], v[34:37]
	v_mfma_f32_16x16x32_bf16 v[22:25], v[220:223], v[180:183], v[22:25]
	v_mfma_f32_16x16x32_bf16 v[18:21], v[228:231], v[180:183], v[18:21]
	v_mfma_f32_16x16x32_bf16 v[6:9], v[220:223], v[212:215], v[6:9]
	v_mfma_f32_16x16x32_bf16 v[2:5], v[228:231], v[212:215], v[2:5]
	s_setprio 0
	s_add_i32 s29, s29, 2
	s_add_u32 s42, s42, 0x100
	s_addc_u32 s43, s43, 0
	s_cmp_gt_u32 s29, 29
	s_barrier
	s_cbranch_scc0 .LBB0_192
; __device__ __forceinline__ float bflo(unsigned w) { return __uint_as_float(w << 16); }
; __device__ __forceinline__ float bfhi(unsigned w) { return __uint_as_float(w & 0xffff0000u); }
; __device__ __forceinline__ float lane_read(float v, int src) { return __int_as_float(__builtin_amdgcn_ds_bpermute(src << 2, __float_as_int(v))); }
; __device__ __forceinline__ u32x4 pack8(const f32x4 v0, const f32x4 v1) { u32x4 w; w.x = cvtpk(v0[0], v0[1]); w.y = cvtpk(v0[2], v0[3]); w.z = cvtpk(v1[0], v1[1]); w.w = cvtpk(v1[2], v1[3]); return w; }
;   __device__ __forceinline__ void operator()(const Acc& acc, const Unit& u, int wr, int wc, int fr_, int fq_) const {
;     int fr = fr_, fq = fq_; asm volatile("" : "+v"(fr), "+v"(fq));
;     const int lane = fq * 16 + fr;
;     const int row0 = u.pm * BM + wr * 64 + fr, col0 = u.pn * BM + wc * 32 + 8 * fq;
; #pragma unroll
;     for (int ai = 0; ai < 2; ++ai) {
;       u32x4 hv[4][2];
; #pragma unroll
;       for (int m = 0; m < 4; ++m)
; #pragma unroll
;         for (int bj = 0; bj < 2; ++bj) hv[m][bj] = *(const u32x4*)(rin + (size_t)(row0 + ai * HALF + m * 16) * DM + col0 + bj * HALF);
; #pragma unroll
;       for (int m = 0; m < 4; ++m) { const size_t ro = (size_t)(row0 + ai * HALF + m * 16) * DM + col0; float ss = 0.f;
; #pragma unroll
;         for (int bj = 0; bj < 2; ++bj) { const u32x4 h = hv[m][bj];
;           f32x4 v0 = acc[ai][bj][m][0], v1 = acc[ai][bj][m][1];
;           v0[0] += bflo(h.x); v0[1] += bfhi(h.x); v0[2] += bflo(h.y); v0[3] += bfhi(h.y);
;           v1[0] += bflo(h.z); v1[1] += bfhi(h.z); v1[2] += bflo(h.w); v1[3] += bfhi(h.w);
;           if (FINAL) { *(f32x4*)(outf + ro + bj * HALF) = v0; *(f32x4*)(outf + ro + bj * HALF + 4) = v1; }
;           else { ss += v0[0] * v0[0] + v0[1] * v0[1] + v0[2] * v0[2] + v0[3] * v0[3] + v1[0] * v1[0] + v1[1] * v1[1] + v1[2] * v1[2] + v1[3] * v1[3];
;             *(u32x4*)(outb + ro + bj * HALF) = pack8(v0, v1); } }
;         if (!FINAL) { ss += lane_read(ss, lane ^ 16); ss += lane_read(ss, lane ^ 32);
;           if (fq == 0) rss[(size_t)(row0 + ai * HALF + m * 16) * 32 + u.pn * 4 + wc] = ss; } }
;     }
	s_lshl_b32 s4, s22, 8
	v_mov_b32_e32 v130, v187
	v_mov_b32_e32 v131, v186
	s_add_i32 s4, s4, s55
	s_nop 0
	v_add_u32_e32 v170, s4, v130
	s_lshl_b32 s4, s18, 8
	s_or_b32 s4, s4, s90
	v_lshl_add_u32 v168, v131, 3, s4
	v_ashrrev_i32_e32 v169, 31, v168
	v_lshlrev_b32_e32 v130, 2, v130
	v_lshlrev_b64 v[192:193], 1, v[168:169]
	v_ashrrev_i32_e32 v171, 31, v170
	v_lshl_add_u32 v130, v131, 6, v130
	v_lshl_add_u64 v[172:173], s[86:87], 0, v[192:193]
	v_lshlrev_b64 v[198:199], 12, v[170:171]
	v_xor_b32_e32 v191, 64, v130
	v_xor_b32_e32 v190, 0x80, v130
	v_cmp_eq_u32_e32 vcc, 0, v131
	v_lshl_add_u64 v[130:131], v[172:173], 0, v[198:199]
	global_load_dwordx4 v[212:215], v[130:131], off
	global_load_dwordx4 v[154:157], v[130:131], off offset:256
	v_add_u32_e32 v182, 16, v170
	v_ashrrev_i32_e32 v183, 31, v182
	v_add_u32_e32 v178, 32, v170
	v_lshlrev_b64 v[184:185], 12, v[182:183]
	v_ashrrev_i32_e32 v179, 31, v178
	v_add_u32_e32 v174, 48, v170
	v_lshl_add_u64 v[130:131], v[172:173], 0, v[184:185]
	v_lshlrev_b64 v[180:181], 12, v[178:179]
	v_ashrrev_i32_e32 v175, 31, v174
	global_load_dwordx4 v[150:153], v[130:131], off
	global_load_dwordx4 v[146:149], v[130:131], off offset:256
	v_lshl_add_u64 v[130:131], v[172:173], 0, v[180:181]
	v_lshlrev_b64 v[176:177], 12, v[174:175]
	global_load_dwordx4 v[142:145], v[130:131], off
	global_load_dwordx4 v[138:141], v[130:131], off offset:256
	v_lshl_add_u64 v[130:131], v[172:173], 0, v[176:177]
	global_load_dwordx4 v[134:137], v[130:131], off
	s_nop 0
	global_load_dwordx4 v[130:133], v[130:131], off offset:256
	s_lshl_b32 s18, s18, 2
	s_ashr_i32 s19, s18, 31
	s_waitcnt vmcnt(0)
	v_lshlrev_b32_e32 v200, 16, v212
	v_and_b32_e32 v201, 0xffff0000, v212
	v_pk_add_f32 v[126:127], v[126:127], v[200:201]
	v_lshlrev_b32_e32 v200, 16, v213
	v_and_b32_e32 v201, 0xffff0000, v213
	v_pk_add_f32 v[128:129], v[128:129], v[200:201]
	v_lshlrev_b32_e32 v200, 16, v214
	v_and_b32_e32 v201, 0xffff0000, v214
	v_pk_add_f32 v[200:201], v[122:123], v[200:201]
	v_lshlrev_b32_e32 v122, 16, v215
	v_and_b32_e32 v123, 0xffff0000, v215
	v_pk_add_f32 v[202:203], v[124:125], v[122:123]
	v_pk_mul_f32 v[204:205], v[126:127], v[126:127]
	v_cvt_pk_bf16_f32 v122, v126, v127
	v_lshl_add_u64 v[126:127], s[0:1], 0, v[198:199]
	v_cvt_pk_bf16_f32 v123, v128, v129
	v_cvt_pk_bf16_f32 v124, v200, v201
	v_cvt_pk_bf16_f32 v125, v202, v203
	v_lshl_add_u64 v[126:127], v[126:127], 0, v[192:193]
	global_store_dwordx4 v[126:127], v[122:125], off
	v_pk_mul_f32 v[206:207], v[128:129], v[128:129]
	v_pk_mul_f32 v[212:213], v[200:201], v[200:201]
	v_lshlrev_b32_e32 v122, 16, v154
	v_and_b32_e32 v123, 0xffff0000, v154
	v_pk_add_f32 v[118:119], v[118:119], v[122:123]
	v_lshlrev_b32_e32 v122, 16, v155
	v_and_b32_e32 v123, 0xffff0000, v155
	v_pk_add_f32 v[120:121], v[120:121], v[122:123]
	v_lshlrev_b32_e32 v122, 16, v156
	v_and_b32_e32 v123, 0xffff0000, v156
	v_pk_add_f32 v[122:123], v[114:115], v[122:123]
	v_lshlrev_b32_e32 v114, 16, v157
	v_and_b32_e32 v115, 0xffff0000, v157
	v_pk_add_f32 v[124:125], v[116:117], v[114:115]
	v_pk_mul_f32 v[114:115], v[118:119], v[118:119]
	v_pk_mul_f32 v[116:117], v[120:121], v[120:121]
	v_add_f32_e32 v114, v114, v115
	v_add_f32_e32 v115, v204, v205
	v_add_f32_e32 v114, v116, v114
	v_add_f32_e32 v115, v206, v115
	v_pk_mul_f32 v[128:129], v[122:123], v[122:123]
	v_add_f32_e32 v114, v117, v114
	v_add_f32_e32 v115, v207, v115
	v_add_f32_e32 v114, v128, v114
	v_add_f32_e32 v115, v212, v115
	v_pk_mul_f32 v[214:215], v[202:203], v[202:203]
	v_pk_mul_f32 v[154:155], v[124:125], v[124:125]
	v_add_f32_e32 v114, v129, v114
	v_add_f32_e32 v115, v213, v115
	v_add_f32_e32 v114, v154, v114
	v_add_f32_e32 v115, v214, v115
	v_add_f32_e32 v114, v155, v114
	v_add_f32_e32 v115, v215, v115
	v_add_f32_e32 v128, v115, v114
	v_cvt_pk_bf16_f32 v114, v118, v119
	v_cvt_pk_bf16_f32 v115, v120, v121
	v_cvt_pk_bf16_f32 v116, v122, v123
	v_cvt_pk_bf16_f32 v117, v124, v125
	global_store_dwordx4 v[126:127], v[114:117], off offset:256
	ds_bpermute_b32 v114, v191, v128
	s_waitcnt lgkmcnt(0)
	v_add_f32_e32 v114, v128, v114
	ds_bpermute_b32 v115, v190, v114
	s_and_saveexec_b64 s[6:7], vcc
	s_cbranch_execz .LBB0_195
	v_readlane_b32 s8, v255, 1
	v_lshlrev_b64 v[116:117], 7, v[170:171]
	v_readlane_b32 s9, v255, 2
	s_lshl_b32 s4, s54, 2
	s_waitcnt lgkmcnt(0)
	v_add_f32_e32 v114, v114, v115
	v_lshl_add_u64 v[116:117], s[8:9], 0, v[116:117]
	v_lshl_add_u64 v[116:117], s[18:19], 2, v[116:117]
	v_lshl_add_u64 v[116:117], v[116:117], 0, s[4:5]
	global_store_dword v[116:117], v114, off

; #define PG8_STAGE(bufoff, gbase, voff) do { _Pragma("unroll") for (int _i = 0; _i < 2; ++_i) \
;     __builtin_amdgcn_global_load_lds((const unsigned*)((const char*)(gbase) + (voff)[_i]), (LAS unsigned*)(lds + (bufoff) + ldsw + _i * 8192), 16, 0, 0); } while (0)
; #define PG8_WAIT_V(n) asm volatile("s_waitcnt vmcnt(" #n ")" ::: "memory")
; #define PG8_BAR __builtin_amdgcn_s_barrier()
; template <class Epi, bool SPLITA = false>
; __device__ __forceinline__ void gemm_phase(const int tid, LAS unsigned char* lds, const Gemm g, const Order& S, const Epi& E) {
;     ...
;   const int aoff = lds_byte(wr * 64 + fr, fq * 8), boff = lds_byte(wc * 32 + fr, fq * 8);
;     ...
;   Unit cur, nxt; int ui = 0;
;   if (!S.next(0, cur)) return;
;   Acc acc;
; #pragma unroll
;   for (int a = 0; a < 2; ++a)
; #pragma unroll
;     for (int b = 0; b < 2; ++b)
; #pragma unroll
;       for (int m = 0; m < 4; ++m)
; #pragma unroll
;         for (int n = 0; n < 2; ++n) acc[a][b][m][n] = (f32x4){0.f, 0.f, 0.f, 0.f};
;   bf16x8 At[4][2], B0[2][2], B1[2][2];
;   const char* cA = (const char*)g.A + (size_t)cur.pm * tstepA + (size_t)cur.pn * apn; const char* cB = (const char*)g.Bt + (size_t)cur.pn * tstepB;
;   const char* cA2 = SPLITA ? (const char*)g.A2 + (size_t)cur.pm * tstepA : cA; const int nt1 = SPLITA ? g.nt1 : nt;
;     ...
;   PG8_STAGE(PG8_SB(0, 0), cB, voffB); PG8_STAGE(PG8_SA(0, 0), cA, voffA); PG8_STAGE(PG8_SB(0, 1), cB + hstepB, voffB); PG8_STAGE(PG8_SA(0, 1), cA + hstepA, voffA);
;   if (wr == 1) PG8_BAR;
;   PG8_WAIT_V(4); PG8_BAR;
;   PG8_STAGE(PG8_SB(1, 0), cB + kstep, voffB); PG8_STAGE(PG8_SA(1, 0), cA + kstep, voffA); PG8_STAGE(PG8_SB(1, 1), cB + hstepB + kstep, voffB);
;   PG8_WAIT_V(6); PG8_BAR;
.LBB0_228:
	v_lshl_add_u64 v[2:3], s[40:41], 0, v[0:1]
	v_mov_b32_e32 v213, v1
	v_bfe_u32 v195, v210, 4, 2
	s_lshl_b32 s6, s1, 6
	s_lshl_b32 s0, s0, 5
	v_mov_b32_e32 v217, v1
	v_and_b32_e32 v196, 15, v210
	v_writelane_b32 v255, s6, 36
	v_lshlrev_b32_e32 v10, 4, v195
	v_lshlrev_b32_e32 v11, 2, v210
	s_and_b32 s0, s0, 0x60
	s_add_i32 m0, s51, 0x18000
	v_lshl_add_u64 v[2:3], v[2:3], 0, s[96:97]
	v_mov_b32_e32 v215, v1
	s_and_b32 s3, 0xffff, s3
	v_lshl_or_b32 v10, v196, 6, v10
	s_lshl_b32 s1, s1, 13
	v_and_b32_e32 v11, 32, v11
	v_writelane_b32 v255, s0, 38
	s_lshl_b32 s0, s0, 7
	s_waitcnt vmcnt(4)
	s_barrier
	global_load_lds_dwordx4 v[2:3], off
	s_add_i32 m0, s51, 0x19f80
	s_add_i32 s47, s51, 0x8000
	s_add_i32 s38, s51, 0xa000
	v_bitop3_b32 v209, s0, v10, v11 bitop3:0xf6
	v_add_u32_e32 v209, 0x10000, v209
	global_load_lds_dwordx4 v212, s[40:41] offset:128
	s_add_i32 m0, s47, 0xffffff80
	s_add_u32 s0, s40, 0x80080
	v_bitop3_b32 v12, v10, s1, v11 bitop3:0xde
	global_load_lds_dwordx4 v216, s[14:15] offset:128
	s_add_i32 m0, s38, 0xffffff80
	s_addc_u32 s1, s41, 0
	global_load_lds_dwordx4 v214, s[14:15] offset:128
	s_add_i32 m0, s51, 0x1c000
	s_nop 0
	global_load_lds_dwordx4 v0, s[0:1]
	v_lshl_add_u64 v[2:3], s[0:1], 0, v[212:213]
	s_add_i32 m0, s51, 0x1e000
	s_ashr_i32 s0, s92, 31
	global_load_lds_dwordx4 v[2:3], off
	s_waitcnt vmcnt(6)
	v_writelane_b32 v255, s0, 40
	s_mov_b32 s39, 0
	v_add_u32_e32 v211, 0, v12
	s_mov_b64 s[0:1], s[4:5]
	s_barrier
	s_branch .LBB0_230

; #define PG8_STAGE(bufoff, gbase, voff) do { _Pragma("unroll") for (int _i = 0; _i < 2; ++_i) \
;     __builtin_amdgcn_global_load_lds((const unsigned*)((const char*)(gbase) + (voff)[_i]), (LAS unsigned*)(lds + (bufoff) + ldsw + _i * 8192), 16, 0, 0); } while (0)
; #define PG8_BAR __builtin_amdgcn_s_barrier()
; template <class Epi, bool SPLITA = false>
; __device__ __forceinline__ void gemm_phase(const int tid, LAS unsigned char* lds, const Gemm g, const Order& S, const Epi& E) {
;     ...
;   PG8_STAGE(PG8_SB(0, 0), cB, voffB); PG8_STAGE(PG8_SA(0, 0), cA, voffA); PG8_STAGE(PG8_SB(0, 1), cB + hstepB, voffB); PG8_STAGE(PG8_SA(0, 1), cA + hstepA, voffA);
;   if (wr == 1) PG8_BAR;
;   PG8_WAIT_V(4); PG8_BAR;
;   PG8_STAGE(PG8_SB(1, 0), cB + kstep, voffB); PG8_STAGE(PG8_SA(1, 0), cA + kstep, voffA); PG8_STAGE(PG8_SB(1, 1), cB + hstepB + kstep, voffB);
;   PG8_WAIT_V(6); PG8_BAR;
;   for (;;) {
;     const bool has_next = S.next(ui + 1, nxt);
;     const char* nA = has_next ? (const char*)g.A + (size_t)nxt.pm * tstepA + (size_t)nxt.pn * apn : cA; const char* nA2 = (SPLITA && has_next) ? (const char*)g.A2 + (size_t)nxt.pm * tstepA : cA2; const char* nB = has_next ? (const char*)g.Bt + (size_t)nxt.pn * tstepB : cB;
;     for (int t = 0; t < nt; t += 2) {
;       const bool last = (t == nt - 2);
;       if constexpr (SPLITA) { if (t == nt1) E.mid(acc, cur, wr, wc, fr, fq); }
;       const char* a1 = PG8_TA(t + 1);
;       const char* a2 = last ? nA : PG8_TA(t + 2); const char* b2 = last ? nB : cB + (size_t)(t + 2) * kstep;
;       const char* a3 = last ? nA + kstep : PG8_TA(t + 3); const char* b3 = b2 + kstep;
;       PG8_LDB(B0, 0, 0); PG8_SCHED; PG8_LDA(At, 0, 0); PG8_STAGE(PG8_SA(1, 1), a1 + hstepA, voffA);
;       PG8_WAIT_L(8); PG8_BAR; PG8_WAIT_L(0); PG8_MMA(0, 0, At, B0); PG8_BAR; PG8_SCHED;
;       PG8_LDB(B1, 0, 1); PG8_STAGE(PG8_SB(0, 0), b2, voffB);
;       PG8_BAR; PG8_WAIT_L(0); PG8_MMA(0, 1, At, B1); PG8_BAR;
;       PG8_LDA(At, 0, 1); PG8_STAGE(PG8_SA(0, 0), a2, voffA);
;       PG8_BAR; PG8_WAIT_L(0); PG8_MMA(1, 0, At, B0); PG8_BAR; PG8_SCHED;
;       PG8_STAGE(PG8_SB(0, 1), b2 + hstepB, voffB);
;       PG8_WAIT_V(6); PG8_BAR; PG8_MMA(1, 1, At, B1); PG8_BAR;
;       PG8_LDB(B0, 1, 0); PG8_SCHED; PG8_LDA(At, 1, 0); PG8_STAGE(PG8_SA(0, 1), a2 + hstepA, voffA);
;       PG8_WAIT_L(8); PG8_BAR; PG8_WAIT_L(0); PG8_MMA(0, 0, At, B0); PG8_BAR; PG8_SCHED;
.LBB0_237:
	s_add_u32 s3, s52, s40
	s_addc_u32 s4, s53, s41
	s_and_b64 s[22:23], exec, s[48:49]
	s_cselect_b32 s49, s30, s4
	s_cselect_b32 s48, s31, s3
	s_cmp_lt_u32 s2, 16
	s_cselect_b64 s[22:23], -1, 0
	s_and_b64 s[28:29], s[22:23], exec
	s_cselect_b32 s3, 0, -16
	s_add_i32 s3, s3, s2
	s_add_i32 s4, s3, 1
	s_and_b64 s[22:23], s[22:23], exec
	s_cselect_b32 s3, s15, s55
	s_cselect_b32 s20, s14, s54
	s_lshl_b64 s[22:23], s[4:5], 7
	s_add_u32 s4, s20, s22
	s_addc_u32 s20, s3, s23
	s_add_i32 s21, 0, 0x10000
	ds_read_b128 v[130:133], v209
	ds_read_b128 v[134:137], v209 offset:1024
	ds_read_b128 v[138:141], v209 offset:2048
	ds_read_b128 v[142:145], v209 offset:3072
	s_add_i32 s3, s2, 2
	s_add_u32 s22, s4, 0x40000
	s_addc_u32 s23, s20, 0
	s_add_i32 m0, s51, 0xc000
	ds_read_b128 v[146:149], v211
	ds_read_b128 v[150:153], v211 offset:1024
	ds_read_b128 v[154:157], v211 offset:2048
	ds_read_b128 v[158:161], v211 offset:3072
	ds_read_b128 v[162:165], v211 offset:4096
	ds_read_b128 v[166:169], v211 offset:5120
	ds_read_b128 v[170:173], v211 offset:6144
	ds_read_b128 v[174:177], v211 offset:7168
	global_load_lds_dwordx4 v216, s[22:23]
	s_add_i32 m0, s51, 0xe000
	s_nop 0
	global_load_lds_dwordx4 v214, s[22:23]
	s_waitcnt lgkmcnt(8)
	s_barrier
	s_waitcnt lgkmcnt(0)
	s_setprio 1
	s_waitcnt lgkmcnt(0)
	v_mfma_f32_16x16x32_bf16 v[126:129], v[130:133], v[146:149], v[126:129]
	v_mfma_f32_16x16x32_bf16 v[122:125], v[138:141], v[146:149], v[122:125]
	v_mfma_f32_16x16x32_bf16 v[110:113], v[130:133], v[154:157], v[110:113]
	v_mfma_f32_16x16x32_bf16 v[106:109], v[138:141], v[154:157], v[106:109]
	v_mfma_f32_16x16x32_bf16 v[94:97], v[130:133], v[162:165], v[94:97]
	v_mfma_f32_16x16x32_bf16 v[90:93], v[138:141], v[162:165], v[90:93]
	v_mfma_f32_16x16x32_bf16 v[78:81], v[130:133], v[170:173], v[78:81]
	v_mfma_f32_16x16x32_bf16 v[74:77], v[138:141], v[170:173], v[74:77]
	v_mfma_f32_16x16x32_bf16 v[126:129], v[134:137], v[150:153], v[126:129]
	v_mfma_f32_16x16x32_bf16 v[122:125], v[142:145], v[150:153], v[122:125]
	v_mfma_f32_16x16x32_bf16 v[110:113], v[134:137], v[158:161], v[110:113]
	v_mfma_f32_16x16x32_bf16 v[106:109], v[142:145], v[158:161], v[106:109]
	v_mfma_f32_16x16x32_bf16 v[94:97], v[134:137], v[166:169], v[94:97]
	v_mfma_f32_16x16x32_bf16 v[90:93], v[142:145], v[166:169], v[90:93]
	v_mfma_f32_16x16x32_bf16 v[78:81], v[134:137], v[174:177], v[78:81]
	v_mfma_f32_16x16x32_bf16 v[74:77], v[142:145], v[174:177], v[74:77]
	s_setprio 0
	s_barrier
	s_add_i32 s4, 0, 0x14000
	s_add_i32 s20, s21, s93
	s_mov_b32 m0, s20
	ds_read_b128 v[178:181], v209 offset:16384
	ds_read_b128 v[182:185], v209 offset:17408
	ds_read_b128 v[186:189], v209 offset:18432
	ds_read_b128 v[190:193], v209 offset:19456
	global_load_lds_dwordx4 v0, s[48:49]
	s_add_i32 m0, s20, 0x2000
	s_nop 0
	global_load_lds_dwordx4 v212, s[48:49]
	s_barrier
	s_waitcnt lgkmcnt(0)
	s_setprio 1
	s_waitcnt lgkmcnt(0)
	v_mfma_f32_16x16x32_bf16 v[118:121], v[178:181], v[146:149], v[118:121]
	v_mfma_f32_16x16x32_bf16 v[114:117], v[186:189], v[146:149], v[114:117]
	v_mfma_f32_16x16x32_bf16 v[102:105], v[178:181], v[154:157], v[102:105]
	v_mfma_f32_16x16x32_bf16 v[98:101], v[186:189], v[154:157], v[98:101]
	v_mfma_f32_16x16x32_bf16 v[86:89], v[178:181], v[162:165], v[86:89]
	v_mfma_f32_16x16x32_bf16 v[82:85], v[186:189], v[162:165], v[82:85]
	v_mfma_f32_16x16x32_bf16 v[70:73], v[178:181], v[170:173], v[70:73]
	v_mfma_f32_16x16x32_bf16 v[66:69], v[186:189], v[170:173], v[66:69]
	v_mfma_f32_16x16x32_bf16 v[118:121], v[182:185], v[150:153], v[118:121]
	v_mfma_f32_16x16x32_bf16 v[114:117], v[190:193], v[150:153], v[114:117]
	v_mfma_f32_16x16x32_bf16 v[102:105], v[182:185], v[158:161], v[102:105]
	v_mfma_f32_16x16x32_bf16 v[98:101], v[190:193], v[158:161], v[98:101]
	v_mfma_f32_16x16x32_bf16 v[86:89], v[182:185], v[166:169], v[86:89]
	v_mfma_f32_16x16x32_bf16 v[82:85], v[190:193], v[166:169], v[82:85]
	v_mfma_f32_16x16x32_bf16 v[70:73], v[182:185], v[174:177], v[70:73]
	v_mfma_f32_16x16x32_bf16 v[66:69], v[190:193], v[174:177], v[66:69]
	s_setprio 0
	s_mov_b32 m0, s51
	s_barrier
	ds_read_b128 v[146:149], v211 offset:16384
	ds_read_b128 v[150:153], v211 offset:17408
	ds_read_b128 v[154:157], v211 offset:18432
	ds_read_b128 v[158:161], v211 offset:19456
	ds_read_b128 v[162:165], v211 offset:20480
	ds_read_b128 v[166:169], v211 offset:21504
	ds_read_b128 v[170:173], v211 offset:22528
	ds_read_b128 v[174:177], v211 offset:23552
	global_load_lds_dwordx4 v216, s[90:91]
	s_mov_b32 m0, s44
	s_nop 0
	global_load_lds_dwordx4 v214, s[90:91]
	s_barrier
	s_waitcnt lgkmcnt(0)
	s_setprio 1
	s_waitcnt lgkmcnt(0)
	v_mfma_f32_16x16x32_bf16 v[62:65], v[130:133], v[146:149], v[62:65]
	v_mfma_f32_16x16x32_bf16 v[58:61], v[138:141], v[146:149], v[58:61]
	v_mfma_f32_16x16x32_bf16 v[46:49], v[130:133], v[154:157], v[46:49]
	v_mfma_f32_16x16x32_bf16 v[42:45], v[138:141], v[154:157], v[42:45]
	v_mfma_f32_16x16x32_bf16 v[30:33], v[130:133], v[162:165], v[30:33]
	v_mfma_f32_16x16x32_bf16 v[26:29], v[138:141], v[162:165], v[26:29]
	v_mfma_f32_16x16x32_bf16 v[14:17], v[130:133], v[170:173], v[14:17]
	v_mfma_f32_16x16x32_bf16 v[10:13], v[138:141], v[170:173], v[10:13]
	v_mfma_f32_16x16x32_bf16 v[62:65], v[134:137], v[150:153], v[62:65]
	v_mfma_f32_16x16x32_bf16 v[58:61], v[142:145], v[150:153], v[58:61]
	v_mfma_f32_16x16x32_bf16 v[46:49], v[134:137], v[158:161], v[46:49]
	v_mfma_f32_16x16x32_bf16 v[42:45], v[142:145], v[158:161], v[42:45]
	v_mfma_f32_16x16x32_bf16 v[30:33], v[134:137], v[166:169], v[30:33]
	v_mfma_f32_16x16x32_bf16 v[26:29], v[142:145], v[166:169], v[26:29]
	v_mfma_f32_16x16x32_bf16 v[14:17], v[134:137], v[174:177], v[14:17]
	v_mfma_f32_16x16x32_bf16 v[10:13], v[142:145], v[174:177], v[10:13]
	s_setprio 0
	s_barrier
; #define PG8_STAGE(bufoff, gbase, voff) do { _Pragma("unroll") for (int _i = 0; _i < 2; ++_i) \
;     __builtin_amdgcn_global_load_lds((const unsigned*)((const char*)(gbase) + (voff)[_i]), (LAS unsigned*)(lds + (bufoff) + ldsw + _i * 8192), 16, 0, 0); } while (0)
; #define PG8_LDA(dst, b, h) do { _Pragma("unroll") for (int m = 0; m < 4; ++m) _Pragma("unroll") for (int k = 0; k < 2; ++k) dst[m][k] = *(const LAS bf16x8*)(lds + PG8_SA(b, h) + aoff + m * 2048 + k * 1024); } while (0)
; #define PG8_LDB(dst, b, h) do { _Pragma("unroll") for (int n = 0; n < 2; ++n) _Pragma("unroll") for (int k = 0; k < 2; ++k) dst[n][k] = *(const LAS bf16x8*)(lds + PG8_SB(b, h) + boff + n * 2048 + k * 1024); } while (0)
; #define PG8_MMA(ai, bj, At, Bt) do { __builtin_amdgcn_s_setprio(1); _Pragma("unroll") for (int m = 0; m < 4; ++m) _Pragma("unroll") for (int n = 0; n < 2; ++n) _Pragma("unroll") for (int k = 0; k < 2; ++k) \
;     acc[ai][bj][m][n] = __builtin_amdgcn_mfma_f32_16x16x32_bf16(Bt[n][k], At[m][k], acc[ai][bj][m][n], 0, 0, 0); __builtin_amdgcn_s_setprio(0); } while (0)
; #define PG8_WAIT_V(n) asm volatile("s_waitcnt vmcnt(" #n ")" ::: "memory")
; #define PG8_WAIT_L(n) asm volatile("s_waitcnt lgkmcnt(" #n ")" ::: "memory")
; #define PG8_BAR __builtin_amdgcn_s_barrier()
; #define PG8_SCHED __builtin_amdgcn_sched_barrier(0)
; template <class Epi, bool SPLITA = false>
; __device__ __forceinline__ void gemm_phase(const int tid, LAS unsigned char* lds, const Gemm g, const Order& S, const Epi& E) {
;     ...
;       PG8_LDA(At, 0, 1); PG8_STAGE(PG8_SA(0, 0), a2, voffA);
;       PG8_BAR; PG8_WAIT_L(0); PG8_MMA(1, 0, At, B0); PG8_BAR; PG8_SCHED;
;       PG8_STAGE(PG8_SB(0, 1), b2 + hstepB, voffB);
;       PG8_WAIT_V(6); PG8_BAR; PG8_MMA(1, 1, At, B1); PG8_BAR;
;       PG8_LDB(B0, 1, 0); PG8_SCHED; PG8_LDA(At, 1, 0); PG8_STAGE(PG8_SA(0, 1), a2 + hstepA, voffA);
;       PG8_WAIT_L(8); PG8_BAR; PG8_WAIT_L(0); PG8_MMA(0, 0, At, B0); PG8_BAR; PG8_SCHED;
;       PG8_LDB(B1, 1, 1); PG8_STAGE(PG8_SB(1, 0), b3, voffB);
;       PG8_BAR; PG8_WAIT_L(0); PG8_MMA(0, 1, At, B1); PG8_BAR;
;       PG8_LDA(At, 1, 1); PG8_STAGE(PG8_SA(1, 0), a3, voffA);
;       PG8_BAR; PG8_WAIT_L(0); PG8_MMA(1, 0, At, B0); PG8_BAR; PG8_SCHED;
	s_add_u32 s22, s48, 0x80000
	s_addc_u32 s23, s49, 0
	s_add_i32 s4, s4, s93
	s_mov_b32 m0, s4
	s_nop 0
	global_load_lds_dwordx4 v0, s[22:23]
	s_add_i32 m0, s4, 0x2000
	s_nop 0
	global_load_lds_dwordx4 v212, s[22:23]
	s_waitcnt vmcnt(6)
	s_barrier
	s_setprio 1
	v_mfma_f32_16x16x32_bf16 v[54:57], v[178:181], v[146:149], v[54:57]
	v_mfma_f32_16x16x32_bf16 v[50:53], v[186:189], v[146:149], v[50:53]
	v_mfma_f32_16x16x32_bf16 v[38:41], v[178:181], v[154:157], v[38:41]
	v_mfma_f32_16x16x32_bf16 v[34:37], v[186:189], v[154:157], v[34:37]
	v_mfma_f32_16x16x32_bf16 v[22:25], v[178:181], v[162:165], v[22:25]
	v_mfma_f32_16x16x32_bf16 v[18:21], v[186:189], v[162:165], v[18:21]
	v_mfma_f32_16x16x32_bf16 v[6:9], v[178:181], v[170:173], v[6:9]
	v_mfma_f32_16x16x32_bf16 v[2:5], v[186:189], v[170:173], v[2:5]
	v_mfma_f32_16x16x32_bf16 v[54:57], v[182:185], v[150:153], v[54:57]
	v_mfma_f32_16x16x32_bf16 v[50:53], v[190:193], v[150:153], v[50:53]
	v_mfma_f32_16x16x32_bf16 v[38:41], v[182:185], v[158:161], v[38:41]
	v_mfma_f32_16x16x32_bf16 v[34:37], v[190:193], v[158:161], v[34:37]
	v_mfma_f32_16x16x32_bf16 v[22:25], v[182:185], v[166:169], v[22:25]
	v_mfma_f32_16x16x32_bf16 v[18:21], v[190:193], v[166:169], v[18:21]
	v_mfma_f32_16x16x32_bf16 v[6:9], v[182:185], v[174:177], v[6:9]
	v_mfma_f32_16x16x32_bf16 v[2:5], v[190:193], v[174:177], v[2:5]
	s_setprio 0
	s_add_i32 s4, 0, 0x18000
	s_barrier
	ds_read_b128 v[130:133], v209 offset:32768
	ds_read_b128 v[134:137], v209 offset:33792
	ds_read_b128 v[138:141], v209 offset:34816
	ds_read_b128 v[142:145], v209 offset:35840
	s_add_u32 s22, s90, 0x40000
	s_addc_u32 s23, s91, 0
	s_mov_b32 m0, s45
	ds_read_b128 v[146:149], v211 offset:32768
	ds_read_b128 v[150:153], v211 offset:33792
	ds_read_b128 v[154:157], v211 offset:34816
	ds_read_b128 v[158:161], v211 offset:35840
	ds_read_b128 v[162:165], v211 offset:36864
	ds_read_b128 v[166:169], v211 offset:37888
	ds_read_b128 v[170:173], v211 offset:38912
	ds_read_b128 v[174:177], v211 offset:39936
	global_load_lds_dwordx4 v216, s[22:23]
	s_mov_b32 m0, s46
	s_nop 0
	global_load_lds_dwordx4 v214, s[22:23]
	s_waitcnt lgkmcnt(8)
	s_barrier
	s_waitcnt lgkmcnt(0)
	s_setprio 1
	s_waitcnt lgkmcnt(0)
	v_mfma_f32_16x16x32_bf16 v[126:129], v[130:133], v[146:149], v[126:129]
	v_mfma_f32_16x16x32_bf16 v[122:125], v[138:141], v[146:149], v[122:125]
	v_mfma_f32_16x16x32_bf16 v[110:113], v[130:133], v[154:157], v[110:113]
	v_mfma_f32_16x16x32_bf16 v[106:109], v[138:141], v[154:157], v[106:109]
	v_mfma_f32_16x16x32_bf16 v[94:97], v[130:133], v[162:165], v[94:97]
	v_mfma_f32_16x16x32_bf16 v[90:93], v[138:141], v[162:165], v[90:93]
	v_mfma_f32_16x16x32_bf16 v[78:81], v[130:133], v[170:173], v[78:81]
	v_mfma_f32_16x16x32_bf16 v[74:77], v[138:141], v[170:173], v[74:77]
	v_mfma_f32_16x16x32_bf16 v[126:129], v[134:137], v[150:153], v[126:129]
	v_mfma_f32_16x16x32_bf16 v[122:125], v[142:145], v[150:153], v[122:125]
	v_mfma_f32_16x16x32_bf16 v[110:113], v[134:137], v[158:161], v[110:113]
	v_mfma_f32_16x16x32_bf16 v[106:109], v[142:145], v[158:161], v[106:109]
	v_mfma_f32_16x16x32_bf16 v[94:97], v[134:137], v[166:169], v[94:97]
	v_mfma_f32_16x16x32_bf16 v[90:93], v[142:145], v[166:169], v[90:93]
	v_mfma_f32_16x16x32_bf16 v[78:81], v[134:137], v[174:177], v[78:81]
	v_mfma_f32_16x16x32_bf16 v[74:77], v[142:145], v[174:177], v[74:77]
	s_setprio 0
	s_barrier
	s_add_i32 s20, 0, 0x1c000
	s_add_i32 s4, s4, s93
	s_add_i32 m0, s4, 0xffffff80
	ds_read_b128 v[178:181], v209 offset:49152
	ds_read_b128 v[182:185], v209 offset:50176
	ds_read_b128 v[186:189], v209 offset:51200
	ds_read_b128 v[190:193], v209 offset:52224
	global_load_lds_dwordx4 v0, s[48:49] offset:128
	s_add_i32 m0, s4, 0x1f80
	s_nop 0
	global_load_lds_dwordx4 v212, s[48:49] offset:128
	s_barrier
; #define PG8_STAGE(bufoff, gbase, voff) do { _Pragma("unroll") for (int _i = 0; _i < 2; ++_i) \
;     __builtin_amdgcn_global_load_lds((const unsigned*)((const char*)(gbase) + (voff)[_i]), (LAS unsigned*)(lds + (bufoff) + ldsw + _i * 8192), 16, 0, 0); } while (0)
; #define PG8_LDA(dst, b, h) do { _Pragma("unroll") for (int m = 0; m < 4; ++m) _Pragma("unroll") for (int k = 0; k < 2; ++k) dst[m][k] = *(const LAS bf16x8*)(lds + PG8_SA(b, h) + aoff + m * 2048 + k * 1024); } while (0)
; #define PG8_LDB(dst, b, h) do { _Pragma("unroll") for (int n = 0; n < 2; ++n) _Pragma("unroll") for (int k = 0; k < 2; ++k) dst[n][k] = *(const LAS bf16x8*)(lds + PG8_SB(b, h) + boff + n * 2048 + k * 1024); } while (0)
; #define PG8_MMA(ai, bj, At, Bt) do { __builtin_amdgcn_s_setprio(1); _Pragma("unroll") for (int m = 0; m < 4; ++m) _Pragma("unroll") for (int n = 0; n < 2; ++n) _Pragma("unroll") for (int k = 0; k < 2; ++k) \
;     acc[ai][bj][m][n] = __builtin_amdgcn_mfma_f32_16x16x32_bf16(Bt[n][k], At[m][k], acc[ai][bj][m][n], 0, 0, 0); __builtin_amdgcn_s_setprio(0); } while (0)
; #define PG8_WAIT_V(n) asm volatile("s_waitcnt vmcnt(" #n ")" ::: "memory")
; #define PG8_WAIT_L(n) asm volatile("s_waitcnt lgkmcnt(" #n ")" ::: "memory")
; #define PG8_BAR __builtin_amdgcn_s_barrier()
; #define PG8_SCHED __builtin_amdgcn_sched_barrier(0)
; template <class Epi, bool SPLITA = false>
; __device__ __forceinline__ void gemm_phase(const int tid, LAS unsigned char* lds, const Gemm g, const Order& S, const Epi& E) {
;     ...
;       PG8_WAIT_V(6); PG8_BAR; PG8_MMA(1, 1, At, B1); PG8_BAR;
;       PG8_LDB(B0, 1, 0); PG8_SCHED; PG8_LDA(At, 1, 0); PG8_STAGE(PG8_SA(0, 1), a2 + hstepA, voffA);
;       PG8_WAIT_L(8); PG8_BAR; PG8_WAIT_L(0); PG8_MMA(0, 0, At, B0); PG8_BAR; PG8_SCHED;
;       PG8_LDB(B1, 1, 1); PG8_STAGE(PG8_SB(1, 0), b3, voffB);
;       PG8_BAR; PG8_WAIT_L(0); PG8_MMA(0, 1, At, B1); PG8_BAR;
;       PG8_LDA(At, 1, 1); PG8_STAGE(PG8_SA(1, 0), a3, voffA);
;       PG8_BAR; PG8_WAIT_L(0); PG8_MMA(1, 0, At, B0); PG8_BAR; PG8_SCHED;
;       PG8_STAGE(PG8_SB(1, 1), b3 + hstepB, voffB);
;       PG8_WAIT_V(6); PG8_BAR; PG8_MMA(1, 1, At, B1); PG8_BAR;
	s_waitcnt lgkmcnt(0)
	s_setprio 1
	s_waitcnt lgkmcnt(0)
	v_mfma_f32_16x16x32_bf16 v[118:121], v[178:181], v[146:149], v[118:121]
	v_mfma_f32_16x16x32_bf16 v[114:117], v[186:189], v[146:149], v[114:117]
	v_mfma_f32_16x16x32_bf16 v[102:105], v[178:181], v[154:157], v[102:105]
	v_mfma_f32_16x16x32_bf16 v[98:101], v[186:189], v[154:157], v[98:101]
	v_mfma_f32_16x16x32_bf16 v[86:89], v[178:181], v[162:165], v[86:89]
	v_mfma_f32_16x16x32_bf16 v[82:85], v[186:189], v[162:165], v[82:85]
	v_mfma_f32_16x16x32_bf16 v[70:73], v[178:181], v[170:173], v[70:73]
	v_mfma_f32_16x16x32_bf16 v[66:69], v[186:189], v[170:173], v[66:69]
	v_mfma_f32_16x16x32_bf16 v[118:121], v[182:185], v[150:153], v[118:121]
	v_mfma_f32_16x16x32_bf16 v[114:117], v[190:193], v[150:153], v[114:117]
	v_mfma_f32_16x16x32_bf16 v[102:105], v[182:185], v[158:161], v[102:105]
	v_mfma_f32_16x16x32_bf16 v[98:101], v[190:193], v[158:161], v[98:101]
	v_mfma_f32_16x16x32_bf16 v[86:89], v[182:185], v[166:169], v[86:89]
	v_mfma_f32_16x16x32_bf16 v[82:85], v[190:193], v[166:169], v[82:85]
	v_mfma_f32_16x16x32_bf16 v[70:73], v[182:185], v[174:177], v[70:73]
	v_mfma_f32_16x16x32_bf16 v[66:69], v[190:193], v[174:177], v[66:69]
	s_setprio 0
	s_mov_b32 m0, s47
	s_barrier
	ds_read_b128 v[146:149], v211 offset:49152
	ds_read_b128 v[150:153], v211 offset:50176
	ds_read_b128 v[154:157], v211 offset:51200
	ds_read_b128 v[158:161], v211 offset:52224
	ds_read_b128 v[162:165], v211 offset:53248
	ds_read_b128 v[166:169], v211 offset:54272
	ds_read_b128 v[170:173], v211 offset:55296
	ds_read_b128 v[174:177], v211 offset:56320
	global_load_lds_dwordx4 v216, s[42:43]
	s_mov_b32 m0, s38
	s_nop 0
	global_load_lds_dwordx4 v214, s[42:43]
	s_barrier
	s_waitcnt lgkmcnt(0)
	s_setprio 1
	s_waitcnt lgkmcnt(0)
	v_mfma_f32_16x16x32_bf16 v[62:65], v[130:133], v[146:149], v[62:65]
	v_mfma_f32_16x16x32_bf16 v[58:61], v[138:141], v[146:149], v[58:61]
	v_mfma_f32_16x16x32_bf16 v[46:49], v[130:133], v[154:157], v[46:49]
	v_mfma_f32_16x16x32_bf16 v[42:45], v[138:141], v[154:157], v[42:45]
	v_mfma_f32_16x16x32_bf16 v[30:33], v[130:133], v[162:165], v[30:33]
	v_mfma_f32_16x16x32_bf16 v[26:29], v[138:141], v[162:165], v[26:29]
	v_mfma_f32_16x16x32_bf16 v[14:17], v[130:133], v[170:173], v[14:17]
	v_mfma_f32_16x16x32_bf16 v[10:13], v[138:141], v[170:173], v[10:13]
	v_mfma_f32_16x16x32_bf16 v[62:65], v[134:137], v[150:153], v[62:65]
	v_mfma_f32_16x16x32_bf16 v[58:61], v[142:145], v[150:153], v[58:61]
	v_mfma_f32_16x16x32_bf16 v[46:49], v[134:137], v[158:161], v[46:49]
	v_mfma_f32_16x16x32_bf16 v[42:45], v[142:145], v[158:161], v[42:45]
	v_mfma_f32_16x16x32_bf16 v[30:33], v[134:137], v[166:169], v[30:33]
	v_mfma_f32_16x16x32_bf16 v[26:29], v[142:145], v[166:169], v[26:29]
	v_mfma_f32_16x16x32_bf16 v[14:17], v[134:137], v[174:177], v[14:17]
	v_mfma_f32_16x16x32_bf16 v[10:13], v[142:145], v[174:177], v[10:13]
	s_setprio 0
	s_barrier
	s_add_u32 s22, s48, 0x80080
	s_addc_u32 s23, s49, 0
	s_add_i32 s4, s20, s93
	s_mov_b32 m0, s4
	s_nop 0
	global_load_lds_dwordx4 v0, s[22:23]
	s_add_i32 m0, s4, 0x2000
	s_nop 0
	global_load_lds_dwordx4 v212, s[22:23]
	s_waitcnt vmcnt(6)
	s_barrier
	s_setprio 1
	v_mfma_f32_16x16x32_bf16 v[54:57], v[178:181], v[146:149], v[54:57]
	v_mfma_f32_16x16x32_bf16 v[50:53], v[186:189], v[146:149], v[50:53]
	v_mfma_f32_16x16x32_bf16 v[38:41], v[178:181], v[154:157], v[38:41]
	v_mfma_f32_16x16x32_bf16 v[34:37], v[186:189], v[154:157], v[34:37]
	v_mfma_f32_16x16x32_bf16 v[22:25], v[178:181], v[162:165], v[22:25]
	v_mfma_f32_16x16x32_bf16 v[18:21], v[186:189], v[162:165], v[18:21]
	v_mfma_f32_16x16x32_bf16 v[6:9], v[178:181], v[170:173], v[6:9]
	v_mfma_f32_16x16x32_bf16 v[2:5], v[186:189], v[170:173], v[2:5]
	v_mfma_f32_16x16x32_bf16 v[54:57], v[182:185], v[150:153], v[54:57]
	v_mfma_f32_16x16x32_bf16 v[50:53], v[190:193], v[150:153], v[50:53]
	v_mfma_f32_16x16x32_bf16 v[38:41], v[182:185], v[158:161], v[38:41]
	v_mfma_f32_16x16x32_bf16 v[34:37], v[190:193], v[158:161], v[34:37]
	v_mfma_f32_16x16x32_bf16 v[22:25], v[182:185], v[166:169], v[22:25]
	v_mfma_f32_16x16x32_bf16 v[18:21], v[190:193], v[166:169], v[18:21]
	v_mfma_f32_16x16x32_bf16 v[6:9], v[182:185], v[174:177], v[6:9]
	v_mfma_f32_16x16x32_bf16 v[2:5], v[190:193], v[174:177], v[2:5]
	s_setprio 0
	s_add_u32 s40, s40, 0x100
	s_addc_u32 s41, s41, 0
	v_readlane_b32 s90, v255, 31
	s_cmp_gt_u32 s2, 29
	s_mov_b32 s2, s3
	v_readlane_b32 s91, v255, 32
	s_barrier
	s_cbranch_scc1 .LBB0_229

; #define PG8_STAGE(bufoff, gbase, voff) do { _Pragma("unroll") for (int _i = 0; _i < 2; ++_i) \
;     __builtin_amdgcn_global_load_lds((const unsigned*)((const char*)(gbase) + (voff)[_i]), (LAS unsigned*)(lds + (bufoff) + ldsw + _i * 8192), 16, 0, 0); } while (0)
; #define PG8_WAIT_V(n) asm volatile("s_waitcnt vmcnt(" #n ")" ::: "memory")
; #define PG8_BAR __builtin_amdgcn_s_barrier()
; template <class Epi, bool SPLITA = false>
; __device__ __forceinline__ void gemm_phase(const int tid, LAS unsigned char* lds, const Gemm g, const Order& S, const Epi& E) {
;     ...
;   const int aoff = lds_byte(wr * 64 + fr, fq * 8), boff = lds_byte(wc * 32 + fr, fq * 8);
;     ...
;   Unit cur, nxt; int ui = 0;
;   if (!S.next(0, cur)) return;
;   Acc acc;
; #pragma unroll
;   for (int a = 0; a < 2; ++a)
; #pragma unroll
;     for (int b = 0; b < 2; ++b)
; #pragma unroll
;       for (int m = 0; m < 4; ++m)
; #pragma unroll
;         for (int n = 0; n < 2; ++n) acc[a][b][m][n] = (f32x4){0.f, 0.f, 0.f, 0.f};
;   bf16x8 At[4][2], B0[2][2], B1[2][2];
;   const char* cA = (const char*)g.A + (size_t)cur.pm * tstepA + (size_t)cur.pn * apn; const char* cB = (const char*)g.Bt + (size_t)cur.pn * tstepB;
;   const char* cA2 = SPLITA ? (const char*)g.A2 + (size_t)cur.pm * tstepA : cA; const int nt1 = SPLITA ? g.nt1 : nt;
;     ...
;   PG8_STAGE(PG8_SB(0, 0), cB, voffB); PG8_STAGE(PG8_SA(0, 0), cA, voffA); PG8_STAGE(PG8_SB(0, 1), cB + hstepB, voffB); PG8_STAGE(PG8_SA(0, 1), cA + hstepA, voffA);
;   if (wr == 1) PG8_BAR;
;   PG8_WAIT_V(4); PG8_BAR;
;   PG8_STAGE(PG8_SB(1, 0), cB + kstep, voffB); PG8_STAGE(PG8_SA(1, 0), cA + kstep, voffA); PG8_STAGE(PG8_SB(1, 1), cB + hstepB + kstep, voffB);
;   PG8_WAIT_V(6); PG8_BAR;
.LBB0_319:
	v_bfe_u32 v144, v210, 4, 2
	v_and_b32_e32 v145, 15, v210
	v_lshlrev_b32_e32 v18, 4, v144
	v_lshlrev_b32_e32 v19, 2, v210
	s_lshl_b32 s44, s0, 6
	v_lshl_or_b32 v18, v145, 6, v18
	s_lshl_b32 s0, s0, 13
	v_and_b32_e32 v19, 32, v19
	v_bitop3_b32 v20, v18, s0, v19 bitop3:0xde
	s_lshl_b32 s0, s1, 5
	s_and_b32 s45, s0, 0x60
	s_add_i32 m0, s30, 0x18000
	v_lshl_add_u64 v[8:9], v[8:9], 0, s[96:97]
	s_lshl_b32 s0, s45, 7
	s_waitcnt vmcnt(4)
	s_barrier
	global_load_lds_dwordx4 v[8:9], off
	v_lshl_add_u64 v[6:7], v[6:7], 0, s[96:97]
	s_add_i32 m0, s30, 0x1a000
	s_add_i32 s46, s30, 0x8000
	s_add_i32 s47, s30, 0xa000
	v_bitop3_b32 v146, s0, v18, v19 bitop3:0xf6
	v_add_u32_e32 v146, 0x10000, v146
	global_load_lds_dwordx4 v[6:7], off
	v_lshl_add_u64 v[4:5], v[4:5], 0, s[96:97]
	s_mov_b32 m0, s46
	s_add_u32 s0, s10, 0x88080
	global_load_lds_dwordx4 v[4:5], off
	v_lshl_add_u64 v[2:3], v[2:3], 0, s[96:97]
	s_mov_b32 m0, s47
	s_addc_u32 s1, s11, 0
	global_load_lds_dwordx4 v[2:3], off
	s_add_i32 m0, s30, 0x1c000
	s_nop 0
	global_load_lds_dwordx4 v0, s[0:1]
	v_lshl_add_u64 v[2:3], s[0:1], 0, v[134:135]
	s_add_i32 m0, s30, 0x1e000
	s_movk_i32 s6, 0x880
	global_load_lds_dwordx4 v134, s[0:1]
	v_lshrrev_b32_e32 v3, 1, v10
	v_mul_lo_u32 v2, v12, s6
	s_mov_b32 s7, 0x8800
	v_mad_u64_u32 v[2:3], s[0:1], v3, s7, v[2:3]
	v_or_b32_e32 v2, v2, v11
	v_add_lshl_u32 v136, v2, v13, 1
	v_lshrrev_b32_e32 v3, 1, v14
	v_mul_lo_u32 v2, v16, s6
	s_waitcnt vmcnt(6)
	v_mad_u64_u32 v[2:3], s[0:1], v3, s7, v[2:3]
	v_or_b32_e32 v2, v2, v15
	s_ashr_i32 s48, s92, 31
	v_mov_b32_e32 v137, v1
	v_add_lshl_u32 v138, v2, v17, 1
	v_mov_b32_e32 v139, v1
	s_mov_b32 s49, 0
	v_add_u32_e32 v147, 0, v20
	s_barrier
	s_waitcnt vmcnt(0)
	s_branch .LBB0_321

; #define PG8_STAGE(bufoff, gbase, voff) do { _Pragma("unroll") for (int _i = 0; _i < 2; ++_i) \
;     __builtin_amdgcn_global_load_lds((const unsigned*)((const char*)(gbase) + (voff)[_i]), (LAS unsigned*)(lds + (bufoff) + ldsw + _i * 8192), 16, 0, 0); } while (0)
; #define PG8_LDA(dst, b, h) do { _Pragma("unroll") for (int m = 0; m < 4; ++m) _Pragma("unroll") for (int k = 0; k < 2; ++k) dst[m][k] = *(const LAS bf16x8*)(lds + PG8_SA(b, h) + aoff + m * 2048 + k * 1024); } while (0)
; #define PG8_LDB(dst, b, h) do { _Pragma("unroll") for (int n = 0; n < 2; ++n) _Pragma("unroll") for (int k = 0; k < 2; ++k) dst[n][k] = *(const LAS bf16x8*)(lds + PG8_SB(b, h) + boff + n * 2048 + k * 1024); } while (0)
; #define PG8_WAIT_V(n) asm volatile("s_waitcnt vmcnt(" #n ")" ::: "memory")
; #define PG8_WAIT_L(n) asm volatile("s_waitcnt lgkmcnt(" #n ")" ::: "memory")
; #define PG8_BAR __builtin_amdgcn_s_barrier()
; #define PG8_SCHED __builtin_amdgcn_sched_barrier(0)
; template <class Epi, bool SPLITA = false>
; __device__ __forceinline__ void gemm_phase(const int tid, LAS unsigned char* lds, const Gemm g, const Order& S, const Epi& E) {
;     ...
;     for (int t = 0; t < nt; t += 2) {
;       const bool last = (t == nt - 2);
;       if constexpr (SPLITA) { if (t == nt1) E.mid(acc, cur, wr, wc, fr, fq); }
;       const char* a1 = PG8_TA(t + 1);
;       const char* a2 = last ? nA : PG8_TA(t + 2); const char* b2 = last ? nB : cB + (size_t)(t + 2) * kstep;
;       const char* a3 = last ? nA + kstep : PG8_TA(t + 3); const char* b3 = b2 + kstep;
;       PG8_LDB(B0, 0, 0); PG8_SCHED; PG8_LDA(At, 0, 0); PG8_STAGE(PG8_SA(1, 1), a1 + hstepA, voffA);
;       PG8_WAIT_L(8); PG8_BAR; PG8_WAIT_L(0); PG8_MMA(0, 0, At, B0); PG8_BAR; PG8_SCHED;
;       PG8_LDB(B1, 0, 1); PG8_STAGE(PG8_SB(0, 0), b2, voffB);
;       PG8_BAR; PG8_WAIT_L(0); PG8_MMA(0, 1, At, B1); PG8_BAR;
;       PG8_LDA(At, 0, 1); PG8_STAGE(PG8_SA(0, 0), a2, voffA);
;       PG8_BAR; PG8_WAIT_L(0); PG8_MMA(1, 0, At, B0); PG8_BAR; PG8_SCHED;
;       PG8_STAGE(PG8_SB(0, 1), b2 + hstepB, voffB);
;       PG8_WAIT_V(6); PG8_BAR; PG8_MMA(1, 1, At, B1); PG8_BAR;
;       PG8_LDB(B0, 1, 0); PG8_SCHED; PG8_LDA(At, 1, 0); PG8_STAGE(PG8_SA(0, 1), a2 + hstepA, voffA);
;       PG8_WAIT_L(8); PG8_BAR; PG8_WAIT_L(0); PG8_MMA(0, 0, At, B0); PG8_BAR; PG8_SCHED;
.LBB0_328:
	s_add_u32 s12, s8, s10
	s_addc_u32 s13, s9, s11
	s_add_u32 s16, s12, 0x100
	s_addc_u32 s17, s13, 0
	s_add_u32 s20, s55, s10
	s_addc_u32 s21, s90, s11
	s_add_u32 s12, s12, 0x180
	s_addc_u32 s13, s13, 0
	s_add_i32 s22, 0, 0x10000
	ds_read_b128 v[148:151], v146
	ds_read_b128 v[152:155], v146 offset:1024
	ds_read_b128 v[156:159], v146 offset:2048
	ds_read_b128 v[160:163], v146 offset:3072
	s_cmpk_eq_i32 s10, 0x1000
	s_cselect_b32 s15, s41, s13
	s_cselect_b32 s14, s40, s12
	s_cselect_b32 s13, s7, s21
	s_cselect_b32 s12, s6, s20
	s_cselect_b32 s17, s1, s17
	s_cselect_b32 s16, s0, s16
	v_lshl_add_u64 v[192:193], v[140:141], 0, s[10:11]
	s_add_i32 m0, s30, 0xc000
	ds_read_b128 v[164:167], v147
	ds_read_b128 v[168:171], v147 offset:1024
	ds_read_b128 v[172:175], v147 offset:2048
	ds_read_b128 v[176:179], v147 offset:3072
	ds_read_b128 v[180:183], v147 offset:4096
	ds_read_b128 v[184:187], v147 offset:5120
	ds_read_b128 v[188:191], v147 offset:6144
	ds_read_b128 v[212:215], v147 offset:7168
	global_load_lds_dwordx4 v[192:193], off
	v_lshl_add_u64 v[192:193], v[142:143], 0, s[10:11]
	s_add_i32 m0, s30, 0xe000
	s_nop 0
	global_load_lds_dwordx4 v[192:193], off
	s_waitcnt lgkmcnt(8)
	s_barrier
	s_waitcnt lgkmcnt(0)
	s_setprio 1
	s_waitcnt lgkmcnt(0)
	v_mfma_f32_16x16x32_bf16 v[126:129], v[148:151], v[164:167], v[126:129]
	v_mfma_f32_16x16x32_bf16 v[122:125], v[156:159], v[164:167], v[122:125]
	v_mfma_f32_16x16x32_bf16 v[110:113], v[148:151], v[172:175], v[110:113]
	v_mfma_f32_16x16x32_bf16 v[106:109], v[156:159], v[172:175], v[106:109]
	v_mfma_f32_16x16x32_bf16 v[94:97], v[148:151], v[180:183], v[94:97]
	v_mfma_f32_16x16x32_bf16 v[90:93], v[156:159], v[180:183], v[90:93]
	v_mfma_f32_16x16x32_bf16 v[78:81], v[148:151], v[188:191], v[78:81]
	v_mfma_f32_16x16x32_bf16 v[74:77], v[156:159], v[188:191], v[74:77]
	v_mfma_f32_16x16x32_bf16 v[126:129], v[152:155], v[168:171], v[126:129]
	v_mfma_f32_16x16x32_bf16 v[122:125], v[160:163], v[168:171], v[122:125]
	v_mfma_f32_16x16x32_bf16 v[110:113], v[152:155], v[176:179], v[110:113]
	v_mfma_f32_16x16x32_bf16 v[106:109], v[160:163], v[176:179], v[106:109]
	v_mfma_f32_16x16x32_bf16 v[94:97], v[152:155], v[184:187], v[94:97]
	v_mfma_f32_16x16x32_bf16 v[90:93], v[160:163], v[184:187], v[90:93]
	v_mfma_f32_16x16x32_bf16 v[78:81], v[152:155], v[212:215], v[78:81]
	v_mfma_f32_16x16x32_bf16 v[74:77], v[160:163], v[212:215], v[74:77]
	s_setprio 0
	s_barrier
	s_add_i32 s20, 0, 0x14000
	s_add_i32 s21, s22, s18
	ds_read_b128 v[216:219], v146 offset:16384
	ds_read_b128 v[220:223], v146 offset:17408
	ds_read_b128 v[224:227], v146 offset:18432
	ds_read_b128 v[228:231], v146 offset:19456
	s_mov_b32 m0, s21
	s_nop 0
	global_load_lds_dwordx4 v0, s[12:13]
	s_add_i32 m0, s21, 0x2000
	s_nop 0
	global_load_lds_dwordx4 v134, s[12:13]
	s_barrier
	s_waitcnt lgkmcnt(0)
	s_setprio 1
	s_waitcnt lgkmcnt(0)
	v_mfma_f32_16x16x32_bf16 v[118:121], v[216:219], v[164:167], v[118:121]
	v_mfma_f32_16x16x32_bf16 v[114:117], v[224:227], v[164:167], v[114:117]
	v_mfma_f32_16x16x32_bf16 v[102:105], v[216:219], v[172:175], v[102:105]
	v_mfma_f32_16x16x32_bf16 v[98:101], v[224:227], v[172:175], v[98:101]
	v_mfma_f32_16x16x32_bf16 v[86:89], v[216:219], v[180:183], v[86:89]
	v_mfma_f32_16x16x32_bf16 v[82:85], v[224:227], v[180:183], v[82:85]
	v_mfma_f32_16x16x32_bf16 v[70:73], v[216:219], v[188:191], v[70:73]
	v_mfma_f32_16x16x32_bf16 v[66:69], v[224:227], v[188:191], v[66:69]
	v_mfma_f32_16x16x32_bf16 v[118:121], v[220:223], v[168:171], v[118:121]
	v_mfma_f32_16x16x32_bf16 v[114:117], v[228:231], v[168:171], v[114:117]
	v_mfma_f32_16x16x32_bf16 v[102:105], v[220:223], v[176:179], v[102:105]
	v_mfma_f32_16x16x32_bf16 v[98:101], v[228:231], v[176:179], v[98:101]
	v_mfma_f32_16x16x32_bf16 v[86:89], v[220:223], v[184:187], v[86:89]
	v_mfma_f32_16x16x32_bf16 v[82:85], v[228:231], v[184:187], v[82:85]
	v_mfma_f32_16x16x32_bf16 v[70:73], v[220:223], v[212:215], v[70:73]
	v_mfma_f32_16x16x32_bf16 v[66:69], v[228:231], v[212:215], v[66:69]
	s_setprio 0
	s_mov_b32 m0, s30
	s_barrier
	ds_read_b128 v[164:167], v147 offset:16384
	ds_read_b128 v[168:171], v147 offset:17408
	ds_read_b128 v[172:175], v147 offset:18432
	ds_read_b128 v[176:179], v147 offset:19456
	ds_read_b128 v[180:183], v147 offset:20480
	ds_read_b128 v[184:187], v147 offset:21504
	ds_read_b128 v[188:191], v147 offset:22528
	ds_read_b128 v[212:215], v147 offset:23552
	global_load_lds_dwordx4 v130, s[16:17]
	s_mov_b32 m0, s31
	s_nop 0
	global_load_lds_dwordx4 v132, s[16:17]
	s_barrier
	s_waitcnt lgkmcnt(0)
	s_setprio 1
	s_waitcnt lgkmcnt(0)
	v_mfma_f32_16x16x32_bf16 v[62:65], v[148:151], v[164:167], v[62:65]
	v_mfma_f32_16x16x32_bf16 v[58:61], v[156:159], v[164:167], v[58:61]
	v_mfma_f32_16x16x32_bf16 v[46:49], v[148:151], v[172:175], v[46:49]
	v_mfma_f32_16x16x32_bf16 v[42:45], v[156:159], v[172:175], v[42:45]
	v_mfma_f32_16x16x32_bf16 v[30:33], v[148:151], v[180:183], v[30:33]
	v_mfma_f32_16x16x32_bf16 v[26:29], v[156:159], v[180:183], v[26:29]
	v_mfma_f32_16x16x32_bf16 v[14:17], v[148:151], v[188:191], v[14:17]
	v_mfma_f32_16x16x32_bf16 v[10:13], v[156:159], v[188:191], v[10:13]
	v_mfma_f32_16x16x32_bf16 v[62:65], v[152:155], v[168:171], v[62:65]
	v_mfma_f32_16x16x32_bf16 v[58:61], v[160:163], v[168:171], v[58:61]
	v_mfma_f32_16x16x32_bf16 v[46:49], v[152:155], v[176:179], v[46:49]
	v_mfma_f32_16x16x32_bf16 v[42:45], v[160:163], v[176:179], v[42:45]
	v_mfma_f32_16x16x32_bf16 v[30:33], v[152:155], v[184:187], v[30:33]
	v_mfma_f32_16x16x32_bf16 v[26:29], v[160:163], v[184:187], v[26:29]
	v_mfma_f32_16x16x32_bf16 v[14:17], v[152:155], v[212:215], v[14:17]
	v_mfma_f32_16x16x32_bf16 v[10:13], v[160:163], v[212:215], v[10:13]
	s_setprio 0
	s_barrier
; #define PG8_STAGE(bufoff, gbase, voff) do { _Pragma("unroll") for (int _i = 0; _i < 2; ++_i) \
;     __builtin_amdgcn_global_load_lds((const unsigned*)((const char*)(gbase) + (voff)[_i]), (LAS unsigned*)(lds + (bufoff) + ldsw + _i * 8192), 16, 0, 0); } while (0)
; #define PG8_LDA(dst, b, h) do { _Pragma("unroll") for (int m = 0; m < 4; ++m) _Pragma("unroll") for (int k = 0; k < 2; ++k) dst[m][k] = *(const LAS bf16x8*)(lds + PG8_SA(b, h) + aoff + m * 2048 + k * 1024); } while (0)
; #define PG8_LDB(dst, b, h) do { _Pragma("unroll") for (int n = 0; n < 2; ++n) _Pragma("unroll") for (int k = 0; k < 2; ++k) dst[n][k] = *(const LAS bf16x8*)(lds + PG8_SB(b, h) + boff + n * 2048 + k * 1024); } while (0)
; #define PG8_MMA(ai, bj, At, Bt) do { __builtin_amdgcn_s_setprio(1); _Pragma("unroll") for (int m = 0; m < 4; ++m) _Pragma("unroll") for (int n = 0; n < 2; ++n) _Pragma("unroll") for (int k = 0; k < 2; ++k) \
;     acc[ai][bj][m][n] = __builtin_amdgcn_mfma_f32_16x16x32_bf16(Bt[n][k], At[m][k], acc[ai][bj][m][n], 0, 0, 0); __builtin_amdgcn_s_setprio(0); } while (0)
; #define PG8_WAIT_V(n) asm volatile("s_waitcnt vmcnt(" #n ")" ::: "memory")
; #define PG8_WAIT_L(n) asm volatile("s_waitcnt lgkmcnt(" #n ")" ::: "memory")
; #define PG8_BAR __builtin_amdgcn_s_barrier()
; #define PG8_SCHED __builtin_amdgcn_sched_barrier(0)
; template <class Epi, bool SPLITA = false>
; __device__ __forceinline__ void gemm_phase(const int tid, LAS unsigned char* lds, const Gemm g, const Order& S, const Epi& E) {
;     ...
;       PG8_LDA(At, 0, 1); PG8_STAGE(PG8_SA(0, 0), a2, voffA);
;       PG8_BAR; PG8_WAIT_L(0); PG8_MMA(1, 0, At, B0); PG8_BAR; PG8_SCHED;
;       PG8_STAGE(PG8_SB(0, 1), b2 + hstepB, voffB);
;       PG8_WAIT_V(6); PG8_BAR; PG8_MMA(1, 1, At, B1); PG8_BAR;
;       PG8_LDB(B0, 1, 0); PG8_SCHED; PG8_LDA(At, 1, 0); PG8_STAGE(PG8_SA(0, 1), a2 + hstepA, voffA);
;       PG8_WAIT_L(8); PG8_BAR; PG8_WAIT_L(0); PG8_MMA(0, 0, At, B0); PG8_BAR; PG8_SCHED;
;       PG8_LDB(B1, 1, 1); PG8_STAGE(PG8_SB(1, 0), b3, voffB);
;       PG8_BAR; PG8_WAIT_L(0); PG8_MMA(0, 1, At, B1); PG8_BAR;
;       PG8_LDA(At, 1, 1); PG8_STAGE(PG8_SA(1, 0), a3, voffA);
;       PG8_BAR; PG8_WAIT_L(0); PG8_MMA(1, 0, At, B0); PG8_BAR; PG8_SCHED;
	s_add_u32 s22, s12, 0x88000
	s_addc_u32 s23, s13, 0
	s_add_i32 s20, s20, s18
	s_mov_b32 m0, s20
	s_nop 0
	global_load_lds_dwordx4 v0, s[22:23]
	s_add_i32 m0, s20, 0x2000
	s_nop 0
	global_load_lds_dwordx4 v134, s[22:23]
	s_waitcnt vmcnt(6)
	s_barrier
	s_setprio 1
	v_mfma_f32_16x16x32_bf16 v[54:57], v[216:219], v[164:167], v[54:57]
	v_mfma_f32_16x16x32_bf16 v[50:53], v[224:227], v[164:167], v[50:53]
	v_mfma_f32_16x16x32_bf16 v[38:41], v[216:219], v[172:175], v[38:41]
	v_mfma_f32_16x16x32_bf16 v[34:37], v[224:227], v[172:175], v[34:37]
	v_mfma_f32_16x16x32_bf16 v[22:25], v[216:219], v[180:183], v[22:25]
	v_mfma_f32_16x16x32_bf16 v[18:21], v[224:227], v[180:183], v[18:21]
	v_mfma_f32_16x16x32_bf16 v[6:9], v[216:219], v[188:191], v[6:9]
	v_mfma_f32_16x16x32_bf16 v[2:5], v[224:227], v[188:191], v[2:5]
	v_mfma_f32_16x16x32_bf16 v[54:57], v[220:223], v[168:171], v[54:57]
	v_mfma_f32_16x16x32_bf16 v[50:53], v[228:231], v[168:171], v[50:53]
	v_mfma_f32_16x16x32_bf16 v[38:41], v[220:223], v[176:179], v[38:41]
	v_mfma_f32_16x16x32_bf16 v[34:37], v[228:231], v[176:179], v[34:37]
	v_mfma_f32_16x16x32_bf16 v[22:25], v[220:223], v[184:187], v[22:25]
	v_mfma_f32_16x16x32_bf16 v[18:21], v[228:231], v[184:187], v[18:21]
	v_mfma_f32_16x16x32_bf16 v[6:9], v[220:223], v[212:215], v[6:9]
	v_mfma_f32_16x16x32_bf16 v[2:5], v[228:231], v[212:215], v[2:5]
	s_setprio 0
	s_add_i32 s20, 0, 0x18000
	s_barrier
	ds_read_b128 v[148:151], v146 offset:32768
	ds_read_b128 v[152:155], v146 offset:33792
	ds_read_b128 v[156:159], v146 offset:34816
	ds_read_b128 v[160:163], v146 offset:35840
	s_add_u32 s16, s16, 0x88000
	s_addc_u32 s17, s17, 0
	s_mov_b32 m0, s42
	ds_read_b128 v[164:167], v147 offset:32768
	ds_read_b128 v[168:171], v147 offset:33792
	ds_read_b128 v[172:175], v147 offset:34816
	ds_read_b128 v[176:179], v147 offset:35840
	ds_read_b128 v[180:183], v147 offset:36864
	ds_read_b128 v[184:187], v147 offset:37888
	ds_read_b128 v[188:191], v147 offset:38912
	ds_read_b128 v[212:215], v147 offset:39936
	global_load_lds_dwordx4 v130, s[16:17]
	s_mov_b32 m0, s43
	s_nop 0
	global_load_lds_dwordx4 v132, s[16:17]
	s_waitcnt lgkmcnt(8)
	s_barrier
	s_waitcnt lgkmcnt(0)
	s_setprio 1
	s_waitcnt lgkmcnt(0)
	v_mfma_f32_16x16x32_bf16 v[126:129], v[148:151], v[164:167], v[126:129]
	v_mfma_f32_16x16x32_bf16 v[122:125], v[156:159], v[164:167], v[122:125]
	v_mfma_f32_16x16x32_bf16 v[110:113], v[148:151], v[172:175], v[110:113]
	v_mfma_f32_16x16x32_bf16 v[106:109], v[156:159], v[172:175], v[106:109]
	v_mfma_f32_16x16x32_bf16 v[94:97], v[148:151], v[180:183], v[94:97]
	v_mfma_f32_16x16x32_bf16 v[90:93], v[156:159], v[180:183], v[90:93]
	v_mfma_f32_16x16x32_bf16 v[78:81], v[148:151], v[188:191], v[78:81]
	v_mfma_f32_16x16x32_bf16 v[74:77], v[156:159], v[188:191], v[74:77]
	v_mfma_f32_16x16x32_bf16 v[126:129], v[152:155], v[168:171], v[126:129]
	v_mfma_f32_16x16x32_bf16 v[122:125], v[160:163], v[168:171], v[122:125]
	v_mfma_f32_16x16x32_bf16 v[110:113], v[152:155], v[176:179], v[110:113]
	v_mfma_f32_16x16x32_bf16 v[106:109], v[160:163], v[176:179], v[106:109]
	v_mfma_f32_16x16x32_bf16 v[94:97], v[152:155], v[184:187], v[94:97]
	v_mfma_f32_16x16x32_bf16 v[90:93], v[160:163], v[184:187], v[90:93]
	v_mfma_f32_16x16x32_bf16 v[78:81], v[152:155], v[212:215], v[78:81]
	v_mfma_f32_16x16x32_bf16 v[74:77], v[160:163], v[212:215], v[74:77]
	s_setprio 0
	s_barrier
	s_add_i32 s16, 0, 0x1c000
	s_add_i32 s17, s20, s18
	s_add_i32 m0, s17, 0xffffff80
	ds_read_b128 v[216:219], v146 offset:49152
	ds_read_b128 v[220:223], v146 offset:50176
	ds_read_b128 v[224:227], v146 offset:51200
	ds_read_b128 v[228:231], v146 offset:52224
	global_load_lds_dwordx4 v0, s[12:13] offset:128
	s_add_i32 m0, s17, 0x1f80
	s_nop 0
	global_load_lds_dwordx4 v134, s[12:13] offset:128
	s_barrier
	s_waitcnt lgkmcnt(0)
	s_setprio 1
	s_waitcnt lgkmcnt(0)
	v_mfma_f32_16x16x32_bf16 v[118:121], v[216:219], v[164:167], v[118:121]
	v_mfma_f32_16x16x32_bf16 v[114:117], v[224:227], v[164:167], v[114:117]
	v_mfma_f32_16x16x32_bf16 v[102:105], v[216:219], v[172:175], v[102:105]
	v_mfma_f32_16x16x32_bf16 v[98:101], v[224:227], v[172:175], v[98:101]
	v_mfma_f32_16x16x32_bf16 v[86:89], v[216:219], v[180:183], v[86:89]
	v_mfma_f32_16x16x32_bf16 v[82:85], v[224:227], v[180:183], v[82:85]
	v_mfma_f32_16x16x32_bf16 v[70:73], v[216:219], v[188:191], v[70:73]
	v_mfma_f32_16x16x32_bf16 v[66:69], v[224:227], v[188:191], v[66:69]
	v_mfma_f32_16x16x32_bf16 v[118:121], v[220:223], v[168:171], v[118:121]
	v_mfma_f32_16x16x32_bf16 v[114:117], v[228:231], v[168:171], v[114:117]
	v_mfma_f32_16x16x32_bf16 v[102:105], v[220:223], v[176:179], v[102:105]
	v_mfma_f32_16x16x32_bf16 v[98:101], v[228:231], v[176:179], v[98:101]
	v_mfma_f32_16x16x32_bf16 v[86:89], v[220:223], v[184:187], v[86:89]
	v_mfma_f32_16x16x32_bf16 v[82:85], v[228:231], v[184:187], v[82:85]
	v_mfma_f32_16x16x32_bf16 v[70:73], v[220:223], v[212:215], v[70:73]
	v_mfma_f32_16x16x32_bf16 v[66:69], v[228:231], v[212:215], v[66:69]
	s_setprio 0
	s_mov_b32 m0, s46
	s_barrier
; #define PG8_STAGE(bufoff, gbase, voff) do { _Pragma("unroll") for (int _i = 0; _i < 2; ++_i) \
;     __builtin_amdgcn_global_load_lds((const unsigned*)((const char*)(gbase) + (voff)[_i]), (LAS unsigned*)(lds + (bufoff) + ldsw + _i * 8192), 16, 0, 0); } while (0)
; #define PG8_LDA(dst, b, h) do { _Pragma("unroll") for (int m = 0; m < 4; ++m) _Pragma("unroll") for (int k = 0; k < 2; ++k) dst[m][k] = *(const LAS bf16x8*)(lds + PG8_SA(b, h) + aoff + m * 2048 + k * 1024); } while (0)
; #define PG8_LDB(dst, b, h) do { _Pragma("unroll") for (int n = 0; n < 2; ++n) _Pragma("unroll") for (int k = 0; k < 2; ++k) dst[n][k] = *(const LAS bf16x8*)(lds + PG8_SB(b, h) + boff + n * 2048 + k * 1024); } while (0)
; #define PG8_MMA(ai, bj, At, Bt) do { __builtin_amdgcn_s_setprio(1); _Pragma("unroll") for (int m = 0; m < 4; ++m) _Pragma("unroll") for (int n = 0; n < 2; ++n) _Pragma("unroll") for (int k = 0; k < 2; ++k) \
;     acc[ai][bj][m][n] = __builtin_amdgcn_mfma_f32_16x16x32_bf16(Bt[n][k], At[m][k], acc[ai][bj][m][n], 0, 0, 0); __builtin_amdgcn_s_setprio(0); } while (0)
; #define PG8_WAIT_V(n) asm volatile("s_waitcnt vmcnt(" #n ")" ::: "memory")
; #define PG8_BAR __builtin_amdgcn_s_barrier()
; template <class Epi, bool SPLITA = false>
; __device__ __forceinline__ void gemm_phase(const int tid, LAS unsigned char* lds, const Gemm g, const Order& S, const Epi& E) {
;     ...
;       PG8_LDB(B1, 1, 1); PG8_STAGE(PG8_SB(1, 0), b3, voffB);
;       PG8_BAR; PG8_WAIT_L(0); PG8_MMA(0, 1, At, B1); PG8_BAR;
;       PG8_LDA(At, 1, 1); PG8_STAGE(PG8_SA(1, 0), a3, voffA);
;       PG8_BAR; PG8_WAIT_L(0); PG8_MMA(1, 0, At, B0); PG8_BAR; PG8_SCHED;
;       PG8_STAGE(PG8_SB(1, 1), b3 + hstepB, voffB);
;       PG8_WAIT_V(6); PG8_BAR; PG8_MMA(1, 1, At, B1); PG8_BAR;
;   __device__ __forceinline__ void operator()(const Acc& acc, const Unit& u, int wr, int wc, int fr_, int fq_) const {
;     ...
;     const int z = u.pn >> 2, b = z >> 4, k1 = z & 15, j0 = (u.pn & 3) * 256 + wc * 32 + 8 * fq;
;     const int r0 = u.pm * BM + wr * 64 + fr;
; #pragma unroll
;     for (int ai = 0; ai < 2; ++ai)
; #pragma unroll
;       for (int m = 0; m < 4; ++m) { const int k2 = r0 + ai * HALF + m * 16;
;         if (k2 < FN2) { bf16_t* rowp = F + (size_t)row_of(b, k1 + 16 * k2) * 1024 + j0;
; #pragma unroll
;           for (int bj = 0; bj < 2; ++bj) *(u32x4*)(rowp + bj * HALF) = pack8(acc[ai][bj][m][0], acc[ai][bj][m][1]); } }
	ds_read_b128 v[164:167], v147 offset:49152
	ds_read_b128 v[168:171], v147 offset:50176
	ds_read_b128 v[172:175], v147 offset:51200
	ds_read_b128 v[176:179], v147 offset:52224
	ds_read_b128 v[180:183], v147 offset:53248
	ds_read_b128 v[184:187], v147 offset:54272
	ds_read_b128 v[188:191], v147 offset:55296
	ds_read_b128 v[212:215], v147 offset:56320
	global_load_lds_dwordx4 v130, s[14:15]
	s_mov_b32 m0, s47
	s_nop 0
	global_load_lds_dwordx4 v132, s[14:15]
	s_barrier
	s_waitcnt lgkmcnt(0)
	s_setprio 1
	s_waitcnt lgkmcnt(0)
	v_mfma_f32_16x16x32_bf16 v[62:65], v[148:151], v[164:167], v[62:65]
	v_mfma_f32_16x16x32_bf16 v[58:61], v[156:159], v[164:167], v[58:61]
	v_mfma_f32_16x16x32_bf16 v[46:49], v[148:151], v[172:175], v[46:49]
	v_mfma_f32_16x16x32_bf16 v[42:45], v[156:159], v[172:175], v[42:45]
	v_mfma_f32_16x16x32_bf16 v[30:33], v[148:151], v[180:183], v[30:33]
	v_mfma_f32_16x16x32_bf16 v[26:29], v[156:159], v[180:183], v[26:29]
	v_mfma_f32_16x16x32_bf16 v[14:17], v[148:151], v[188:191], v[14:17]
	v_mfma_f32_16x16x32_bf16 v[10:13], v[156:159], v[188:191], v[10:13]
	v_mfma_f32_16x16x32_bf16 v[62:65], v[152:155], v[168:171], v[62:65]
	v_mfma_f32_16x16x32_bf16 v[58:61], v[160:163], v[168:171], v[58:61]
	v_mfma_f32_16x16x32_bf16 v[46:49], v[152:155], v[176:179], v[46:49]
	v_mfma_f32_16x16x32_bf16 v[42:45], v[160:163], v[176:179], v[42:45]
	v_mfma_f32_16x16x32_bf16 v[30:33], v[152:155], v[184:187], v[30:33]
	v_mfma_f32_16x16x32_bf16 v[26:29], v[160:163], v[184:187], v[26:29]
	v_mfma_f32_16x16x32_bf16 v[14:17], v[152:155], v[212:215], v[14:17]
	v_mfma_f32_16x16x32_bf16 v[10:13], v[160:163], v[212:215], v[10:13]
	s_setprio 0
	s_barrier
	s_add_u32 s12, s12, 0x88080
	s_addc_u32 s13, s13, 0
	s_add_i32 s14, s16, s18
	s_mov_b32 m0, s14
	s_nop 0
	global_load_lds_dwordx4 v0, s[12:13]
	s_add_i32 m0, s14, 0x2000
	s_nop 0
	global_load_lds_dwordx4 v134, s[12:13]
	s_waitcnt vmcnt(6)
	s_barrier
	s_setprio 1
	v_mfma_f32_16x16x32_bf16 v[54:57], v[216:219], v[164:167], v[54:57]
	v_mfma_f32_16x16x32_bf16 v[50:53], v[224:227], v[164:167], v[50:53]
	v_mfma_f32_16x16x32_bf16 v[38:41], v[216:219], v[172:175], v[38:41]
	v_mfma_f32_16x16x32_bf16 v[34:37], v[224:227], v[172:175], v[34:37]
	v_mfma_f32_16x16x32_bf16 v[22:25], v[216:219], v[180:183], v[22:25]
	v_mfma_f32_16x16x32_bf16 v[18:21], v[224:227], v[180:183], v[18:21]
	v_mfma_f32_16x16x32_bf16 v[6:9], v[216:219], v[188:191], v[6:9]
	v_mfma_f32_16x16x32_bf16 v[2:5], v[224:227], v[188:191], v[2:5]
	v_mfma_f32_16x16x32_bf16 v[54:57], v[220:223], v[168:171], v[54:57]
	v_mfma_f32_16x16x32_bf16 v[50:53], v[228:231], v[168:171], v[50:53]
	v_mfma_f32_16x16x32_bf16 v[38:41], v[220:223], v[176:179], v[38:41]
	v_mfma_f32_16x16x32_bf16 v[34:37], v[228:231], v[176:179], v[34:37]
	v_mfma_f32_16x16x32_bf16 v[22:25], v[220:223], v[184:187], v[22:25]
	v_mfma_f32_16x16x32_bf16 v[18:21], v[228:231], v[184:187], v[18:21]
	v_mfma_f32_16x16x32_bf16 v[6:9], v[220:223], v[212:215], v[6:9]
	v_mfma_f32_16x16x32_bf16 v[2:5], v[228:231], v[212:215], v[2:5]
	s_setprio 0
	s_add_i32 s91, s91, 2
	s_add_u32 s10, s10, 0x100
	s_addc_u32 s11, s11, 0
	s_cmp_gt_u32 s91, 31
	s_barrier
	s_cbranch_scc0 .LBB0_328
	s_lshl_b32 s10, s51, 8
	v_mov_b32_e32 v141, v145
	v_mov_b32_e32 v140, v144
	s_and_b32 s10, s10, 0x300
	s_or_b32 s10, s10, s45
	v_lshl_add_u32 v140, v140, 3, s10
	s_lshl_b32 s10, s52, 8
	s_ashr_i32 s8, s51, 6
	s_add_i32 s10, s10, s44
	s_bfe_u32 s9, s51, 0x40002
	v_add_u32_e32 v142, s10, v141
	s_lshl_b32 s10, s8, 14
	s_lshl_b32 s11, s8, 4
	s_movk_i32 s8, 0x401
	s_add_i32 s10, s10, -16
	s_add_i32 s11, s11, 0x8000
	v_ashrrev_i32_e32 v141, 31, v140
	v_cmp_gt_i32_e32 vcc, s8, v142
	v_lshl_or_b32 v143, v142, 4, s9
	s_and_saveexec_b64 s[8:9], vcc
	s_cbranch_execz .LBB0_331
	v_mov_b32_e32 v148, s10
	v_mov_b32_e32 v149, s11
	v_cmp_gt_i32_e32 vcc, 16, v143
	v_readlane_b32 s12, v255, 1
	v_readlane_b32 s13, v255, 2
	v_cndmask_b32_e32 v148, v148, v149, vcc
	v_add_u32_e32 v148, v148, v143
	v_ashrrev_i32_e32 v149, 31, v148
	v_lshlrev_b64 v[148:149], 11, v[148:149]
	v_lshl_add_u64 v[148:149], s[12:13], 0, v[148:149]
	v_lshl_add_u64 v[148:149], v[140:141], 1, v[148:149]
	v_cvt_pk_bf16_f32 v126, v126, v127
	v_cvt_pk_bf16_f32 v127, v128, v129
	v_cvt_pk_bf16_f32 v128, v122, v123
	v_cvt_pk_bf16_f32 v129, v124, v125
	v_cvt_pk_bf16_f32 v118, v118, v119
	v_cvt_pk_bf16_f32 v119, v120, v121
	v_cvt_pk_bf16_f32 v120, v114, v115
	v_cvt_pk_bf16_f32 v121, v116, v117
	global_store_dwordx4 v[148:149], v[126:129], off
	global_store_dwordx4 v[148:149], v[118:121], off offset:256

; #define PG8_STAGE(bufoff, gbase, voff) do { _Pragma("unroll") for (int _i = 0; _i < 2; ++_i) \
;     __builtin_amdgcn_global_load_lds((const unsigned*)((const char*)(gbase) + (voff)[_i]), (LAS unsigned*)(lds + (bufoff) + ldsw + _i * 8192), 16, 0, 0); } while (0)
; #define PG8_WAIT_V(n) asm volatile("s_waitcnt vmcnt(" #n ")" ::: "memory")
; #define PG8_BAR __builtin_amdgcn_s_barrier()
; template <class Epi, bool SPLITA = false>
; __device__ __forceinline__ void gemm_phase(const int tid, LAS unsigned char* lds, const Gemm g, const Order& S, const Epi& E) {
;     ...
;   const int K = g.K, nt = K / BK;
;   unsigned voffA[2], voffB[2];
; #pragma unroll
;   for (int i = 0; i < 2; ++i) { int R, C; stage_rc(tid * 16 + i * 8192, R, C); const int Rb = Epi::PERM ? ((R & ~31) + perm32(R & 31)) : R;
;     voffA[i] = (unsigned)(R * g.lda + C) * 2u; voffB[i] = (unsigned)(Rb * g.ldb + C) * 2u; }
;   const size_t kstep = (size_t)(BK * 2);
;   const size_t hstepA = (size_t)HALF * g.lda * 2, hstepB = (size_t)HALF * g.ldb * 2;
;   const size_t tstepA = 2 * hstepA, tstepB = g.bpn < 0 ? 2 * hstepB : (size_t)g.bpn, apn = (size_t)g.apn;
;   const unsigned ldsw = (unsigned)wid * 1024u;
;   const int aoff = lds_byte(wr * 64 + fr, fq * 8), boff = lds_byte(wc * 32 + fr, fq * 8);
;     ...
;   Unit cur, nxt; int ui = 0;
;   if (!S.next(0, cur)) return;
;   Acc acc;
; #pragma unroll
;   for (int a = 0; a < 2; ++a)
; #pragma unroll
;     for (int b = 0; b < 2; ++b)
; #pragma unroll
;       for (int m = 0; m < 4; ++m)
; #pragma unroll
;         for (int n = 0; n < 2; ++n) acc[a][b][m][n] = (f32x4){0.f, 0.f, 0.f, 0.f};
;   bf16x8 At[4][2], B0[2][2], B1[2][2];
;   const char* cA = (const char*)g.A + (size_t)cur.pm * tstepA + (size_t)cur.pn * apn; const char* cB = (const char*)g.Bt + (size_t)cur.pn * tstepB;
;   const char* cA2 = SPLITA ? (const char*)g.A2 + (size_t)cur.pm * tstepA : cA; const int nt1 = SPLITA ? g.nt1 : nt;
;     ...
;   PG8_STAGE(PG8_SB(0, 0), cB, voffB); PG8_STAGE(PG8_SA(0, 0), cA, voffA); PG8_STAGE(PG8_SB(0, 1), cB + hstepB, voffB); PG8_STAGE(PG8_SA(0, 1), cA + hstepA, voffA);
;   if (wr == 1) PG8_BAR;
;   PG8_WAIT_V(4); PG8_BAR;
;   PG8_STAGE(PG8_SB(1, 0), cB + kstep, voffB); PG8_STAGE(PG8_SA(1, 0), cA + kstep, voffA); PG8_STAGE(PG8_SB(1, 1), cB + hstepB + kstep, voffB);
;   PG8_WAIT_V(6); PG8_BAR;
.LBB0_388:
	s_and_b32 s90, 0xffff, s3
	s_ashr_i32 s3, s0, 31
	v_bfe_u32 v144, v210, 4, 2
	s_lshr_b32 s3, s3, 26
	s_lshl_b32 s1, s1, 5
	v_and_b32_e32 v145, 15, v210
	s_add_i32 s3, s0, s3
	v_lshlrev_b32_e32 v12, 4, v144
	v_lshlrev_b32_e32 v13, 2, v210
	s_and_b32 s48, s1, 0x60
	s_ashr_i32 s46, s3, 6
	s_lshl_b32 s47, s2, 6
	v_lshl_or_b32 v12, v145, 6, v12
	s_lshl_b32 s2, s2, 13
	v_and_b32_e32 v13, 32, v13
	s_lshl_b32 s1, s48, 7
	v_readlane_b32 s8, v255, 24
	v_bitop3_b32 v14, v12, s2, v13 bitop3:0xde
	v_readlane_b32 s9, v255, 25
	s_add_u32 s2, s8, 0x3c1e0080
	v_mov_b32_e32 v135, v1
	s_addc_u32 s3, s9, 0
	v_mov_b32_e32 v131, v1
	v_bitop3_b32 v146, s1, v12, v13 bitop3:0xf6
	v_add_u32_e32 v146, 0x10000, v146
	s_add_i32 m0, s30, 0x18000
	s_waitcnt vmcnt(4)
	s_barrier
	global_load_lds_dwordx4 v134, s[2:3]
	s_add_i32 m0, s30, 0x1a000
	s_add_i32 s49, s30, 0x8000
	s_add_i32 s51, s30, 0xa000
	global_load_lds_dwordx4 v130, s[2:3]
	v_lshl_add_u64 v[4:5], v[4:5], 0, s[96:97]
	s_mov_b32 m0, s49
	s_add_u32 s2, s8, 0x3c1e8080
	global_load_lds_dwordx4 v[4:5], off
	v_lshl_add_u64 v[2:3], v[2:3], 0, s[96:97]
	s_mov_b32 m0, s51
	s_addc_u32 s3, s9, 0
	global_load_lds_dwordx4 v[2:3], off
	s_add_i32 m0, s30, 0x1c000
	s_nop 0
	global_load_lds_dwordx4 v134, s[2:3]
	v_lshl_add_u64 v[2:3], s[2:3], 0, v[130:131]
	s_add_i32 m0, s30, 0x1e000
	s_cmp_gt_i32 s0, 63
	global_load_lds_dwordx4 v130, s[2:3]
	v_lshlrev_b32_e32 v2, 14, v9
	v_and_b32_e32 v2, 0xffff8000, v2
	v_lshl_add_u32 v2, v10, 11, v2
	v_and_b32_e32 v3, 1, v9
	v_lshl_or_b32 v2, v3, 6, v2
	v_lshl_add_u32 v2, v11, 1, v2
	v_mov_b32_e32 v3, v1
	s_mov_b64 s[0:1], 0x40080
	v_lshl_add_u64 v[136:137], v[2:3], 0, s[0:1]
	v_lshlrev_b32_e32 v2, 14, v6
	v_and_b32_e32 v2, 0xffff8000, v2
	v_lshl_add_u32 v2, v7, 11, v2
	v_and_b32_e32 v3, 1, v6
	s_waitcnt vmcnt(6)
	v_lshl_or_b32 v2, v3, 6, v2
	v_lshl_add_u32 v2, v8, 1, v2
	v_mov_b32_e32 v3, v1
	s_cselect_b64 s[2:3], -1, 0
	s_add_i32 s52, s46, -2
	s_ashr_i32 s53, s92, 31
	v_lshl_add_u64 v[138:139], v[2:3], 0, s[0:1]
	s_mov_b32 s54, 0
	v_add_u32_e32 v147, 0, v14
	s_barrier
	s_waitcnt vmcnt(0)
	s_branch .LBB0_390

; #define PG8_STAGE(bufoff, gbase, voff) do { _Pragma("unroll") for (int _i = 0; _i < 2; ++_i) \
;     __builtin_amdgcn_global_load_lds((const unsigned*)((const char*)(gbase) + (voff)[_i]), (LAS unsigned*)(lds + (bufoff) + ldsw + _i * 8192), 16, 0, 0); } while (0)
; #define PG8_LDA(dst, b, h) do { _Pragma("unroll") for (int m = 0; m < 4; ++m) _Pragma("unroll") for (int k = 0; k < 2; ++k) dst[m][k] = *(const LAS bf16x8*)(lds + PG8_SA(b, h) + aoff + m * 2048 + k * 1024); } while (0)
; #define PG8_LDB(dst, b, h) do { _Pragma("unroll") for (int n = 0; n < 2; ++n) _Pragma("unroll") for (int k = 0; k < 2; ++k) dst[n][k] = *(const LAS bf16x8*)(lds + PG8_SB(b, h) + boff + n * 2048 + k * 1024); } while (0)
; template <class Epi, bool SPLITA = false>
; __device__ __forceinline__ void gemm_phase(const int tid, LAS unsigned char* lds, const Gemm g, const Order& S, const Epi& E) {
;     ...
;     const bool has_next = S.next(ui + 1, nxt);
;     const char* nA = has_next ? (const char*)g.A + (size_t)nxt.pm * tstepA + (size_t)nxt.pn * apn : cA; const char* nA2 = (SPLITA && has_next) ? (const char*)g.A2 + (size_t)nxt.pm * tstepA : cA2; const char* nB = has_next ? (const char*)g.Bt + (size_t)nxt.pn * tstepB : cB;
;     for (int t = 0; t < nt; t += 2) {
;       const bool last = (t == nt - 2);
;       if constexpr (SPLITA) { if (t == nt1) E.mid(acc, cur, wr, wc, fr, fq); }
;       const char* a1 = PG8_TA(t + 1);
;       const char* a2 = last ? nA : PG8_TA(t + 2); const char* b2 = last ? nB : cB + (size_t)(t + 2) * kstep;
;       const char* a3 = last ? nA + kstep : PG8_TA(t + 3); const char* b3 = b2 + kstep;
;       PG8_LDB(B0, 0, 0); PG8_SCHED; PG8_LDA(At, 0, 0); PG8_STAGE(PG8_SA(1, 1), a1 + hstepA, voffA);
;       PG8_WAIT_L(8); PG8_BAR; PG8_WAIT_L(0); PG8_MMA(0, 0, At, B0); PG8_BAR; PG8_SCHED;
;       PG8_LDB(B1, 0, 1); PG8_STAGE(PG8_SB(0, 0), b2, voffB);
;       PG8_BAR; PG8_WAIT_L(0); PG8_MMA(0, 1, At, B1); PG8_BAR;
;       PG8_LDA(At, 0, 1); PG8_STAGE(PG8_SA(0, 0), a2, voffA);
;       PG8_BAR; PG8_WAIT_L(0); PG8_MMA(1, 0, At, B0); PG8_BAR; PG8_SCHED;
;       PG8_STAGE(PG8_SB(0, 1), b2 + hstepB, voffB);
;       PG8_WAIT_V(6); PG8_BAR; PG8_MMA(1, 1, At, B1); PG8_BAR;
;       PG8_LDB(B0, 1, 0); PG8_SCHED; PG8_LDA(At, 1, 0); PG8_STAGE(PG8_SA(0, 1), a2 + hstepA, voffA);
;       PG8_WAIT_L(8); PG8_BAR; PG8_WAIT_L(0); PG8_MMA(0, 0, At, B0); PG8_BAR; PG8_SCHED;
.LBB0_400:
	s_add_i32 s29, s18, 2
	s_add_u32 s16, s14, 0x100
	s_addc_u32 s17, s15, 0
	s_add_u32 s19, s12, s14
	s_addc_u32 s20, s13, s15
	s_add_u32 s21, s19, 0x100
	s_addc_u32 s22, s20, 0
	s_add_u32 s19, s19, 0x180
	s_addc_u32 s20, s20, 0
	s_add_i32 s23, 0, 0x10000
	ds_read_b128 v[148:151], v146
	ds_read_b128 v[152:155], v146 offset:1024
	ds_read_b128 v[156:159], v146 offset:2048
	ds_read_b128 v[160:163], v146 offset:3072
	s_cmp_eq_u32 s52, s18
	s_cselect_b32 s18, 0, s16
	s_cselect_b32 s41, s11, s20
	s_cselect_b32 s40, s9, s19
	s_cselect_b32 s19, 0, s17
	s_cselect_b32 s42, s0, s21
	s_cselect_b32 s43, s1, s22
	s_add_u32 s18, s6, s18
	s_addc_u32 s19, s7, s19
	v_lshl_add_u64 v[192:193], v[140:141], 0, s[14:15]
	s_add_i32 m0, s30, 0xc000
	ds_read_b128 v[164:167], v147
	ds_read_b128 v[168:171], v147 offset:1024
	ds_read_b128 v[172:175], v147 offset:2048
	ds_read_b128 v[176:179], v147 offset:3072
	ds_read_b128 v[180:183], v147 offset:4096
	ds_read_b128 v[184:187], v147 offset:5120
	ds_read_b128 v[188:191], v147 offset:6144
	ds_read_b128 v[212:215], v147 offset:7168
	global_load_lds_dwordx4 v[192:193], off
	v_lshl_add_u64 v[192:193], v[142:143], 0, s[14:15]
	s_add_i32 m0, s30, 0xe000
	s_nop 0
	global_load_lds_dwordx4 v[192:193], off
	s_waitcnt lgkmcnt(8)
	s_barrier
	s_waitcnt lgkmcnt(0)
	s_setprio 1
	s_waitcnt lgkmcnt(0)
	v_mfma_f32_16x16x32_bf16 v[122:125], v[148:151], v[164:167], v[122:125]
	v_mfma_f32_16x16x32_bf16 v[126:129], v[156:159], v[164:167], v[126:129]
	v_mfma_f32_16x16x32_bf16 v[110:113], v[148:151], v[172:175], v[110:113]
	v_mfma_f32_16x16x32_bf16 v[106:109], v[156:159], v[172:175], v[106:109]
	v_mfma_f32_16x16x32_bf16 v[94:97], v[148:151], v[180:183], v[94:97]
	v_mfma_f32_16x16x32_bf16 v[90:93], v[156:159], v[180:183], v[90:93]
	v_mfma_f32_16x16x32_bf16 v[78:81], v[148:151], v[188:191], v[78:81]
	v_mfma_f32_16x16x32_bf16 v[74:77], v[156:159], v[188:191], v[74:77]
	v_mfma_f32_16x16x32_bf16 v[122:125], v[152:155], v[168:171], v[122:125]
	v_mfma_f32_16x16x32_bf16 v[126:129], v[160:163], v[168:171], v[126:129]
	v_mfma_f32_16x16x32_bf16 v[110:113], v[152:155], v[176:179], v[110:113]
	v_mfma_f32_16x16x32_bf16 v[106:109], v[160:163], v[176:179], v[106:109]
	v_mfma_f32_16x16x32_bf16 v[94:97], v[152:155], v[184:187], v[94:97]
	v_mfma_f32_16x16x32_bf16 v[90:93], v[160:163], v[184:187], v[90:93]
	v_mfma_f32_16x16x32_bf16 v[78:81], v[152:155], v[212:215], v[78:81]
	v_mfma_f32_16x16x32_bf16 v[74:77], v[160:163], v[212:215], v[74:77]
	s_setprio 0
	s_barrier
	s_add_i32 s20, 0, 0x14000
	s_add_i32 s14, s23, s28
	ds_read_b128 v[216:219], v146 offset:16384
	ds_read_b128 v[220:223], v146 offset:17408
	ds_read_b128 v[224:227], v146 offset:18432
	ds_read_b128 v[228:231], v146 offset:19456
	s_mov_b32 m0, s14
	s_nop 0
	global_load_lds_dwordx4 v134, s[18:19]
	s_add_i32 m0, s14, 0x2000
	s_nop 0
	global_load_lds_dwordx4 v130, s[18:19]
	s_barrier
	s_waitcnt lgkmcnt(0)
	s_setprio 1
	s_waitcnt lgkmcnt(0)
	v_mfma_f32_16x16x32_bf16 v[118:121], v[216:219], v[164:167], v[118:121]
	v_mfma_f32_16x16x32_bf16 v[114:117], v[224:227], v[164:167], v[114:117]
	v_mfma_f32_16x16x32_bf16 v[102:105], v[216:219], v[172:175], v[102:105]
	v_mfma_f32_16x16x32_bf16 v[98:101], v[224:227], v[172:175], v[98:101]
	v_mfma_f32_16x16x32_bf16 v[86:89], v[216:219], v[180:183], v[86:89]
	v_mfma_f32_16x16x32_bf16 v[82:85], v[224:227], v[180:183], v[82:85]
	v_mfma_f32_16x16x32_bf16 v[70:73], v[216:219], v[188:191], v[70:73]
	v_mfma_f32_16x16x32_bf16 v[66:69], v[224:227], v[188:191], v[66:69]
	v_mfma_f32_16x16x32_bf16 v[118:121], v[220:223], v[168:171], v[118:121]
	v_mfma_f32_16x16x32_bf16 v[114:117], v[228:231], v[168:171], v[114:117]
	v_mfma_f32_16x16x32_bf16 v[102:105], v[220:223], v[176:179], v[102:105]
	v_mfma_f32_16x16x32_bf16 v[98:101], v[228:231], v[176:179], v[98:101]
	v_mfma_f32_16x16x32_bf16 v[86:89], v[220:223], v[184:187], v[86:89]
	v_mfma_f32_16x16x32_bf16 v[82:85], v[228:231], v[184:187], v[82:85]
	v_mfma_f32_16x16x32_bf16 v[70:73], v[220:223], v[212:215], v[70:73]
	v_mfma_f32_16x16x32_bf16 v[66:69], v[228:231], v[212:215], v[66:69]
	s_setprio 0
	s_mov_b32 m0, s30
	s_barrier
	ds_read_b128 v[164:167], v147 offset:16384
	ds_read_b128 v[168:171], v147 offset:17408
	ds_read_b128 v[172:175], v147 offset:18432
	ds_read_b128 v[176:179], v147 offset:19456
	ds_read_b128 v[180:183], v147 offset:20480
	ds_read_b128 v[184:187], v147 offset:21504
	ds_read_b128 v[188:191], v147 offset:22528
	ds_read_b128 v[212:215], v147 offset:23552
	global_load_lds_dwordx4 v0, s[42:43]
	s_mov_b32 m0, s31
	s_nop 0
	global_load_lds_dwordx4 v132, s[42:43]
	s_barrier
	s_waitcnt lgkmcnt(0)
	s_setprio 1
	s_waitcnt lgkmcnt(0)
	v_mfma_f32_16x16x32_bf16 v[62:65], v[148:151], v[164:167], v[62:65]
	v_mfma_f32_16x16x32_bf16 v[58:61], v[156:159], v[164:167], v[58:61]
	v_mfma_f32_16x16x32_bf16 v[46:49], v[148:151], v[172:175], v[46:49]
	v_mfma_f32_16x16x32_bf16 v[42:45], v[156:159], v[172:175], v[42:45]
	v_mfma_f32_16x16x32_bf16 v[30:33], v[148:151], v[180:183], v[30:33]
	v_mfma_f32_16x16x32_bf16 v[26:29], v[156:159], v[180:183], v[26:29]
	v_mfma_f32_16x16x32_bf16 v[14:17], v[148:151], v[188:191], v[14:17]
	v_mfma_f32_16x16x32_bf16 v[10:13], v[156:159], v[188:191], v[10:13]
	v_mfma_f32_16x16x32_bf16 v[62:65], v[152:155], v[168:171], v[62:65]
	v_mfma_f32_16x16x32_bf16 v[58:61], v[160:163], v[168:171], v[58:61]
	v_mfma_f32_16x16x32_bf16 v[46:49], v[152:155], v[176:179], v[46:49]
	v_mfma_f32_16x16x32_bf16 v[42:45], v[160:163], v[176:179], v[42:45]
	v_mfma_f32_16x16x32_bf16 v[30:33], v[152:155], v[184:187], v[30:33]
	v_mfma_f32_16x16x32_bf16 v[26:29], v[160:163], v[184:187], v[26:29]
	v_mfma_f32_16x16x32_bf16 v[14:17], v[152:155], v[212:215], v[14:17]
	v_mfma_f32_16x16x32_bf16 v[10:13], v[160:163], v[212:215], v[10:13]
	s_setprio 0
	s_barrier
; #define PG8_STAGE(bufoff, gbase, voff) do { _Pragma("unroll") for (int _i = 0; _i < 2; ++_i) \
;     __builtin_amdgcn_global_load_lds((const unsigned*)((const char*)(gbase) + (voff)[_i]), (LAS unsigned*)(lds + (bufoff) + ldsw + _i * 8192), 16, 0, 0); } while (0)
; #define PG8_LDA(dst, b, h) do { _Pragma("unroll") for (int m = 0; m < 4; ++m) _Pragma("unroll") for (int k = 0; k < 2; ++k) dst[m][k] = *(const LAS bf16x8*)(lds + PG8_SA(b, h) + aoff + m * 2048 + k * 1024); } while (0)
; #define PG8_LDB(dst, b, h) do { _Pragma("unroll") for (int n = 0; n < 2; ++n) _Pragma("unroll") for (int k = 0; k < 2; ++k) dst[n][k] = *(const LAS bf16x8*)(lds + PG8_SB(b, h) + boff + n * 2048 + k * 1024); } while (0)
; #define PG8_MMA(ai, bj, At, Bt) do { __builtin_amdgcn_s_setprio(1); _Pragma("unroll") for (int m = 0; m < 4; ++m) _Pragma("unroll") for (int n = 0; n < 2; ++n) _Pragma("unroll") for (int k = 0; k < 2; ++k) \
;     acc[ai][bj][m][n] = __builtin_amdgcn_mfma_f32_16x16x32_bf16(Bt[n][k], At[m][k], acc[ai][bj][m][n], 0, 0, 0); __builtin_amdgcn_s_setprio(0); } while (0)
; #define PG8_WAIT_V(n) asm volatile("s_waitcnt vmcnt(" #n ")" ::: "memory")
; #define PG8_WAIT_L(n) asm volatile("s_waitcnt lgkmcnt(" #n ")" ::: "memory")
; #define PG8_BAR __builtin_amdgcn_s_barrier()
; #define PG8_SCHED __builtin_amdgcn_sched_barrier(0)
; template <class Epi, bool SPLITA = false>
; __device__ __forceinline__ void gemm_phase(const int tid, LAS unsigned char* lds, const Gemm g, const Order& S, const Epi& E) {
;     ...
;       PG8_LDA(At, 0, 1); PG8_STAGE(PG8_SA(0, 0), a2, voffA);
;       PG8_BAR; PG8_WAIT_L(0); PG8_MMA(1, 0, At, B0); PG8_BAR; PG8_SCHED;
;       PG8_STAGE(PG8_SB(0, 1), b2 + hstepB, voffB);
;       PG8_WAIT_V(6); PG8_BAR; PG8_MMA(1, 1, At, B1); PG8_BAR;
;       PG8_LDB(B0, 1, 0); PG8_SCHED; PG8_LDA(At, 1, 0); PG8_STAGE(PG8_SA(0, 1), a2 + hstepA, voffA);
;       PG8_WAIT_L(8); PG8_BAR; PG8_WAIT_L(0); PG8_MMA(0, 0, At, B0); PG8_BAR; PG8_SCHED;
;       PG8_LDB(B1, 1, 1); PG8_STAGE(PG8_SB(1, 0), b3, voffB);
;       PG8_BAR; PG8_WAIT_L(0); PG8_MMA(0, 1, At, B1); PG8_BAR;
;       PG8_LDA(At, 1, 1); PG8_STAGE(PG8_SA(1, 0), a3, voffA);
;       PG8_BAR; PG8_WAIT_L(0); PG8_MMA(1, 0, At, B0); PG8_BAR; PG8_SCHED;
	s_add_u32 s14, s18, 0x8000
	s_addc_u32 s15, s19, 0
	s_add_i32 s20, s20, s28
	s_mov_b32 m0, s20
	s_nop 0
	global_load_lds_dwordx4 v134, s[14:15]
	s_add_i32 m0, s20, 0x2000
	s_nop 0
	global_load_lds_dwordx4 v130, s[14:15]
	s_waitcnt vmcnt(6)
	s_barrier
	s_setprio 1
	v_mfma_f32_16x16x32_bf16 v[54:57], v[216:219], v[164:167], v[54:57]
	v_mfma_f32_16x16x32_bf16 v[50:53], v[224:227], v[164:167], v[50:53]
	v_mfma_f32_16x16x32_bf16 v[38:41], v[216:219], v[172:175], v[38:41]
	v_mfma_f32_16x16x32_bf16 v[34:37], v[224:227], v[172:175], v[34:37]
	v_mfma_f32_16x16x32_bf16 v[22:25], v[216:219], v[180:183], v[22:25]
	v_mfma_f32_16x16x32_bf16 v[18:21], v[224:227], v[180:183], v[18:21]
	v_mfma_f32_16x16x32_bf16 v[6:9], v[216:219], v[188:191], v[6:9]
	v_mfma_f32_16x16x32_bf16 v[2:5], v[224:227], v[188:191], v[2:5]
	v_mfma_f32_16x16x32_bf16 v[54:57], v[220:223], v[168:171], v[54:57]
	v_mfma_f32_16x16x32_bf16 v[50:53], v[228:231], v[168:171], v[50:53]
	v_mfma_f32_16x16x32_bf16 v[38:41], v[220:223], v[176:179], v[38:41]
	v_mfma_f32_16x16x32_bf16 v[34:37], v[228:231], v[176:179], v[34:37]
	v_mfma_f32_16x16x32_bf16 v[22:25], v[220:223], v[184:187], v[22:25]
	v_mfma_f32_16x16x32_bf16 v[18:21], v[228:231], v[184:187], v[18:21]
	v_mfma_f32_16x16x32_bf16 v[6:9], v[220:223], v[212:215], v[6:9]
	v_mfma_f32_16x16x32_bf16 v[2:5], v[228:231], v[212:215], v[2:5]
	s_setprio 0
	s_add_i32 s20, 0, 0x18000
	s_barrier
	ds_read_b128 v[148:151], v146 offset:32768
	ds_read_b128 v[152:155], v146 offset:33792
	ds_read_b128 v[156:159], v146 offset:34816
	ds_read_b128 v[160:163], v146 offset:35840
	s_add_u32 s14, s42, 0x40000
	s_addc_u32 s15, s43, 0
	s_mov_b32 m0, s44
	ds_read_b128 v[164:167], v147 offset:32768
	ds_read_b128 v[168:171], v147 offset:33792
	ds_read_b128 v[172:175], v147 offset:34816
	ds_read_b128 v[176:179], v147 offset:35840
	ds_read_b128 v[180:183], v147 offset:36864
	ds_read_b128 v[184:187], v147 offset:37888
	ds_read_b128 v[188:191], v147 offset:38912
	ds_read_b128 v[212:215], v147 offset:39936
	global_load_lds_dwordx4 v0, s[14:15]
	s_mov_b32 m0, s45
	s_nop 0
	global_load_lds_dwordx4 v132, s[14:15]
	s_waitcnt lgkmcnt(8)
	s_barrier
	s_waitcnt lgkmcnt(0)
	s_setprio 1
	s_waitcnt lgkmcnt(0)
	v_mfma_f32_16x16x32_bf16 v[122:125], v[148:151], v[164:167], v[122:125]
	v_mfma_f32_16x16x32_bf16 v[126:129], v[156:159], v[164:167], v[126:129]
	v_mfma_f32_16x16x32_bf16 v[110:113], v[148:151], v[172:175], v[110:113]
	v_mfma_f32_16x16x32_bf16 v[106:109], v[156:159], v[172:175], v[106:109]
	v_mfma_f32_16x16x32_bf16 v[94:97], v[148:151], v[180:183], v[94:97]
	v_mfma_f32_16x16x32_bf16 v[90:93], v[156:159], v[180:183], v[90:93]
	v_mfma_f32_16x16x32_bf16 v[78:81], v[148:151], v[188:191], v[78:81]
	v_mfma_f32_16x16x32_bf16 v[74:77], v[156:159], v[188:191], v[74:77]
	v_mfma_f32_16x16x32_bf16 v[122:125], v[152:155], v[168:171], v[122:125]
	v_mfma_f32_16x16x32_bf16 v[126:129], v[160:163], v[168:171], v[126:129]
	v_mfma_f32_16x16x32_bf16 v[110:113], v[152:155], v[176:179], v[110:113]
	v_mfma_f32_16x16x32_bf16 v[106:109], v[160:163], v[176:179], v[106:109]
	v_mfma_f32_16x16x32_bf16 v[94:97], v[152:155], v[184:187], v[94:97]
	v_mfma_f32_16x16x32_bf16 v[90:93], v[160:163], v[184:187], v[90:93]
	v_mfma_f32_16x16x32_bf16 v[78:81], v[152:155], v[212:215], v[78:81]
	v_mfma_f32_16x16x32_bf16 v[74:77], v[160:163], v[212:215], v[74:77]
	s_setprio 0
	s_barrier
	s_add_i32 s21, 0, 0x1c000
	s_add_i32 s14, s20, s28
	s_add_i32 m0, s14, 0xffffff80
	ds_read_b128 v[216:219], v146 offset:49152
	ds_read_b128 v[220:223], v146 offset:50176
	ds_read_b128 v[224:227], v146 offset:51200
	ds_read_b128 v[228:231], v146 offset:52224
	global_load_lds_dwordx4 v134, s[18:19] offset:128
	s_add_i32 m0, s14, 0x1f80
	s_nop 0
	global_load_lds_dwordx4 v130, s[18:19] offset:128
	s_barrier
; #define PG8_STAGE(bufoff, gbase, voff) do { _Pragma("unroll") for (int _i = 0; _i < 2; ++_i) \
;     __builtin_amdgcn_global_load_lds((const unsigned*)((const char*)(gbase) + (voff)[_i]), (LAS unsigned*)(lds + (bufoff) + ldsw + _i * 8192), 16, 0, 0); } while (0)
; #define PG8_LDA(dst, b, h) do { _Pragma("unroll") for (int m = 0; m < 4; ++m) _Pragma("unroll") for (int k = 0; k < 2; ++k) dst[m][k] = *(const LAS bf16x8*)(lds + PG8_SA(b, h) + aoff + m * 2048 + k * 1024); } while (0)
; #define PG8_LDB(dst, b, h) do { _Pragma("unroll") for (int n = 0; n < 2; ++n) _Pragma("unroll") for (int k = 0; k < 2; ++k) dst[n][k] = *(const LAS bf16x8*)(lds + PG8_SB(b, h) + boff + n * 2048 + k * 1024); } while (0)
; #define PG8_MMA(ai, bj, At, Bt) do { __builtin_amdgcn_s_setprio(1); _Pragma("unroll") for (int m = 0; m < 4; ++m) _Pragma("unroll") for (int n = 0; n < 2; ++n) _Pragma("unroll") for (int k = 0; k < 2; ++k) \
;     acc[ai][bj][m][n] = __builtin_amdgcn_mfma_f32_16x16x32_bf16(Bt[n][k], At[m][k], acc[ai][bj][m][n], 0, 0, 0); __builtin_amdgcn_s_setprio(0); } while (0)
; #define PG8_WAIT_V(n) asm volatile("s_waitcnt vmcnt(" #n ")" ::: "memory")
; #define PG8_WAIT_L(n) asm volatile("s_waitcnt lgkmcnt(" #n ")" ::: "memory")
; #define PG8_BAR __builtin_amdgcn_s_barrier()
; #define PG8_SCHED __builtin_amdgcn_sched_barrier(0)
; template <class Epi, bool SPLITA = false>
; __device__ __forceinline__ void gemm_phase(const int tid, LAS unsigned char* lds, const Gemm g, const Order& S, const Epi& E) {
;     ...
;       PG8_WAIT_V(6); PG8_BAR; PG8_MMA(1, 1, At, B1); PG8_BAR;
;       PG8_LDB(B0, 1, 0); PG8_SCHED; PG8_LDA(At, 1, 0); PG8_STAGE(PG8_SA(0, 1), a2 + hstepA, voffA);
;       PG8_WAIT_L(8); PG8_BAR; PG8_WAIT_L(0); PG8_MMA(0, 0, At, B0); PG8_BAR; PG8_SCHED;
;       PG8_LDB(B1, 1, 1); PG8_STAGE(PG8_SB(1, 0), b3, voffB);
;       PG8_BAR; PG8_WAIT_L(0); PG8_MMA(0, 1, At, B1); PG8_BAR;
;       PG8_LDA(At, 1, 1); PG8_STAGE(PG8_SA(1, 0), a3, voffA);
;       PG8_BAR; PG8_WAIT_L(0); PG8_MMA(1, 0, At, B0); PG8_BAR; PG8_SCHED;
;       PG8_STAGE(PG8_SB(1, 1), b3 + hstepB, voffB);
;       PG8_WAIT_V(6); PG8_BAR; PG8_MMA(1, 1, At, B1); PG8_BAR;
	s_waitcnt lgkmcnt(0)
	s_setprio 1
	s_waitcnt lgkmcnt(0)
	v_mfma_f32_16x16x32_bf16 v[118:121], v[216:219], v[164:167], v[118:121]
	v_mfma_f32_16x16x32_bf16 v[114:117], v[224:227], v[164:167], v[114:117]
	v_mfma_f32_16x16x32_bf16 v[102:105], v[216:219], v[172:175], v[102:105]
	v_mfma_f32_16x16x32_bf16 v[98:101], v[224:227], v[172:175], v[98:101]
	v_mfma_f32_16x16x32_bf16 v[86:89], v[216:219], v[180:183], v[86:89]
	v_mfma_f32_16x16x32_bf16 v[82:85], v[224:227], v[180:183], v[82:85]
	v_mfma_f32_16x16x32_bf16 v[70:73], v[216:219], v[188:191], v[70:73]
	v_mfma_f32_16x16x32_bf16 v[66:69], v[224:227], v[188:191], v[66:69]
	v_mfma_f32_16x16x32_bf16 v[118:121], v[220:223], v[168:171], v[118:121]
	v_mfma_f32_16x16x32_bf16 v[114:117], v[228:231], v[168:171], v[114:117]
	v_mfma_f32_16x16x32_bf16 v[102:105], v[220:223], v[176:179], v[102:105]
	v_mfma_f32_16x16x32_bf16 v[98:101], v[228:231], v[176:179], v[98:101]
	v_mfma_f32_16x16x32_bf16 v[86:89], v[220:223], v[184:187], v[86:89]
	v_mfma_f32_16x16x32_bf16 v[82:85], v[228:231], v[184:187], v[82:85]
	v_mfma_f32_16x16x32_bf16 v[70:73], v[220:223], v[212:215], v[70:73]
	v_mfma_f32_16x16x32_bf16 v[66:69], v[228:231], v[212:215], v[66:69]
	s_setprio 0
	s_mov_b32 m0, s49
	s_barrier
	ds_read_b128 v[164:167], v147 offset:49152
	ds_read_b128 v[168:171], v147 offset:50176
	ds_read_b128 v[172:175], v147 offset:51200
	ds_read_b128 v[176:179], v147 offset:52224
	ds_read_b128 v[180:183], v147 offset:53248
	ds_read_b128 v[184:187], v147 offset:54272
	ds_read_b128 v[188:191], v147 offset:55296
	ds_read_b128 v[212:215], v147 offset:56320
	global_load_lds_dwordx4 v0, s[40:41]
	s_mov_b32 m0, s51
	s_nop 0
	global_load_lds_dwordx4 v132, s[40:41]
	s_barrier
	s_waitcnt lgkmcnt(0)
	s_setprio 1
	s_waitcnt lgkmcnt(0)
	v_mfma_f32_16x16x32_bf16 v[62:65], v[148:151], v[164:167], v[62:65]
	v_mfma_f32_16x16x32_bf16 v[58:61], v[156:159], v[164:167], v[58:61]
	v_mfma_f32_16x16x32_bf16 v[46:49], v[148:151], v[172:175], v[46:49]
	v_mfma_f32_16x16x32_bf16 v[42:45], v[156:159], v[172:175], v[42:45]
	v_mfma_f32_16x16x32_bf16 v[30:33], v[148:151], v[180:183], v[30:33]
	v_mfma_f32_16x16x32_bf16 v[26:29], v[156:159], v[180:183], v[26:29]
	v_mfma_f32_16x16x32_bf16 v[14:17], v[148:151], v[188:191], v[14:17]
	v_mfma_f32_16x16x32_bf16 v[10:13], v[156:159], v[188:191], v[10:13]
	v_mfma_f32_16x16x32_bf16 v[62:65], v[152:155], v[168:171], v[62:65]
	v_mfma_f32_16x16x32_bf16 v[58:61], v[160:163], v[168:171], v[58:61]
	v_mfma_f32_16x16x32_bf16 v[46:49], v[152:155], v[176:179], v[46:49]
	v_mfma_f32_16x16x32_bf16 v[42:45], v[160:163], v[176:179], v[42:45]
	v_mfma_f32_16x16x32_bf16 v[30:33], v[152:155], v[184:187], v[30:33]
	v_mfma_f32_16x16x32_bf16 v[26:29], v[160:163], v[184:187], v[26:29]
	v_mfma_f32_16x16x32_bf16 v[14:17], v[152:155], v[212:215], v[14:17]
	v_mfma_f32_16x16x32_bf16 v[10:13], v[160:163], v[212:215], v[10:13]
	s_setprio 0
	s_barrier
	s_add_u32 s14, s18, 0x8080
	s_addc_u32 s15, s19, 0
	s_add_i32 s18, s21, s28
	s_mov_b32 m0, s18
	s_nop 0
	global_load_lds_dwordx4 v134, s[14:15]
	s_add_i32 m0, s18, 0x2000
	s_nop 0
	global_load_lds_dwordx4 v130, s[14:15]
	s_waitcnt vmcnt(6)
	s_barrier
	s_setprio 1
	v_mfma_f32_16x16x32_bf16 v[54:57], v[216:219], v[164:167], v[54:57]
	v_mfma_f32_16x16x32_bf16 v[50:53], v[224:227], v[164:167], v[50:53]
	v_mfma_f32_16x16x32_bf16 v[38:41], v[216:219], v[172:175], v[38:41]
	v_mfma_f32_16x16x32_bf16 v[34:37], v[224:227], v[172:175], v[34:37]
	v_mfma_f32_16x16x32_bf16 v[22:25], v[216:219], v[180:183], v[22:25]
	v_mfma_f32_16x16x32_bf16 v[18:21], v[224:227], v[180:183], v[18:21]
	v_mfma_f32_16x16x32_bf16 v[6:9], v[216:219], v[188:191], v[6:9]
	v_mfma_f32_16x16x32_bf16 v[2:5], v[224:227], v[188:191], v[2:5]
	v_mfma_f32_16x16x32_bf16 v[54:57], v[220:223], v[168:171], v[54:57]
	v_mfma_f32_16x16x32_bf16 v[50:53], v[228:231], v[168:171], v[50:53]
	v_mfma_f32_16x16x32_bf16 v[38:41], v[220:223], v[176:179], v[38:41]
	v_mfma_f32_16x16x32_bf16 v[34:37], v[228:231], v[176:179], v[34:37]
	v_mfma_f32_16x16x32_bf16 v[22:25], v[220:223], v[184:187], v[22:25]
	v_mfma_f32_16x16x32_bf16 v[18:21], v[228:231], v[184:187], v[18:21]
	v_mfma_f32_16x16x32_bf16 v[6:9], v[220:223], v[212:215], v[6:9]
	v_mfma_f32_16x16x32_bf16 v[2:5], v[228:231], v[212:215], v[2:5]
	s_setprio 0
	s_cmp_ge_i32 s29, s46
	s_mov_b64 s[14:15], s[16:17]
	s_mov_b32 s18, s29
	s_barrier
	s_cbranch_scc0 .LBB0_400
	s_mov_b64 s[20:21], s[34:35]
	v_mov_b32_e32 v219, v196
	s_branch .LBB0_389

; #define PG8_STAGE(bufoff, gbase, voff) do { _Pragma("unroll") for (int _i = 0; _i < 2; ++_i) \
;     __builtin_amdgcn_global_load_lds((const unsigned*)((const char*)(gbase) + (voff)[_i]), (LAS unsigned*)(lds + (bufoff) + ldsw + _i * 8192), 16, 0, 0); } while (0)
; #define PG8_WAIT_V(n) asm volatile("s_waitcnt vmcnt(" #n ")" ::: "memory")
; #define PG8_BAR __builtin_amdgcn_s_barrier()
; template <class Epi, bool SPLITA = false>
; __device__ __forceinline__ void gemm_phase(const int tid, LAS unsigned char* lds, const Gemm g, const Order& S, const Epi& E) {
;     ...
;   const int aoff = lds_byte(wr * 64 + fr, fq * 8), boff = lds_byte(wc * 32 + fr, fq * 8);
;     ...
;   Unit cur, nxt; int ui = 0;
;   if (!S.next(0, cur)) return;
;   Acc acc;
; #pragma unroll
;   for (int a = 0; a < 2; ++a)
; #pragma unroll
;     for (int b = 0; b < 2; ++b)
; #pragma unroll
;       for (int m = 0; m < 4; ++m)
; #pragma unroll
;         for (int n = 0; n < 2; ++n) acc[a][b][m][n] = (f32x4){0.f, 0.f, 0.f, 0.f};
;   bf16x8 At[4][2], B0[2][2], B1[2][2];
;   const char* cA = (const char*)g.A + (size_t)cur.pm * tstepA + (size_t)cur.pn * apn; const char* cB = (const char*)g.Bt + (size_t)cur.pn * tstepB;
;   const char* cA2 = SPLITA ? (const char*)g.A2 + (size_t)cur.pm * tstepA : cA; const int nt1 = SPLITA ? g.nt1 : nt;
;     ...
;   PG8_STAGE(PG8_SB(0, 0), cB, voffB); PG8_STAGE(PG8_SA(0, 0), cA, voffA); PG8_STAGE(PG8_SB(0, 1), cB + hstepB, voffB); PG8_STAGE(PG8_SA(0, 1), cA + hstepA, voffA);
;   if (wr == 1) PG8_BAR;
;   PG8_WAIT_V(4); PG8_BAR;
;   PG8_STAGE(PG8_SB(1, 0), cB + kstep, voffB); PG8_STAGE(PG8_SA(1, 0), cA + kstep, voffA); PG8_STAGE(PG8_SB(1, 1), cB + hstepB + kstep, voffB);
;   PG8_WAIT_V(6); PG8_BAR;
.LBB0_458:
	s_lshl_b64 s[6:7], s[6:7], 2
	v_bfe_u32 v180, v210, 4, 2
	s_add_u32 s6, s66, s6
	v_and_b32_e32 v181, 15, v210
	v_lshlrev_b32_e32 v16, 4, v180
	v_lshlrev_b32_e32 v17, 2, v210
	s_addc_u32 s7, s67, s7
	v_lshl_or_b32 v16, v181, 6, v16
	s_lshl_b32 s1, s4, 13
	v_and_b32_e32 v17, 32, v17
	v_bitop3_b32 v18, v16, s1, v17 bitop3:0xde
	s_lshl_b32 s1, s8, 5
	s_and_b32 s47, s1, 0x60
	s_add_i32 m0, s19, 0x18000
	v_lshl_add_u64 v[8:9], v[8:9], 0, s[96:97]
	s_lshl_b32 s46, s4, 6
	s_lshl_b32 s1, s47, 7
	s_waitcnt vmcnt(4)
	s_barrier
	global_load_lds_dwordx4 v[8:9], off
	v_lshl_add_u64 v[6:7], v[6:7], 0, s[96:97]
	s_add_i32 m0, s19, 0x1a000
	s_add_i32 s51, s19, 0x8000
	s_add_i32 s52, s19, 0xa000
	global_load_lds_dwordx4 v[6:7], off
	v_lshl_add_u64 v[4:5], v[4:5], 0, s[96:97]
	s_mov_b32 m0, s51
	s_add_u32 s8, s40, 0x80080
	global_load_lds_dwordx4 v[4:5], off
	v_lshl_add_u64 v[2:3], v[2:3], 0, s[96:97]
	s_mov_b32 m0, s52
	s_addc_u32 s9, s41, 0
	global_load_lds_dwordx4 v[2:3], off
	s_add_i32 m0, s19, 0x1c000
	s_nop 0
	global_load_lds_dwordx4 v0, s[8:9]
	v_lshl_add_u64 v[2:3], s[8:9], 0, v[150:151]
	s_add_i32 m0, s19, 0x1e000
	v_bitop3_b32 v182, s1, v16, v17 bitop3:0xf6
	v_add_u32_e32 v182, 0x10000, v182
	global_load_lds_dwordx4 v150, s[8:9]
	v_lshlrev_b32_e32 v2, 15, v10
	v_and_b32_e32 v2, 0xffff0000, v2
	v_lshl_add_u32 v2, v11, 12, v2
	v_and_b32_e32 v3, 1, v10
	v_lshl_or_b32 v2, v3, 6, v2
	v_lshl_add_u32 v152, v12, 1, v2
	v_lshlrev_b32_e32 v2, 15, v13
	v_and_b32_e32 v2, 0xffff0000, v2
	s_waitcnt vmcnt(6)
	v_lshl_add_u32 v2, v14, 12, v2
	v_and_b32_e32 v3, 1, v13
	v_lshl_or_b32 v2, v3, 6, v2
	s_ashr_i32 s53, s92, 31
	v_mov_b32_e32 v153, v1
	v_lshl_add_u32 v154, v15, 1, v2
	v_mov_b32_e32 v155, v1
	s_mov_b32 s90, 0
	v_add_u32_e32 v183, 0, v18
	s_barrier
	s_branch .LBB0_460

; #define PG8_STAGE(bufoff, gbase, voff) do { _Pragma("unroll") for (int _i = 0; _i < 2; ++_i) \
;     __builtin_amdgcn_global_load_lds((const unsigned*)((const char*)(gbase) + (voff)[_i]), (LAS unsigned*)(lds + (bufoff) + ldsw + _i * 8192), 16, 0, 0); } while (0)
; #define PG8_LDA(dst, b, h) do { _Pragma("unroll") for (int m = 0; m < 4; ++m) _Pragma("unroll") for (int k = 0; k < 2; ++k) dst[m][k] = *(const LAS bf16x8*)(lds + PG8_SA(b, h) + aoff + m * 2048 + k * 1024); } while (0)
; #define PG8_LDB(dst, b, h) do { _Pragma("unroll") for (int n = 0; n < 2; ++n) _Pragma("unroll") for (int k = 0; k < 2; ++k) dst[n][k] = *(const LAS bf16x8*)(lds + PG8_SB(b, h) + boff + n * 2048 + k * 1024); } while (0)
; #define PG8_WAIT_V(n) asm volatile("s_waitcnt vmcnt(" #n ")" ::: "memory")
; #define PG8_WAIT_L(n) asm volatile("s_waitcnt lgkmcnt(" #n ")" ::: "memory")
; #define PG8_BAR __builtin_amdgcn_s_barrier()
; #define PG8_SCHED __builtin_amdgcn_sched_barrier(0)
; template <class Epi, bool SPLITA = false>
; __device__ __forceinline__ void gemm_phase(const int tid, LAS unsigned char* lds, const Gemm g, const Order& S, const Epi& E) {
;     ...
;     for (int t = 0; t < nt; t += 2) {
;       const bool last = (t == nt - 2);
;       if constexpr (SPLITA) { if (t == nt1) E.mid(acc, cur, wr, wc, fr, fq); }
;       const char* a1 = PG8_TA(t + 1);
;       const char* a2 = last ? nA : PG8_TA(t + 2); const char* b2 = last ? nB : cB + (size_t)(t + 2) * kstep;
;       const char* a3 = last ? nA + kstep : PG8_TA(t + 3); const char* b3 = b2 + kstep;
;       PG8_LDB(B0, 0, 0); PG8_SCHED; PG8_LDA(At, 0, 0); PG8_STAGE(PG8_SA(1, 1), a1 + hstepA, voffA);
;       PG8_WAIT_L(8); PG8_BAR; PG8_WAIT_L(0); PG8_MMA(0, 0, At, B0); PG8_BAR; PG8_SCHED;
;       PG8_LDB(B1, 0, 1); PG8_STAGE(PG8_SB(0, 0), b2, voffB);
;       PG8_BAR; PG8_WAIT_L(0); PG8_MMA(0, 1, At, B1); PG8_BAR;
;       PG8_LDA(At, 0, 1); PG8_STAGE(PG8_SA(0, 0), a2, voffA);
;       PG8_BAR; PG8_WAIT_L(0); PG8_MMA(1, 0, At, B0); PG8_BAR; PG8_SCHED;
;       PG8_STAGE(PG8_SB(0, 1), b2 + hstepB, voffB);
;       PG8_WAIT_V(6); PG8_BAR; PG8_MMA(1, 1, At, B1); PG8_BAR;
;       PG8_LDB(B0, 1, 0); PG8_SCHED; PG8_LDA(At, 1, 0); PG8_STAGE(PG8_SA(0, 1), a2 + hstepA, voffA);
;       PG8_WAIT_L(8); PG8_BAR; PG8_WAIT_L(0); PG8_MMA(0, 0, At, B0); PG8_BAR; PG8_SCHED;
.LBB0_463:
	s_add_u32 s20, s16, s40
	s_addc_u32 s21, s17, s41
	s_add_u32 s22, s20, 0x100
	s_addc_u32 s23, s21, 0
	s_add_u32 s29, vcc_lo, s40
	s_addc_u32 s42, vcc_hi, s41
	s_add_u32 s20, s20, 0x180
	s_addc_u32 s21, s21, 0
	s_add_i32 s94, 0, 0x10000
	ds_read_b128 v[62:65], v182
	ds_read_b128 v[74:77], v182 offset:1024
	ds_read_b128 v[78:81], v182 offset:2048
	ds_read_b128 v[156:159], v182 offset:3072
	s_cmpk_eq_i32 s40, 0xf00
	s_cselect_b32 s49, s93, s21
	s_cselect_b32 s48, s91, s20
	s_cselect_b32 s43, s9, s42
	s_cselect_b32 s42, s28, s29
	s_cselect_b32 s55, s1, s23
	s_cselect_b32 s54, s11, s22
	v_lshl_add_u64 v[192:193], v[58:59], 0, s[40:41]
	s_add_i32 m0, s19, 0xc000
	ds_read_b128 v[160:163], v183
	ds_read_b128 v[164:167], v183 offset:1024
	ds_read_b128 v[168:171], v183 offset:2048
	ds_read_b128 v[172:175], v183 offset:3072
	ds_read_b128 v[176:179], v183 offset:4096
	ds_read_b128 v[184:187], v183 offset:5120
	ds_read_b128 v[188:191], v183 offset:6144
	ds_read_b128 v[212:215], v183 offset:7168
	global_load_lds_dwordx4 v[192:193], off
	v_lshl_add_u64 v[192:193], v[60:61], 0, s[40:41]
	s_add_i32 m0, s19, 0xe000
	s_nop 0
	global_load_lds_dwordx4 v[192:193], off
	s_waitcnt lgkmcnt(8)
	s_barrier
	s_waitcnt lgkmcnt(0)
	s_setprio 1
	s_waitcnt lgkmcnt(0)
	v_mfma_f32_16x16x32_bf16 v[142:145], v[62:65], v[160:163], v[142:145]
	v_mfma_f32_16x16x32_bf16 v[138:141], v[78:81], v[160:163], v[138:141]
	v_mfma_f32_16x16x32_bf16 v[126:129], v[62:65], v[168:171], v[126:129]
	v_mfma_f32_16x16x32_bf16 v[122:125], v[78:81], v[168:171], v[122:125]
	v_mfma_f32_16x16x32_bf16 v[110:113], v[62:65], v[176:179], v[110:113]
	v_mfma_f32_16x16x32_bf16 v[106:109], v[78:81], v[176:179], v[106:109]
	v_mfma_f32_16x16x32_bf16 v[94:97], v[62:65], v[188:191], v[94:97]
	v_mfma_f32_16x16x32_bf16 v[90:93], v[78:81], v[188:191], v[90:93]
	v_mfma_f32_16x16x32_bf16 v[142:145], v[74:77], v[164:167], v[142:145]
	v_mfma_f32_16x16x32_bf16 v[138:141], v[156:159], v[164:167], v[138:141]
	v_mfma_f32_16x16x32_bf16 v[126:129], v[74:77], v[172:175], v[126:129]
	v_mfma_f32_16x16x32_bf16 v[122:125], v[156:159], v[172:175], v[122:125]
	v_mfma_f32_16x16x32_bf16 v[110:113], v[74:77], v[184:187], v[110:113]
	v_mfma_f32_16x16x32_bf16 v[106:109], v[156:159], v[184:187], v[106:109]
	v_mfma_f32_16x16x32_bf16 v[94:97], v[74:77], v[212:215], v[94:97]
	v_mfma_f32_16x16x32_bf16 v[90:93], v[156:159], v[212:215], v[90:93]
	s_setprio 0
	s_barrier
	s_add_i32 s20, 0, 0x14000
	s_add_i32 s21, s94, s30
	ds_read_b128 v[216:219], v182 offset:16384
	ds_read_b128 v[220:223], v182 offset:17408
	ds_read_b128 v[224:227], v182 offset:18432
	ds_read_b128 v[228:231], v182 offset:19456
	s_mov_b32 m0, s21
	s_nop 0
	global_load_lds_dwordx4 v0, s[42:43]
	s_add_i32 m0, s21, 0x2000
	s_nop 0
	global_load_lds_dwordx4 v150, s[42:43]
	s_barrier
	s_waitcnt lgkmcnt(0)
	s_setprio 1
	s_waitcnt lgkmcnt(0)
	v_mfma_f32_16x16x32_bf16 v[134:137], v[216:219], v[160:163], v[134:137]
	v_mfma_f32_16x16x32_bf16 v[130:133], v[224:227], v[160:163], v[130:133]
	v_mfma_f32_16x16x32_bf16 v[118:121], v[216:219], v[168:171], v[118:121]
	v_mfma_f32_16x16x32_bf16 v[114:117], v[224:227], v[168:171], v[114:117]
	v_mfma_f32_16x16x32_bf16 v[102:105], v[216:219], v[176:179], v[102:105]
	v_mfma_f32_16x16x32_bf16 v[98:101], v[224:227], v[176:179], v[98:101]
	v_mfma_f32_16x16x32_bf16 v[86:89], v[216:219], v[188:191], v[86:89]
	v_mfma_f32_16x16x32_bf16 v[82:85], v[224:227], v[188:191], v[82:85]
	v_mfma_f32_16x16x32_bf16 v[134:137], v[220:223], v[164:167], v[134:137]
	v_mfma_f32_16x16x32_bf16 v[130:133], v[228:231], v[164:167], v[130:133]
	v_mfma_f32_16x16x32_bf16 v[118:121], v[220:223], v[172:175], v[118:121]
	v_mfma_f32_16x16x32_bf16 v[114:117], v[228:231], v[172:175], v[114:117]
	v_mfma_f32_16x16x32_bf16 v[102:105], v[220:223], v[184:187], v[102:105]
	v_mfma_f32_16x16x32_bf16 v[98:101], v[228:231], v[184:187], v[98:101]
	v_mfma_f32_16x16x32_bf16 v[86:89], v[220:223], v[212:215], v[86:89]
	v_mfma_f32_16x16x32_bf16 v[82:85], v[228:231], v[212:215], v[82:85]
	s_setprio 0
	s_mov_b32 m0, s19
	s_barrier
	ds_read_b128 v[160:163], v183 offset:16384
	ds_read_b128 v[164:167], v183 offset:17408
	ds_read_b128 v[168:171], v183 offset:18432
	ds_read_b128 v[172:175], v183 offset:19456
	ds_read_b128 v[176:179], v183 offset:20480
	ds_read_b128 v[184:187], v183 offset:21504
	ds_read_b128 v[188:191], v183 offset:22528
	ds_read_b128 v[212:215], v183 offset:23552
	global_load_lds_dwordx4 v146, s[54:55]
	s_mov_b32 m0, s31
	s_nop 0
	global_load_lds_dwordx4 v148, s[54:55]
	s_barrier
	s_waitcnt lgkmcnt(0)
	s_setprio 1
	s_waitcnt lgkmcnt(0)
	v_mfma_f32_16x16x32_bf16 v[70:73], v[62:65], v[160:163], v[70:73]
	v_mfma_f32_16x16x32_bf16 v[66:69], v[78:81], v[160:163], v[66:69]
	v_mfma_f32_16x16x32_bf16 v[46:49], v[62:65], v[168:171], v[46:49]
	v_mfma_f32_16x16x32_bf16 v[42:45], v[78:81], v[168:171], v[42:45]
	v_mfma_f32_16x16x32_bf16 v[30:33], v[62:65], v[176:179], v[30:33]
	v_mfma_f32_16x16x32_bf16 v[26:29], v[78:81], v[176:179], v[26:29]
	v_mfma_f32_16x16x32_bf16 v[14:17], v[62:65], v[188:191], v[14:17]
	v_mfma_f32_16x16x32_bf16 v[10:13], v[78:81], v[188:191], v[10:13]
	v_mfma_f32_16x16x32_bf16 v[70:73], v[74:77], v[164:167], v[70:73]
	v_mfma_f32_16x16x32_bf16 v[66:69], v[156:159], v[164:167], v[66:69]
	v_mfma_f32_16x16x32_bf16 v[46:49], v[74:77], v[172:175], v[46:49]
	v_mfma_f32_16x16x32_bf16 v[42:45], v[156:159], v[172:175], v[42:45]
	v_mfma_f32_16x16x32_bf16 v[30:33], v[74:77], v[184:187], v[30:33]
	v_mfma_f32_16x16x32_bf16 v[26:29], v[156:159], v[184:187], v[26:29]
	v_mfma_f32_16x16x32_bf16 v[14:17], v[74:77], v[212:215], v[14:17]
	v_mfma_f32_16x16x32_bf16 v[10:13], v[156:159], v[212:215], v[10:13]
	s_setprio 0
	s_barrier
; #define PG8_STAGE(bufoff, gbase, voff) do { _Pragma("unroll") for (int _i = 0; _i < 2; ++_i) \
;     __builtin_amdgcn_global_load_lds((const unsigned*)((const char*)(gbase) + (voff)[_i]), (LAS unsigned*)(lds + (bufoff) + ldsw + _i * 8192), 16, 0, 0); } while (0)
; #define PG8_LDA(dst, b, h) do { _Pragma("unroll") for (int m = 0; m < 4; ++m) _Pragma("unroll") for (int k = 0; k < 2; ++k) dst[m][k] = *(const LAS bf16x8*)(lds + PG8_SA(b, h) + aoff + m * 2048 + k * 1024); } while (0)
; #define PG8_LDB(dst, b, h) do { _Pragma("unroll") for (int n = 0; n < 2; ++n) _Pragma("unroll") for (int k = 0; k < 2; ++k) dst[n][k] = *(const LAS bf16x8*)(lds + PG8_SB(b, h) + boff + n * 2048 + k * 1024); } while (0)
; #define PG8_MMA(ai, bj, At, Bt) do { __builtin_amdgcn_s_setprio(1); _Pragma("unroll") for (int m = 0; m < 4; ++m) _Pragma("unroll") for (int n = 0; n < 2; ++n) _Pragma("unroll") for (int k = 0; k < 2; ++k) \
;     acc[ai][bj][m][n] = __builtin_amdgcn_mfma_f32_16x16x32_bf16(Bt[n][k], At[m][k], acc[ai][bj][m][n], 0, 0, 0); __builtin_amdgcn_s_setprio(0); } while (0)
; #define PG8_WAIT_V(n) asm volatile("s_waitcnt vmcnt(" #n ")" ::: "memory")
; #define PG8_WAIT_L(n) asm volatile("s_waitcnt lgkmcnt(" #n ")" ::: "memory")
; #define PG8_BAR __builtin_amdgcn_s_barrier()
; #define PG8_SCHED __builtin_amdgcn_sched_barrier(0)
; template <class Epi, bool SPLITA = false>
; __device__ __forceinline__ void gemm_phase(const int tid, LAS unsigned char* lds, const Gemm g, const Order& S, const Epi& E) {
;     ...
;       PG8_LDA(At, 0, 1); PG8_STAGE(PG8_SA(0, 0), a2, voffA);
;       PG8_BAR; PG8_WAIT_L(0); PG8_MMA(1, 0, At, B0); PG8_BAR; PG8_SCHED;
;       PG8_STAGE(PG8_SB(0, 1), b2 + hstepB, voffB);
;       PG8_WAIT_V(6); PG8_BAR; PG8_MMA(1, 1, At, B1); PG8_BAR;
;       PG8_LDB(B0, 1, 0); PG8_SCHED; PG8_LDA(At, 1, 0); PG8_STAGE(PG8_SA(0, 1), a2 + hstepA, voffA);
;       PG8_WAIT_L(8); PG8_BAR; PG8_WAIT_L(0); PG8_MMA(0, 0, At, B0); PG8_BAR; PG8_SCHED;
;       PG8_LDB(B1, 1, 1); PG8_STAGE(PG8_SB(1, 0), b3, voffB);
;       PG8_BAR; PG8_WAIT_L(0); PG8_MMA(0, 1, At, B1); PG8_BAR;
;       PG8_LDA(At, 1, 1); PG8_STAGE(PG8_SA(1, 0), a3, voffA);
;       PG8_BAR; PG8_WAIT_L(0); PG8_MMA(1, 0, At, B0); PG8_BAR; PG8_SCHED;
	s_add_u32 s22, s42, 0x80000
	s_addc_u32 s23, s43, 0
	s_add_i32 s20, s20, s30
	s_mov_b32 m0, s20
	s_nop 0
	global_load_lds_dwordx4 v0, s[22:23]
	s_add_i32 m0, s20, 0x2000
	s_nop 0
	global_load_lds_dwordx4 v150, s[22:23]
	s_waitcnt vmcnt(6)
	s_barrier
	s_setprio 1
	v_mfma_f32_16x16x32_bf16 v[54:57], v[216:219], v[160:163], v[54:57]
	v_mfma_f32_16x16x32_bf16 v[50:53], v[224:227], v[160:163], v[50:53]
	v_mfma_f32_16x16x32_bf16 v[38:41], v[216:219], v[168:171], v[38:41]
	v_mfma_f32_16x16x32_bf16 v[34:37], v[224:227], v[168:171], v[34:37]
	v_mfma_f32_16x16x32_bf16 v[22:25], v[216:219], v[176:179], v[22:25]
	v_mfma_f32_16x16x32_bf16 v[18:21], v[224:227], v[176:179], v[18:21]
	v_mfma_f32_16x16x32_bf16 v[6:9], v[216:219], v[188:191], v[6:9]
	v_mfma_f32_16x16x32_bf16 v[2:5], v[224:227], v[188:191], v[2:5]
	v_mfma_f32_16x16x32_bf16 v[54:57], v[220:223], v[164:167], v[54:57]
	v_mfma_f32_16x16x32_bf16 v[50:53], v[228:231], v[164:167], v[50:53]
	v_mfma_f32_16x16x32_bf16 v[38:41], v[220:223], v[172:175], v[38:41]
	v_mfma_f32_16x16x32_bf16 v[34:37], v[228:231], v[172:175], v[34:37]
	v_mfma_f32_16x16x32_bf16 v[22:25], v[220:223], v[184:187], v[22:25]
	v_mfma_f32_16x16x32_bf16 v[18:21], v[228:231], v[184:187], v[18:21]
	v_mfma_f32_16x16x32_bf16 v[6:9], v[220:223], v[212:215], v[6:9]
	v_mfma_f32_16x16x32_bf16 v[2:5], v[228:231], v[212:215], v[2:5]
	s_setprio 0
	s_add_i32 s20, 0, 0x18000
	s_barrier
	ds_read_b128 v[62:65], v182 offset:32768
	ds_read_b128 v[74:77], v182 offset:33792
	ds_read_b128 v[78:81], v182 offset:34816
	ds_read_b128 v[156:159], v182 offset:35840
	s_add_u32 s22, s54, 0x80000
	s_addc_u32 s23, s55, 0
	s_mov_b32 m0, s44
	ds_read_b128 v[160:163], v183 offset:32768
	ds_read_b128 v[164:167], v183 offset:33792
	ds_read_b128 v[168:171], v183 offset:34816
	ds_read_b128 v[172:175], v183 offset:35840
	ds_read_b128 v[176:179], v183 offset:36864
	ds_read_b128 v[184:187], v183 offset:37888
	ds_read_b128 v[188:191], v183 offset:38912
	ds_read_b128 v[212:215], v183 offset:39936
	global_load_lds_dwordx4 v146, s[22:23]
	s_mov_b32 m0, s45
	s_nop 0
	global_load_lds_dwordx4 v148, s[22:23]
	s_waitcnt lgkmcnt(8)
	s_barrier
	s_waitcnt lgkmcnt(0)
	s_setprio 1
	s_waitcnt lgkmcnt(0)
	v_mfma_f32_16x16x32_bf16 v[142:145], v[62:65], v[160:163], v[142:145]
	v_mfma_f32_16x16x32_bf16 v[138:141], v[78:81], v[160:163], v[138:141]
	v_mfma_f32_16x16x32_bf16 v[126:129], v[62:65], v[168:171], v[126:129]
	v_mfma_f32_16x16x32_bf16 v[122:125], v[78:81], v[168:171], v[122:125]
	v_mfma_f32_16x16x32_bf16 v[110:113], v[62:65], v[176:179], v[110:113]
	v_mfma_f32_16x16x32_bf16 v[106:109], v[78:81], v[176:179], v[106:109]
	v_mfma_f32_16x16x32_bf16 v[94:97], v[62:65], v[188:191], v[94:97]
	v_mfma_f32_16x16x32_bf16 v[90:93], v[78:81], v[188:191], v[90:93]
	v_mfma_f32_16x16x32_bf16 v[142:145], v[74:77], v[164:167], v[142:145]
	v_mfma_f32_16x16x32_bf16 v[138:141], v[156:159], v[164:167], v[138:141]
	v_mfma_f32_16x16x32_bf16 v[126:129], v[74:77], v[172:175], v[126:129]
	v_mfma_f32_16x16x32_bf16 v[122:125], v[156:159], v[172:175], v[122:125]
	v_mfma_f32_16x16x32_bf16 v[110:113], v[74:77], v[184:187], v[110:113]
	v_mfma_f32_16x16x32_bf16 v[106:109], v[156:159], v[184:187], v[106:109]
	v_mfma_f32_16x16x32_bf16 v[94:97], v[74:77], v[212:215], v[94:97]
	v_mfma_f32_16x16x32_bf16 v[90:93], v[156:159], v[212:215], v[90:93]
	s_setprio 0
	s_barrier
	s_add_i32 s21, 0, 0x1c000
	s_add_i32 s20, s20, s30
	s_add_i32 m0, s20, 0xffffff80
	ds_read_b128 v[216:219], v182 offset:49152
	ds_read_b128 v[220:223], v182 offset:50176
	ds_read_b128 v[224:227], v182 offset:51200
	ds_read_b128 v[228:231], v182 offset:52224
	global_load_lds_dwordx4 v0, s[42:43] offset:128
	s_add_i32 m0, s20, 0x1f80
	s_nop 0
	global_load_lds_dwordx4 v150, s[42:43] offset:128
	s_barrier
; #define PG8_STAGE(bufoff, gbase, voff) do { _Pragma("unroll") for (int _i = 0; _i < 2; ++_i) \
;     __builtin_amdgcn_global_load_lds((const unsigned*)((const char*)(gbase) + (voff)[_i]), (LAS unsigned*)(lds + (bufoff) + ldsw + _i * 8192), 16, 0, 0); } while (0)
; #define PG8_LDA(dst, b, h) do { _Pragma("unroll") for (int m = 0; m < 4; ++m) _Pragma("unroll") for (int k = 0; k < 2; ++k) dst[m][k] = *(const LAS bf16x8*)(lds + PG8_SA(b, h) + aoff + m * 2048 + k * 1024); } while (0)
; #define PG8_LDB(dst, b, h) do { _Pragma("unroll") for (int n = 0; n < 2; ++n) _Pragma("unroll") for (int k = 0; k < 2; ++k) dst[n][k] = *(const LAS bf16x8*)(lds + PG8_SB(b, h) + boff + n * 2048 + k * 1024); } while (0)
; #define PG8_MMA(ai, bj, At, Bt) do { __builtin_amdgcn_s_setprio(1); _Pragma("unroll") for (int m = 0; m < 4; ++m) _Pragma("unroll") for (int n = 0; n < 2; ++n) _Pragma("unroll") for (int k = 0; k < 2; ++k) \
;     acc[ai][bj][m][n] = __builtin_amdgcn_mfma_f32_16x16x32_bf16(Bt[n][k], At[m][k], acc[ai][bj][m][n], 0, 0, 0); __builtin_amdgcn_s_setprio(0); } while (0)
; #define PG8_WAIT_V(n) asm volatile("s_waitcnt vmcnt(" #n ")" ::: "memory")
; #define PG8_WAIT_L(n) asm volatile("s_waitcnt lgkmcnt(" #n ")" ::: "memory")
; #define PG8_BAR __builtin_amdgcn_s_barrier()
; #define PG8_SCHED __builtin_amdgcn_sched_barrier(0)
; template <class Epi, bool SPLITA = false>
; __device__ __forceinline__ void gemm_phase(const int tid, LAS unsigned char* lds, const Gemm g, const Order& S, const Epi& E) {
;     ...
;       PG8_LDB(B1, 1, 1); PG8_STAGE(PG8_SB(1, 0), b3, voffB);
;       PG8_BAR; PG8_WAIT_L(0); PG8_MMA(0, 1, At, B1); PG8_BAR;
;       PG8_LDA(At, 1, 1); PG8_STAGE(PG8_SA(1, 0), a3, voffA);
;       PG8_BAR; PG8_WAIT_L(0); PG8_MMA(1, 0, At, B0); PG8_BAR; PG8_SCHED;
;       PG8_STAGE(PG8_SB(1, 1), b3 + hstepB, voffB);
;       PG8_WAIT_V(6); PG8_BAR; PG8_MMA(1, 1, At, B1); PG8_BAR;
;   __device__ __forceinline__ void operator()(const Acc& acc, const Unit& u, int wr, int wc, int fr_, int fq_) const {
;     ...
;     bf16_t* base; int ld, c0; bool gate = false;
;     if (u.pn < 4) { base = Q; ld = 1024; c0 = u.pn * 256; }
;     else if (u.pn == 4) { base = Kb; ld = 256; c0 = 0; }
;     else if (u.pn == 5) { base = Vb; ld = 256; c0 = 0; }
;     else if (u.pn < 10) { base = F; ld = 1024; c0 = (u.pn - 6) * 256; }
;     else { base = Gt; ld = 4096; c0 = (u.pn - 10) * 256; gate = true; }
	s_waitcnt lgkmcnt(0)
	s_setprio 1
	s_waitcnt lgkmcnt(0)
	v_mfma_f32_16x16x32_bf16 v[134:137], v[216:219], v[160:163], v[134:137]
	v_mfma_f32_16x16x32_bf16 v[130:133], v[224:227], v[160:163], v[130:133]
	v_mfma_f32_16x16x32_bf16 v[118:121], v[216:219], v[168:171], v[118:121]
	v_mfma_f32_16x16x32_bf16 v[114:117], v[224:227], v[168:171], v[114:117]
	v_mfma_f32_16x16x32_bf16 v[102:105], v[216:219], v[176:179], v[102:105]
	v_mfma_f32_16x16x32_bf16 v[98:101], v[224:227], v[176:179], v[98:101]
	v_mfma_f32_16x16x32_bf16 v[86:89], v[216:219], v[188:191], v[86:89]
	v_mfma_f32_16x16x32_bf16 v[82:85], v[224:227], v[188:191], v[82:85]
	v_mfma_f32_16x16x32_bf16 v[134:137], v[220:223], v[164:167], v[134:137]
	v_mfma_f32_16x16x32_bf16 v[130:133], v[228:231], v[164:167], v[130:133]
	v_mfma_f32_16x16x32_bf16 v[118:121], v[220:223], v[172:175], v[118:121]
	v_mfma_f32_16x16x32_bf16 v[114:117], v[228:231], v[172:175], v[114:117]
	v_mfma_f32_16x16x32_bf16 v[102:105], v[220:223], v[184:187], v[102:105]
	v_mfma_f32_16x16x32_bf16 v[98:101], v[228:231], v[184:187], v[98:101]
	v_mfma_f32_16x16x32_bf16 v[86:89], v[220:223], v[212:215], v[86:89]
	v_mfma_f32_16x16x32_bf16 v[82:85], v[228:231], v[212:215], v[82:85]
	s_setprio 0
	s_mov_b32 m0, s51
	s_barrier
	ds_read_b128 v[160:163], v183 offset:49152
	ds_read_b128 v[164:167], v183 offset:50176
	ds_read_b128 v[168:171], v183 offset:51200
	ds_read_b128 v[172:175], v183 offset:52224
	ds_read_b128 v[176:179], v183 offset:53248
	ds_read_b128 v[184:187], v183 offset:54272
	ds_read_b128 v[188:191], v183 offset:55296
	ds_read_b128 v[212:215], v183 offset:56320
	global_load_lds_dwordx4 v146, s[48:49]
	s_mov_b32 m0, s52
	s_nop 0
	global_load_lds_dwordx4 v148, s[48:49]
	s_barrier
	s_waitcnt lgkmcnt(0)
	s_setprio 1
	s_waitcnt lgkmcnt(0)
	v_mfma_f32_16x16x32_bf16 v[70:73], v[62:65], v[160:163], v[70:73]
	v_mfma_f32_16x16x32_bf16 v[66:69], v[78:81], v[160:163], v[66:69]
	v_mfma_f32_16x16x32_bf16 v[46:49], v[62:65], v[168:171], v[46:49]
	v_mfma_f32_16x16x32_bf16 v[42:45], v[78:81], v[168:171], v[42:45]
	v_mfma_f32_16x16x32_bf16 v[30:33], v[62:65], v[176:179], v[30:33]
	v_mfma_f32_16x16x32_bf16 v[26:29], v[78:81], v[176:179], v[26:29]
	v_mfma_f32_16x16x32_bf16 v[14:17], v[62:65], v[188:191], v[14:17]
	v_mfma_f32_16x16x32_bf16 v[10:13], v[78:81], v[188:191], v[10:13]
	v_mfma_f32_16x16x32_bf16 v[70:73], v[74:77], v[164:167], v[70:73]
	v_mfma_f32_16x16x32_bf16 v[66:69], v[156:159], v[164:167], v[66:69]
	v_mfma_f32_16x16x32_bf16 v[46:49], v[74:77], v[172:175], v[46:49]
	v_mfma_f32_16x16x32_bf16 v[42:45], v[156:159], v[172:175], v[42:45]
	v_mfma_f32_16x16x32_bf16 v[30:33], v[74:77], v[184:187], v[30:33]
	v_mfma_f32_16x16x32_bf16 v[26:29], v[156:159], v[184:187], v[26:29]
	v_mfma_f32_16x16x32_bf16 v[14:17], v[74:77], v[212:215], v[14:17]
	v_mfma_f32_16x16x32_bf16 v[10:13], v[156:159], v[212:215], v[10:13]
	s_setprio 0
	s_barrier
	s_add_u32 s22, s42, 0x80080
	s_addc_u32 s23, s43, 0
	s_add_i32 s20, s21, s30
	s_mov_b32 m0, s20
	s_nop 0
	global_load_lds_dwordx4 v0, s[22:23]
	s_add_i32 m0, s20, 0x2000
	s_nop 0
	global_load_lds_dwordx4 v150, s[22:23]
	s_waitcnt vmcnt(6)
	s_barrier
	s_setprio 1
	v_mfma_f32_16x16x32_bf16 v[54:57], v[216:219], v[160:163], v[54:57]
	v_mfma_f32_16x16x32_bf16 v[50:53], v[224:227], v[160:163], v[50:53]
	v_mfma_f32_16x16x32_bf16 v[38:41], v[216:219], v[168:171], v[38:41]
	v_mfma_f32_16x16x32_bf16 v[34:37], v[224:227], v[168:171], v[34:37]
	v_mfma_f32_16x16x32_bf16 v[22:25], v[216:219], v[176:179], v[22:25]
	v_mfma_f32_16x16x32_bf16 v[18:21], v[224:227], v[176:179], v[18:21]
	v_mfma_f32_16x16x32_bf16 v[6:9], v[216:219], v[188:191], v[6:9]
	v_mfma_f32_16x16x32_bf16 v[2:5], v[224:227], v[188:191], v[2:5]
	v_mfma_f32_16x16x32_bf16 v[54:57], v[220:223], v[164:167], v[54:57]
	v_mfma_f32_16x16x32_bf16 v[50:53], v[228:231], v[164:167], v[50:53]
	v_mfma_f32_16x16x32_bf16 v[38:41], v[220:223], v[172:175], v[38:41]
	v_mfma_f32_16x16x32_bf16 v[34:37], v[228:231], v[172:175], v[34:37]
	v_mfma_f32_16x16x32_bf16 v[22:25], v[220:223], v[184:187], v[22:25]
	v_mfma_f32_16x16x32_bf16 v[18:21], v[228:231], v[184:187], v[18:21]
	v_mfma_f32_16x16x32_bf16 v[6:9], v[220:223], v[212:215], v[6:9]
	v_mfma_f32_16x16x32_bf16 v[2:5], v[228:231], v[212:215], v[2:5]
	s_setprio 0
	s_add_i32 s4, s4, 2
	s_add_u32 s40, s40, 0x100
	s_addc_u32 s41, s41, 0
	s_cmp_gt_u32 s4, 29
	s_barrier
	s_cbranch_scc0 .LBB0_463
	v_mov_b32_e32 v158, v181
	v_mov_b32_e32 v58, v180
	s_cmp_gt_i32 s0, 3
	s_mov_b64 s[48:49], -1
	s_mov_b64 s[20:21], s[34:35]
	s_cbranch_scc0 .LBB0_475
	s_cmp_lt_i32 s0, 5
	s_mov_b64 s[48:49], 0
	s_cbranch_scc1 .LBB0_474
	s_cmp_lg_u32 s0, 5
	s_mov_b64 s[54:55], -1
	s_cbranch_scc0 .LBB0_472
	s_lshl_b32 s4, s0, 8
	s_cmp_gt_u32 s0, 9
	s_mov_b64 s[40:41], -1
	s_mov_b64 s[42:43], -1
	s_cbranch_scc0 .LBB0_469
	s_add_i32 s1, s4, 0xfffff600
	s_mov_b64 s[42:43], 0
